# 4-phase GEMM K-loops, s_setprio flips around MFMA clusters removed
# speedup vs baseline: 1.0049x; 1.0049x over previous
; #define PG8_STAGE(bufoff, gbase, voff) do { _Pragma("unroll") for (int _i = 0; _i < 2; ++_i) \
;         __builtin_amdgcn_global_load_lds((const unsigned*)((const char*)(gbase) + (voff)[_i]), (LAS unsigned*)(lds + (bufoff) + ldsw + _i * 8192), 16, 0, 0); } while (0)
; #define PG8_LDA(dst, b, h) do { _Pragma("unroll") for (int m = 0; m < 4; ++m) _Pragma("unroll") for (int k = 0; k < 2; ++k) dst[m][k] = *(const LAS bf16x8*)(lds + PG8_SA(b, h) + aoff + m * 2048 + k * 1024); } while (0)
; #define PG8_WAIT_V(n) asm volatile("s_waitcnt vmcnt(" #n ")" ::: "memory")
; template <class Epi, class Sched>
; __device__ __forceinline__ void gemm_phase(LAS unsigned char* lds, const Gemm g, const Sched& S, const Epi& E) {
;     ...
;         for (int t = 0; t < ntu; t += 2) {
;             const bool last = (t == ntu - 2);
;             const char* a1 = cA + (size_t)(t + 1) * kstep;
;             const char* a2 = last ? nA : cA + (size_t)(t + 2) * kstep; const char* b2 = last ? nB : cB + (size_t)(t + 2) * kstep;
;             const char* a3 = a2 + kstep; const char* b3 = b2 + kstep;
;             if (last && has_next) S.a_ready(nxt);
;             PG8_LDB(B0, 0, 0); PG8_SCHED; PG8_LDA(At, 0, 0); PG8_STAGE(PG8_SA(1, 1), a1 + hstepA, voffA);
;             PG8_WAIT_L(8); PG8_BAR; PG8_WAIT_L(0); PG8_MMA(0, 0, At, B0); PG8_BAR; PG8_SCHED;
;             PG8_LDB(B1, 0, 1); PG8_STAGE(PG8_SB(0, 0), b2, voffB);
;             PG8_BAR; PG8_WAIT_L(0); PG8_MMA(0, 1, At, B1); PG8_BAR;
;             PG8_LDA(At, 0, 1); PG8_STAGE(PG8_SA(0, 0), a2, voffA);
;             PG8_BAR; PG8_WAIT_L(0); PG8_MMA(1, 0, At, B0); PG8_BAR; PG8_SCHED;
;             PG8_STAGE(PG8_SB(0, 1), b2 + hstepB, voffB);
;             PG8_WAIT_V(6); PG8_BAR; PG8_MMA(1, 1, At, B1); PG8_BAR;
;             PG8_LDB(B0, 1, 0); PG8_SCHED; PG8_LDA(At, 1, 0); PG8_STAGE(PG8_SA(0, 1), a2 + hstepA, voffA);
;             PG8_WAIT_L(8); PG8_BAR; PG8_WAIT_L(0); PG8_MMA(0, 0, At, B0); PG8_BAR; PG8_SCHED;
;             PG8_LDB(B1, 1, 1); PG8_STAGE(PG8_SB(1, 0), b3, voffB);
;             PG8_BAR; PG8_WAIT_L(0); PG8_MMA(0, 1, At, B1); PG8_BAR;
;             PG8_LDA(At, 1, 1); PG8_STAGE(PG8_SA(1, 0), a3, voffA);
;             PG8_BAR; PG8_WAIT_L(0); PG8_MMA(1, 0, At, B0); PG8_BAR; PG8_SCHED;
;             PG8_STAGE(PG8_SB(1, 1), b3 + hstepB, voffB);
;             PG8_WAIT_V(6); PG8_BAR; PG8_MMA(1, 1, At, B1); PG8_BAR;
.LBB0_381:
	s_add_u32 s37, s12, 0xfff80080
	s_addc_u32 s38, s13, -1
	s_add_i32 s46, 0, 0x10000
	v_add_u32_e32 v162, s46, v170
	ds_read_b128 v[150:153], v162
	ds_read_b128 v[154:157], v162 offset:1024
	ds_read_b128 v[158:161], v162 offset:2048
	ds_read_b128 v[162:165], v162 offset:3072
	s_cmp_eq_u32 s36, 28
	s_cselect_b32 s55, s1, s38
	s_cselect_b32 s54, s25, s37
	s_cselect_b32 s53, s23, s30
	s_cselect_b32 s52, s28, s29
	ds_read_b128 v[186:189], v176
	ds_read_b128 v[190:193], v176 offset:1024
	ds_read_b128 v[194:197], v176 offset:2048
	ds_read_b128 v[198:201], v176 offset:3072
	ds_read_b128 v[202:205], v176 offset:4096
	ds_read_b128 v[206:209], v176 offset:5120
	ds_read_b128 v[210:213], v176 offset:6144
	ds_read_b128 v[214:217], v176 offset:7168
	s_mov_b32 s98, 0xfff80000
	s_mov_b32 s99, -1
	v_lshl_add_u64 v[232:233], s[12:13], 0, v[146:147]
	v_lshl_add_u64 v[232:233], v[232:233], 0, s[98:99]
	s_mov_b32 m0, s70
	s_nop 0
	global_load_lds_dwordx4 v[232:233], off
	v_lshl_add_u64 v[232:233], s[12:13], 0, v[148:149]
	v_lshl_add_u64 v[232:233], v[232:233], 0, s[98:99]
	s_mov_b32 m0, s71
	s_nop 0
	global_load_lds_dwordx4 v[232:233], off
	v_lshl_add_u64 v[232:233], s[12:13], 0, v[146:147]
	s_add_i32 m0, s63, 0xc000
	s_nop 0
	global_load_lds_dwordx4 v[232:233], off
	v_lshl_add_u64 v[232:233], s[12:13], 0, v[148:149]
	s_add_i32 m0, s63, 0xe000
	s_nop 0
	global_load_lds_dwordx4 v[232:233], off
	s_add_i32 s37, 0, 0x14000
	v_add_u32_e32 v166, s37, v170
	ds_read_b128 v[218:221], v166
	ds_read_b128 v[222:225], v166 offset:1024
	ds_read_b128 v[226:229], v166 offset:2048
	ds_read_b128 v[244:247], v166 offset:3072
	s_waitcnt lgkmcnt(0)
	s_barrier
	v_mfma_f32_16x16x32_bf16 v[126:129], v[150:153], v[186:189], v[126:129]
	v_mfma_f32_16x16x32_bf16 v[122:125], v[158:161], v[186:189], v[122:125]
	v_mfma_f32_16x16x32_bf16 v[110:113], v[150:153], v[194:197], v[110:113]
	v_mfma_f32_16x16x32_bf16 v[106:109], v[158:161], v[194:197], v[106:109]
	v_mfma_f32_16x16x32_bf16 v[94:97], v[150:153], v[202:205], v[94:97]
	v_mfma_f32_16x16x32_bf16 v[90:93], v[158:161], v[202:205], v[90:93]
	v_mfma_f32_16x16x32_bf16 v[78:81], v[150:153], v[210:213], v[78:81]
	v_mfma_f32_16x16x32_bf16 v[74:77], v[158:161], v[210:213], v[74:77]
	v_mfma_f32_16x16x32_bf16 v[126:129], v[154:157], v[190:193], v[126:129]
	v_mfma_f32_16x16x32_bf16 v[122:125], v[162:165], v[190:193], v[122:125]
	v_mfma_f32_16x16x32_bf16 v[110:113], v[154:157], v[198:201], v[110:113]
	v_mfma_f32_16x16x32_bf16 v[106:109], v[162:165], v[198:201], v[106:109]
	v_mfma_f32_16x16x32_bf16 v[94:97], v[154:157], v[206:209], v[94:97]
	v_mfma_f32_16x16x32_bf16 v[90:93], v[162:165], v[206:209], v[90:93]
	v_mfma_f32_16x16x32_bf16 v[78:81], v[154:157], v[214:217], v[78:81]
	v_mfma_f32_16x16x32_bf16 v[74:77], v[162:165], v[214:217], v[74:77]
	v_mfma_f32_16x16x32_bf16 v[118:121], v[218:221], v[186:189], v[118:121]
	v_mfma_f32_16x16x32_bf16 v[114:117], v[226:229], v[186:189], v[114:117]
	v_mfma_f32_16x16x32_bf16 v[102:105], v[218:221], v[194:197], v[102:105]
	v_mfma_f32_16x16x32_bf16 v[98:101], v[226:229], v[194:197], v[98:101]
	v_mfma_f32_16x16x32_bf16 v[86:89], v[218:221], v[202:205], v[86:89]
	v_mfma_f32_16x16x32_bf16 v[82:85], v[226:229], v[202:205], v[82:85]
	v_mfma_f32_16x16x32_bf16 v[70:73], v[218:221], v[210:213], v[70:73]
	v_mfma_f32_16x16x32_bf16 v[66:69], v[226:229], v[210:213], v[66:69]
	v_mfma_f32_16x16x32_bf16 v[118:121], v[222:225], v[190:193], v[118:121]
	v_mfma_f32_16x16x32_bf16 v[114:117], v[244:247], v[190:193], v[114:117]
	v_mfma_f32_16x16x32_bf16 v[102:105], v[222:225], v[198:201], v[102:105]
	v_mfma_f32_16x16x32_bf16 v[98:101], v[244:247], v[198:201], v[98:101]
	v_mfma_f32_16x16x32_bf16 v[86:89], v[222:225], v[206:209], v[86:89]
	v_mfma_f32_16x16x32_bf16 v[82:85], v[244:247], v[206:209], v[82:85]
	v_mfma_f32_16x16x32_bf16 v[70:73], v[222:225], v[214:217], v[70:73]
	v_mfma_f32_16x16x32_bf16 v[66:69], v[244:247], v[214:217], v[66:69]
	s_barrier
	ds_read_b128 v[186:189], v176 offset:16384
	ds_read_b128 v[190:193], v176 offset:17408
	ds_read_b128 v[194:197], v176 offset:18432
	ds_read_b128 v[198:201], v176 offset:19456
	ds_read_b128 v[202:205], v176 offset:20480
	ds_read_b128 v[206:209], v176 offset:21504
	ds_read_b128 v[210:213], v176 offset:22528
	ds_read_b128 v[214:217], v176 offset:23552
	s_add_i32 s38, s46, s62
	v_lshl_add_u64 v[166:167], s[52:53], 0, v[134:135]
	s_mov_b32 m0, s38
	v_lshl_add_u64 v[182:183], s[52:53], 0, v[130:131]
	global_load_lds_dwordx4 v[166:167], off
	s_add_i32 m0, s38, 0x2000
	s_nop 0
	global_load_lds_dwordx4 v[182:183], off
	s_add_u32 s76, s52, 0x80000
	s_addc_u32 s77, s53, 0
	s_add_i32 s37, s37, s62
	v_lshl_add_u64 v[234:235], s[76:77], 0, v[134:135]
	s_mov_b32 m0, s37
	s_nop 0
	global_load_lds_dwordx4 v[234:235], off
	v_lshl_add_u64 v[234:235], s[76:77], 0, v[130:131]
	s_add_i32 m0, s37, 0x2000
	s_nop 0
	global_load_lds_dwordx4 v[234:235], off
	s_waitcnt vmcnt(4)
	s_waitcnt lgkmcnt(0)
	s_barrier
; #define PG8_STAGE(bufoff, gbase, voff) do { _Pragma("unroll") for (int _i = 0; _i < 2; ++_i) \
;         __builtin_amdgcn_global_load_lds((const unsigned*)((const char*)(gbase) + (voff)[_i]), (LAS unsigned*)(lds + (bufoff) + ldsw + _i * 8192), 16, 0, 0); } while (0)
; #define PG8_LDA(dst, b, h) do { _Pragma("unroll") for (int m = 0; m < 4; ++m) _Pragma("unroll") for (int k = 0; k < 2; ++k) dst[m][k] = *(const LAS bf16x8*)(lds + PG8_SA(b, h) + aoff + m * 2048 + k * 1024); } while (0)
; #define PG8_WAIT_V(n) asm volatile("s_waitcnt vmcnt(" #n ")" ::: "memory")
; template <class Epi, class Sched>
; __device__ __forceinline__ void gemm_phase(LAS unsigned char* lds, const Gemm g, const Sched& S, const Epi& E) {
;     ...
;         for (int t = 0; t < ntu; t += 2) {
;             const bool last = (t == ntu - 2);
;             const char* a1 = cA + (size_t)(t + 1) * kstep;
;             const char* a2 = last ? nA : cA + (size_t)(t + 2) * kstep; const char* b2 = last ? nB : cB + (size_t)(t + 2) * kstep;
;             const char* a3 = a2 + kstep; const char* b3 = b2 + kstep;
;             if (last && has_next) S.a_ready(nxt);
;             PG8_LDB(B0, 0, 0); PG8_SCHED; PG8_LDA(At, 0, 0); PG8_STAGE(PG8_SA(1, 1), a1 + hstepA, voffA);
;             PG8_WAIT_L(8); PG8_BAR; PG8_WAIT_L(0); PG8_MMA(0, 0, At, B0); PG8_BAR; PG8_SCHED;
;             PG8_LDB(B1, 0, 1); PG8_STAGE(PG8_SB(0, 0), b2, voffB);
;             PG8_BAR; PG8_WAIT_L(0); PG8_MMA(0, 1, At, B1); PG8_BAR;
;             PG8_LDA(At, 0, 1); PG8_STAGE(PG8_SA(0, 0), a2, voffA);
;             PG8_BAR; PG8_WAIT_L(0); PG8_MMA(1, 0, At, B0); PG8_BAR; PG8_SCHED;
;             PG8_STAGE(PG8_SB(0, 1), b2 + hstepB, voffB);
;             PG8_WAIT_V(6); PG8_BAR; PG8_MMA(1, 1, At, B1); PG8_BAR;
;             PG8_LDB(B0, 1, 0); PG8_SCHED; PG8_LDA(At, 1, 0); PG8_STAGE(PG8_SA(0, 1), a2 + hstepA, voffA);
;             PG8_WAIT_L(8); PG8_BAR; PG8_WAIT_L(0); PG8_MMA(0, 0, At, B0); PG8_BAR; PG8_SCHED;
;             PG8_LDB(B1, 1, 1); PG8_STAGE(PG8_SB(1, 0), b3, voffB);
;             PG8_BAR; PG8_WAIT_L(0); PG8_MMA(0, 1, At, B1); PG8_BAR;
;             PG8_LDA(At, 1, 1); PG8_STAGE(PG8_SA(1, 0), a3, voffA);
;             PG8_BAR; PG8_WAIT_L(0); PG8_MMA(1, 0, At, B0); PG8_BAR; PG8_SCHED;
;             PG8_STAGE(PG8_SB(1, 1), b3 + hstepB, voffB);
;             PG8_WAIT_V(6); PG8_BAR; PG8_MMA(1, 1, At, B1); PG8_BAR;
	v_mfma_f32_16x16x32_bf16 v[62:65], v[150:153], v[186:189], v[62:65]
	v_mfma_f32_16x16x32_bf16 v[58:61], v[158:161], v[186:189], v[58:61]
	v_mfma_f32_16x16x32_bf16 v[46:49], v[150:153], v[194:197], v[46:49]
	v_mfma_f32_16x16x32_bf16 v[42:45], v[158:161], v[194:197], v[42:45]
	v_mfma_f32_16x16x32_bf16 v[30:33], v[150:153], v[202:205], v[30:33]
	v_mfma_f32_16x16x32_bf16 v[26:29], v[158:161], v[202:205], v[26:29]
	v_mfma_f32_16x16x32_bf16 v[14:17], v[150:153], v[210:213], v[14:17]
	v_mfma_f32_16x16x32_bf16 v[10:13], v[158:161], v[210:213], v[10:13]
	v_mfma_f32_16x16x32_bf16 v[62:65], v[154:157], v[190:193], v[62:65]
	v_mfma_f32_16x16x32_bf16 v[58:61], v[162:165], v[190:193], v[58:61]
	v_mfma_f32_16x16x32_bf16 v[46:49], v[154:157], v[198:201], v[46:49]
	v_mfma_f32_16x16x32_bf16 v[42:45], v[162:165], v[198:201], v[42:45]
	v_mfma_f32_16x16x32_bf16 v[30:33], v[154:157], v[206:209], v[30:33]
	v_mfma_f32_16x16x32_bf16 v[26:29], v[162:165], v[206:209], v[26:29]
	v_mfma_f32_16x16x32_bf16 v[14:17], v[154:157], v[214:217], v[14:17]
	v_mfma_f32_16x16x32_bf16 v[10:13], v[162:165], v[214:217], v[10:13]
	v_mfma_f32_16x16x32_bf16 v[54:57], v[218:221], v[186:189], v[54:57]
	v_mfma_f32_16x16x32_bf16 v[50:53], v[226:229], v[186:189], v[50:53]
	v_mfma_f32_16x16x32_bf16 v[38:41], v[218:221], v[194:197], v[38:41]
	v_mfma_f32_16x16x32_bf16 v[34:37], v[226:229], v[194:197], v[34:37]
	v_mfma_f32_16x16x32_bf16 v[22:25], v[218:221], v[202:205], v[22:25]
	v_mfma_f32_16x16x32_bf16 v[18:21], v[226:229], v[202:205], v[18:21]
	v_mfma_f32_16x16x32_bf16 v[6:9], v[218:221], v[210:213], v[6:9]
	v_mfma_f32_16x16x32_bf16 v[2:5], v[226:229], v[210:213], v[2:5]
	v_mfma_f32_16x16x32_bf16 v[54:57], v[222:225], v[190:193], v[54:57]
	v_mfma_f32_16x16x32_bf16 v[50:53], v[244:247], v[190:193], v[50:53]
	v_mfma_f32_16x16x32_bf16 v[38:41], v[222:225], v[198:201], v[38:41]
	v_mfma_f32_16x16x32_bf16 v[34:37], v[244:247], v[198:201], v[34:37]
	v_mfma_f32_16x16x32_bf16 v[22:25], v[222:225], v[206:209], v[22:25]
	v_mfma_f32_16x16x32_bf16 v[18:21], v[244:247], v[206:209], v[18:21]
	v_mfma_f32_16x16x32_bf16 v[6:9], v[222:225], v[214:217], v[6:9]
	v_mfma_f32_16x16x32_bf16 v[2:5], v[244:247], v[214:217], v[2:5]
	s_add_i32 s37, 0, 0x18000
	v_add_u32_e32 v162, s37, v170
	s_barrier
	ds_read_b128 v[150:153], v162
	ds_read_b128 v[154:157], v162 offset:1024
	ds_read_b128 v[158:161], v162 offset:2048
	ds_read_b128 v[162:165], v162 offset:3072
	ds_read_b128 v[186:189], v176 offset:32768
	ds_read_b128 v[190:193], v176 offset:33792
	ds_read_b128 v[194:197], v176 offset:34816
	ds_read_b128 v[198:201], v176 offset:35840
	ds_read_b128 v[202:205], v176 offset:36864
	ds_read_b128 v[206:209], v176 offset:37888
	ds_read_b128 v[210:213], v176 offset:38912
	ds_read_b128 v[214:217], v176 offset:39936
	s_mov_b32 m0, s63
	v_lshl_add_u64 v[184:185], s[54:55], 0, v[136:137]
	global_load_lds_dwordx4 v[184:185], off
	v_lshl_add_u64 v[230:231], s[54:55], 0, v[132:133]
	s_mov_b32 m0, s66
	s_nop 0
	global_load_lds_dwordx4 v[230:231], off
	s_add_u32 s54, s54, 0x80000
	s_addc_u32 s55, s55, 0
	s_mov_b32 m0, s67
	v_lshl_add_u64 v[236:237], s[54:55], 0, v[136:137]
	global_load_lds_dwordx4 v[236:237], off
	v_lshl_add_u64 v[236:237], s[54:55], 0, v[132:133]
	s_mov_b32 m0, s68
	s_nop 0
	global_load_lds_dwordx4 v[236:237], off
	s_add_i32 s38, 0, 0x1c000
	v_add_u32_e32 v177, s38, v170
	ds_read_b128 v[218:221], v177
	ds_read_b128 v[222:225], v177 offset:1024
	ds_read_b128 v[226:229], v177 offset:2048
	ds_read_b128 v[244:247], v177 offset:3072
	s_waitcnt lgkmcnt(0)
	s_barrier
	v_mfma_f32_16x16x32_bf16 v[126:129], v[150:153], v[186:189], v[126:129]
	v_mfma_f32_16x16x32_bf16 v[122:125], v[158:161], v[186:189], v[122:125]
	v_mfma_f32_16x16x32_bf16 v[110:113], v[150:153], v[194:197], v[110:113]
	v_mfma_f32_16x16x32_bf16 v[106:109], v[158:161], v[194:197], v[106:109]
	v_mfma_f32_16x16x32_bf16 v[94:97], v[150:153], v[202:205], v[94:97]
	v_mfma_f32_16x16x32_bf16 v[90:93], v[158:161], v[202:205], v[90:93]
	v_mfma_f32_16x16x32_bf16 v[78:81], v[150:153], v[210:213], v[78:81]
	v_mfma_f32_16x16x32_bf16 v[74:77], v[158:161], v[210:213], v[74:77]
	v_mfma_f32_16x16x32_bf16 v[126:129], v[154:157], v[190:193], v[126:129]
	v_mfma_f32_16x16x32_bf16 v[122:125], v[162:165], v[190:193], v[122:125]
	v_mfma_f32_16x16x32_bf16 v[110:113], v[154:157], v[198:201], v[110:113]
	v_mfma_f32_16x16x32_bf16 v[106:109], v[162:165], v[198:201], v[106:109]
	v_mfma_f32_16x16x32_bf16 v[94:97], v[154:157], v[206:209], v[94:97]
	v_mfma_f32_16x16x32_bf16 v[90:93], v[162:165], v[206:209], v[90:93]
	v_mfma_f32_16x16x32_bf16 v[78:81], v[154:157], v[214:217], v[78:81]
	v_mfma_f32_16x16x32_bf16 v[74:77], v[162:165], v[214:217], v[74:77]
	v_mfma_f32_16x16x32_bf16 v[118:121], v[218:221], v[186:189], v[118:121]
	v_mfma_f32_16x16x32_bf16 v[114:117], v[226:229], v[186:189], v[114:117]
	v_mfma_f32_16x16x32_bf16 v[102:105], v[218:221], v[194:197], v[102:105]
	v_mfma_f32_16x16x32_bf16 v[98:101], v[226:229], v[194:197], v[98:101]
	v_mfma_f32_16x16x32_bf16 v[86:89], v[218:221], v[202:205], v[86:89]
	v_mfma_f32_16x16x32_bf16 v[82:85], v[226:229], v[202:205], v[82:85]
	v_mfma_f32_16x16x32_bf16 v[70:73], v[218:221], v[210:213], v[70:73]
	v_mfma_f32_16x16x32_bf16 v[66:69], v[226:229], v[210:213], v[66:69]
	v_mfma_f32_16x16x32_bf16 v[118:121], v[222:225], v[190:193], v[118:121]
	v_mfma_f32_16x16x32_bf16 v[114:117], v[244:247], v[190:193], v[114:117]
	v_mfma_f32_16x16x32_bf16 v[102:105], v[222:225], v[198:201], v[102:105]
	v_mfma_f32_16x16x32_bf16 v[98:101], v[244:247], v[198:201], v[98:101]
	v_mfma_f32_16x16x32_bf16 v[86:89], v[222:225], v[206:209], v[86:89]
	v_mfma_f32_16x16x32_bf16 v[82:85], v[244:247], v[206:209], v[82:85]
	v_mfma_f32_16x16x32_bf16 v[70:73], v[222:225], v[214:217], v[70:73]
	v_mfma_f32_16x16x32_bf16 v[66:69], v[244:247], v[214:217], v[66:69]
	s_barrier
; #define PG8_BAR __builtin_amdgcn_s_barrier()
;     __device__ __forceinline__ void operator()(f32x4 (&acc)[2][2][4][2], const Unit& u, int wr, int wc, int fr, int fq) const {
;         const int pn = u.pn, lane = fq * 16 + fr, pmb = u.pm % 17; const bool lat = pmb != 0;
;         const int row0 = u.pm * BM + wr * 64 + fr, colq = wc * 32 + 8 * fq;
;         bf16_t* zp = Z + (size_t)row0 * ZS + pn * BM + colq;
;     ...
;         if (pn < 4) {
; #pragma unroll
;             EW_ROWS { float ss = 0.f;
; #pragma unroll
;                 for (int bj = 0; bj < 2; ++bj) { float v[8];
; #pragma unroll
; template <class Epi, class Sched>
; __device__ __forceinline__ void gemm_phase(LAS unsigned char* lds, const Gemm g, const Sched& S, const Epi& E) {
;     ...
;         for (int t = 0; t < ntu; t += 2) {
;             const bool last = (t == ntu - 2);
;             const char* a1 = cA + (size_t)(t + 1) * kstep;
;             const char* a2 = last ? nA : cA + (size_t)(t + 2) * kstep; const char* b2 = last ? nB : cB + (size_t)(t + 2) * kstep;
;             const char* a3 = a2 + kstep; const char* b3 = b2 + kstep;
;             if (last && has_next) S.a_ready(nxt);
;             PG8_LDB(B0, 0, 0); PG8_SCHED; PG8_LDA(At, 0, 0); PG8_STAGE(PG8_SA(1, 1), a1 + hstepA, voffA);
;             PG8_WAIT_L(8); PG8_BAR; PG8_WAIT_L(0); PG8_MMA(0, 0, At, B0); PG8_BAR; PG8_SCHED;
;             PG8_LDB(B1, 0, 1); PG8_STAGE(PG8_SB(0, 0), b2, voffB);
;             PG8_BAR; PG8_WAIT_L(0); PG8_MMA(0, 1, At, B1); PG8_BAR;
;             PG8_LDA(At, 0, 1); PG8_STAGE(PG8_SA(0, 0), a2, voffA);
;             PG8_BAR; PG8_WAIT_L(0); PG8_MMA(1, 0, At, B0); PG8_BAR; PG8_SCHED;
;             PG8_STAGE(PG8_SB(0, 1), b2 + hstepB, voffB);
;             PG8_WAIT_V(6); PG8_BAR; PG8_MMA(1, 1, At, B1); PG8_BAR;
;             PG8_LDB(B0, 1, 0); PG8_SCHED; PG8_LDA(At, 1, 0); PG8_STAGE(PG8_SA(0, 1), a2 + hstepA, voffA);
;             PG8_WAIT_L(8); PG8_BAR; PG8_WAIT_L(0); PG8_MMA(0, 0, At, B0); PG8_BAR; PG8_SCHED;
;             PG8_LDB(B1, 1, 1); PG8_STAGE(PG8_SB(1, 0), b3, voffB);
;             PG8_BAR; PG8_WAIT_L(0); PG8_MMA(0, 1, At, B1); PG8_BAR;
;             PG8_LDA(At, 1, 1); PG8_STAGE(PG8_SA(1, 0), a3, voffA);
;             PG8_BAR; PG8_WAIT_L(0); PG8_MMA(1, 0, At, B0); PG8_BAR; PG8_SCHED;
;             PG8_STAGE(PG8_SB(1, 1), b3 + hstepB, voffB);
;             PG8_WAIT_V(6); PG8_BAR; PG8_MMA(1, 1, At, B1); PG8_BAR;
	ds_read_b128 v[186:189], v176 offset:49152
	ds_read_b128 v[190:193], v176 offset:50176
	ds_read_b128 v[194:197], v176 offset:51200
	ds_read_b128 v[198:201], v176 offset:52224
	ds_read_b128 v[202:205], v176 offset:53248
	ds_read_b128 v[206:209], v176 offset:54272
	ds_read_b128 v[210:213], v176 offset:55296
	ds_read_b128 v[214:217], v176 offset:56320
	s_add_i32 s37, s37, s62
	v_lshl_add_u64 v[166:167], v[166:167], 0, s[92:93]
	s_mov_b32 m0, s37
	s_nop 0
	global_load_lds_dwordx4 v[166:167], off
	v_lshl_add_u64 v[166:167], v[182:183], 0, s[92:93]
	s_add_i32 m0, s37, 0x2000
	s_nop 0
	global_load_lds_dwordx4 v[166:167], off
	s_add_u32 s52, s52, 0x80080
	s_addc_u32 s53, s53, 0
	s_add_i32 s37, s38, s62
	v_lshl_add_u64 v[238:239], s[52:53], 0, v[134:135]
	s_mov_b32 m0, s37
	s_nop 0
	global_load_lds_dwordx4 v[238:239], off
	v_lshl_add_u64 v[238:239], s[52:53], 0, v[130:131]
	s_add_i32 m0, s37, 0x2000
	s_nop 0
	global_load_lds_dwordx4 v[238:239], off
	s_waitcnt vmcnt(4)
	s_waitcnt lgkmcnt(0)
	s_barrier
	v_mfma_f32_16x16x32_bf16 v[62:65], v[150:153], v[186:189], v[62:65]
	v_mfma_f32_16x16x32_bf16 v[58:61], v[158:161], v[186:189], v[58:61]
	v_mfma_f32_16x16x32_bf16 v[46:49], v[150:153], v[194:197], v[46:49]
	v_mfma_f32_16x16x32_bf16 v[42:45], v[158:161], v[194:197], v[42:45]
	v_mfma_f32_16x16x32_bf16 v[30:33], v[150:153], v[202:205], v[30:33]
	v_mfma_f32_16x16x32_bf16 v[26:29], v[158:161], v[202:205], v[26:29]
	v_mfma_f32_16x16x32_bf16 v[14:17], v[150:153], v[210:213], v[14:17]
	v_mfma_f32_16x16x32_bf16 v[10:13], v[158:161], v[210:213], v[10:13]
	v_mfma_f32_16x16x32_bf16 v[62:65], v[154:157], v[190:193], v[62:65]
	v_mfma_f32_16x16x32_bf16 v[58:61], v[162:165], v[190:193], v[58:61]
	v_mfma_f32_16x16x32_bf16 v[46:49], v[154:157], v[198:201], v[46:49]
	v_mfma_f32_16x16x32_bf16 v[42:45], v[162:165], v[198:201], v[42:45]
	v_mfma_f32_16x16x32_bf16 v[30:33], v[154:157], v[206:209], v[30:33]
	v_mfma_f32_16x16x32_bf16 v[26:29], v[162:165], v[206:209], v[26:29]
	v_mfma_f32_16x16x32_bf16 v[14:17], v[154:157], v[214:217], v[14:17]
	v_mfma_f32_16x16x32_bf16 v[10:13], v[162:165], v[214:217], v[10:13]
	v_mfma_f32_16x16x32_bf16 v[54:57], v[218:221], v[186:189], v[54:57]
	v_mfma_f32_16x16x32_bf16 v[50:53], v[226:229], v[186:189], v[50:53]
	v_mfma_f32_16x16x32_bf16 v[38:41], v[218:221], v[194:197], v[38:41]
	v_mfma_f32_16x16x32_bf16 v[34:37], v[226:229], v[194:197], v[34:37]
	v_mfma_f32_16x16x32_bf16 v[22:25], v[218:221], v[202:205], v[22:25]
	v_mfma_f32_16x16x32_bf16 v[18:21], v[226:229], v[202:205], v[18:21]
	v_mfma_f32_16x16x32_bf16 v[6:9], v[218:221], v[210:213], v[6:9]
	v_mfma_f32_16x16x32_bf16 v[2:5], v[226:229], v[210:213], v[2:5]
	v_mfma_f32_16x16x32_bf16 v[54:57], v[222:225], v[190:193], v[54:57]
	v_mfma_f32_16x16x32_bf16 v[50:53], v[244:247], v[190:193], v[50:53]
	v_mfma_f32_16x16x32_bf16 v[38:41], v[222:225], v[198:201], v[38:41]
	v_mfma_f32_16x16x32_bf16 v[34:37], v[244:247], v[198:201], v[34:37]
	v_mfma_f32_16x16x32_bf16 v[22:25], v[222:225], v[206:209], v[22:25]
	v_mfma_f32_16x16x32_bf16 v[18:21], v[244:247], v[206:209], v[18:21]
	v_mfma_f32_16x16x32_bf16 v[6:9], v[222:225], v[214:217], v[6:9]
	v_mfma_f32_16x16x32_bf16 v[2:5], v[244:247], v[214:217], v[2:5]
	s_add_i32 s36, s36, 2
	s_add_u32 s12, s12, 0x100
	s_addc_u32 s13, s13, 0
	s_add_u32 s29, s29, 0x100
	s_addc_u32 s30, s30, 0
	s_cmp_gt_u32 s36, 29
	s_barrier
	s_cbranch_scc0 .LBB0_381
	v_lshl_add_u32 v152, s0, 8, v169
	v_mov_b64_e32 v[150:151], s[16:17]
	v_mad_i64_i32 v[150:151], s[12:13], v152, s84, v[150:151]
	s_lshl_b32 s12, s33, 8
	s_ashr_i32 s13, s12, 31
	v_lshl_add_u64 v[150:151], s[12:13], 1, v[150:151]
	v_readlane_b32 s76, v255, 26
	v_ashrrev_i32_e32 v153, 31, v152
	v_lshl_add_u64 v[150:151], v[150:151], 0, v[178:179]
	s_cmp_gt_i32 s33, 3
	s_mov_b64 s[12:13], -1
	v_readlane_b32 s77, v255, 27
	s_mov_b64 s[36:37], s[74:75]
	v_mov_b32_e32 v230, 0x3727c5ac
	s_cbranch_scc0 .LBB0_446
	s_cmp_gt_u32 s33, 7
	s_cbranch_scc0 .LBB0_443
	s_cmp_gt_u32 s33, 11
	s_cbranch_scc0 .LBB0_424
	s_mul_hi_i32 s1, s0, 0x78787879
	s_lshr_b32 s12, s1, 31
	s_ashr_i32 s1, s1, 3
	s_add_i32 s1, s1, s12
	s_mul_i32 s1, s1, 17
	s_sub_i32 s1, s0, s1
	s_cmp_lg_u32 s1, 0
	s_cselect_b64 s[28:29], -1, 0
	s_cmp_lt_u32 s33, 20
	s_cselect_b64 s[12:13], -1, 0
	s_and_b64 s[12:13], s[12:13], s[28:29]
	s_andn2_b64 vcc, exec, s[12:13]
	s_mov_b64 s[12:13], -1
	s_cbranch_vccz .LBB0_421
	s_cmp_gt_u32 s33, 23
	s_cbranch_scc0 .LBB0_418
	s_cmp_gt_u32 s33, 47
	s_cbranch_scc0 .LBB0_415
	s_andn2_b64 vcc, exec, s[4:5]
	s_cbranch_vccnz .LBB0_414
	s_lshl_b32 s23, s1, 2
	v_cndmask_b32_e64 v154, 0, 1, s[28:29]
	v_cmp_ne_u32_e64 s[12:13], 1, v154
	s_andn2_b64 vcc, exec, s[28:29]
	s_add_i32 s23, s23, s79
	s_cbranch_vccnz .LBB0_391
	v_mov_b32_e32 v154, s23
	v_cndmask_b32_e64 v154, v168, v154, s[6:7]
	v_lshlrev_b32_e32 v154, 4, v154
	v_ashrrev_i32_e32 v155, 31, v154
	v_lshl_add_u64 v[154:155], v[154:155], 3, v[138:139]
	global_load_dwordx4 v[164:167], v[154:155], off offset:16
	global_load_dwordx4 v[156:159], v[154:155], off
	s_waitcnt vmcnt(0)
	v_pk_mul_f32 v[162:163], v[122:123], v[164:165] op_sel:[1,1] op_sel_hi:[0,1]
	v_pk_mul_f32 v[184:185], v[126:127], v[156:157] op_sel:[1,1] op_sel_hi:[0,1]
	v_pk_fma_f32 v[154:155], v[126:127], v[156:157], v[184:185] op_sel_hi:[1,0,1]
	v_pk_mul_f32 v[182:183], v[126:127], v[156:157]
	v_mov_b32_e32 v154, v159
	v_pk_mul_f32 v[160:161], v[128:129], v[154:155] op_sel:[1,0] op_sel_hi:[0,0]
	v_mul_f32_e32 v154, v125, v167
	v_pk_fma_f32 v[156:157], v[128:129], v[158:159], v[160:161] op_sel_hi:[1,0,1] neg_lo:[0,0,1] neg_hi:[0,0,1]
	v_pk_fma_f32 v[158:159], v[128:129], v[158:159], v[160:161] op_sel_hi:[1,0,1]
	v_pk_fma_f32 v[160:161], v[122:123], v[164:165], v[162:163] op_sel_hi:[1,0,1] neg_lo:[0,0,1] neg_hi:[0,0,1]
	v_pk_fma_f32 v[162:163], v[122:123], v[164:165], v[162:163] op_sel_hi:[1,0,1]
	v_pk_fma_f32 v[164:165], v[124:125], v[166:167], v[154:155] op_sel_hi:[1,1,0] neg_lo:[0,0,1] neg_hi:[0,0,1]
	v_mul_f32_e32 v154, v124, v167
	v_pk_fma_f32 v[166:167], v[124:125], v[166:167], v[154:155] op_sel:[1,0,0] op_sel_hi:[0,1,0]
	v_sub_f32_e32 v154, v182, v184
	s_branch .LBB0_392

; #define PG8_STAGE(bufoff, gbase, voff) do { _Pragma("unroll") for (int _i = 0; _i < 2; ++_i) \
;         __builtin_amdgcn_global_load_lds((const unsigned*)((const char*)(gbase) + (voff)[_i]), (LAS unsigned*)(lds + (bufoff) + ldsw + _i * 8192), 16, 0, 0); } while (0)
; #define PG8_LDA(dst, b, h) do { _Pragma("unroll") for (int m = 0; m < 4; ++m) _Pragma("unroll") for (int k = 0; k < 2; ++k) dst[m][k] = *(const LAS bf16x8*)(lds + PG8_SA(b, h) + aoff + m * 2048 + k * 1024); } while (0)
; #define PG8_WAIT_V(n) asm volatile("s_waitcnt vmcnt(" #n ")" ::: "memory")
; template <class Epi, class Sched>
; __device__ __forceinline__ void gemm_phase(LAS unsigned char* lds, const Gemm g, const Sched& S, const Epi& E) {
;     ...
;         for (int t = 0; t < ntu; t += 2) {
;             const bool last = (t == ntu - 2);
;             const char* a1 = cA + (size_t)(t + 1) * kstep;
;             const char* a2 = last ? nA : cA + (size_t)(t + 2) * kstep; const char* b2 = last ? nB : cB + (size_t)(t + 2) * kstep;
;             const char* a3 = a2 + kstep; const char* b3 = b2 + kstep;
;             if (last && has_next) S.a_ready(nxt);
;             PG8_LDB(B0, 0, 0); PG8_SCHED; PG8_LDA(At, 0, 0); PG8_STAGE(PG8_SA(1, 1), a1 + hstepA, voffA);
;             PG8_WAIT_L(8); PG8_BAR; PG8_WAIT_L(0); PG8_MMA(0, 0, At, B0); PG8_BAR; PG8_SCHED;
;             PG8_LDB(B1, 0, 1); PG8_STAGE(PG8_SB(0, 0), b2, voffB);
;             PG8_BAR; PG8_WAIT_L(0); PG8_MMA(0, 1, At, B1); PG8_BAR;
;             PG8_LDA(At, 0, 1); PG8_STAGE(PG8_SA(0, 0), a2, voffA);
;             PG8_BAR; PG8_WAIT_L(0); PG8_MMA(1, 0, At, B0); PG8_BAR; PG8_SCHED;
;             PG8_STAGE(PG8_SB(0, 1), b2 + hstepB, voffB);
;             PG8_WAIT_V(6); PG8_BAR; PG8_MMA(1, 1, At, B1); PG8_BAR;
;             PG8_LDB(B0, 1, 0); PG8_SCHED; PG8_LDA(At, 1, 0); PG8_STAGE(PG8_SA(0, 1), a2 + hstepA, voffA);
;             PG8_WAIT_L(8); PG8_BAR; PG8_WAIT_L(0); PG8_MMA(0, 0, At, B0); PG8_BAR; PG8_SCHED;
;             PG8_LDB(B1, 1, 1); PG8_STAGE(PG8_SB(1, 0), b3, voffB);
;             PG8_BAR; PG8_WAIT_L(0); PG8_MMA(0, 1, At, B1); PG8_BAR;
;             PG8_LDA(At, 1, 1); PG8_STAGE(PG8_SA(1, 0), a3, voffA);
;             PG8_BAR; PG8_WAIT_L(0); PG8_MMA(1, 0, At, B0); PG8_BAR; PG8_SCHED;
;             PG8_STAGE(PG8_SB(1, 1), b3 + hstepB, voffB);
;             PG8_WAIT_V(6); PG8_BAR; PG8_MMA(1, 1, At, B1); PG8_BAR;
.LBB0_571:
	s_add_u32 s6, s56, 0x100
	s_addc_u32 s7, s57, 0
	s_add_i32 s77, 0, 0x10000
	v_add_u32_e32 v142, s77, v197
	ds_read_b128 v[130:133], v142
	ds_read_b128 v[134:137], v142 offset:1024
	ds_read_b128 v[138:141], v142 offset:2048
	ds_read_b128 v[142:145], v142 offset:3072
	s_cmp_eq_u32 s76, 4
	s_cselect_b32 s63, s53, s7
	s_cselect_b32 s62, s52, s6
	s_cselect_b32 s59, s28, s51
	s_cselect_b32 s58, s29, s30
	ds_read_b128 v[164:167], v201
	ds_read_b128 v[168:171], v201 offset:1024
	ds_read_b128 v[172:175], v201 offset:2048
	ds_read_b128 v[186:189], v201 offset:3072
	ds_read_b128 v[202:205], v201 offset:4096
	ds_read_b128 v[206:209], v201 offset:5120
	ds_read_b128 v[210:213], v201 offset:6144
	ds_read_b128 v[214:217], v201 offset:7168
	s_mov_b32 s98, 0xffe7c000
	s_mov_b32 s99, -1
	v_lshl_add_u64 v[232:233], s[56:57], 0, v[160:161]
	v_lshl_add_u64 v[232:233], v[232:233], 0, s[98:99]
	s_mov_b32 m0, s66
	s_nop 0
	global_load_lds_dwordx4 v[232:233], off
	v_lshl_add_u64 v[232:233], s[56:57], 0, v[162:163]
	v_lshl_add_u64 v[232:233], v[232:233], 0, s[98:99]
	s_mov_b32 m0, s67
	s_nop 0
	global_load_lds_dwordx4 v[232:233], off
	v_lshl_add_u64 v[232:233], s[56:57], 0, v[160:161]
	s_add_i32 m0, s38, 0xc000
	s_nop 0
	global_load_lds_dwordx4 v[232:233], off
	v_lshl_add_u64 v[232:233], s[56:57], 0, v[162:163]
	s_add_i32 m0, s38, 0xe000
	s_nop 0
	global_load_lds_dwordx4 v[232:233], off
	s_add_i32 s79, 0, 0x14000
	v_add_u32_e32 v176, s79, v197
	ds_read_b128 v[218:221], v176
	ds_read_b128 v[222:225], v176 offset:1024
	ds_read_b128 v[226:229], v176 offset:2048
	ds_read_b128 v[244:247], v176 offset:3072
	s_waitcnt lgkmcnt(0)
	s_barrier
	v_mfma_f32_16x16x32_bf16 v[126:129], v[130:133], v[164:167], v[126:129]
	v_mfma_f32_16x16x32_bf16 v[122:125], v[138:141], v[164:167], v[122:125]
	v_mfma_f32_16x16x32_bf16 v[118:121], v[130:133], v[172:175], v[118:121]
	v_mfma_f32_16x16x32_bf16 v[114:117], v[138:141], v[172:175], v[114:117]
	v_mfma_f32_16x16x32_bf16 v[110:113], v[130:133], v[202:205], v[110:113]
	v_mfma_f32_16x16x32_bf16 v[106:109], v[138:141], v[202:205], v[106:109]
	v_mfma_f32_16x16x32_bf16 v[102:105], v[130:133], v[210:213], v[102:105]
	v_mfma_f32_16x16x32_bf16 v[98:101], v[138:141], v[210:213], v[98:101]
	v_mfma_f32_16x16x32_bf16 v[126:129], v[134:137], v[168:171], v[126:129]
	v_mfma_f32_16x16x32_bf16 v[122:125], v[142:145], v[168:171], v[122:125]
	v_mfma_f32_16x16x32_bf16 v[118:121], v[134:137], v[186:189], v[118:121]
	v_mfma_f32_16x16x32_bf16 v[114:117], v[142:145], v[186:189], v[114:117]
	v_mfma_f32_16x16x32_bf16 v[110:113], v[134:137], v[206:209], v[110:113]
	v_mfma_f32_16x16x32_bf16 v[106:109], v[142:145], v[206:209], v[106:109]
	v_mfma_f32_16x16x32_bf16 v[102:105], v[134:137], v[214:217], v[102:105]
	v_mfma_f32_16x16x32_bf16 v[98:101], v[142:145], v[214:217], v[98:101]
	v_mfma_f32_16x16x32_bf16 v[94:97], v[218:221], v[164:167], v[94:97]
	v_mfma_f32_16x16x32_bf16 v[90:93], v[226:229], v[164:167], v[90:93]
	v_mfma_f32_16x16x32_bf16 v[86:89], v[218:221], v[172:175], v[86:89]
	v_mfma_f32_16x16x32_bf16 v[82:85], v[226:229], v[172:175], v[82:85]
	v_mfma_f32_16x16x32_bf16 v[78:81], v[218:221], v[202:205], v[78:81]
	v_mfma_f32_16x16x32_bf16 v[74:77], v[226:229], v[202:205], v[74:77]
	v_mfma_f32_16x16x32_bf16 v[70:73], v[218:221], v[210:213], v[70:73]
	v_mfma_f32_16x16x32_bf16 v[66:69], v[226:229], v[210:213], v[66:69]
	v_mfma_f32_16x16x32_bf16 v[94:97], v[222:225], v[168:171], v[94:97]
	v_mfma_f32_16x16x32_bf16 v[90:93], v[244:247], v[168:171], v[90:93]
	v_mfma_f32_16x16x32_bf16 v[86:89], v[222:225], v[186:189], v[86:89]
	v_mfma_f32_16x16x32_bf16 v[82:85], v[244:247], v[186:189], v[82:85]
	v_mfma_f32_16x16x32_bf16 v[78:81], v[222:225], v[206:209], v[78:81]
	v_mfma_f32_16x16x32_bf16 v[74:77], v[244:247], v[206:209], v[74:77]
	v_mfma_f32_16x16x32_bf16 v[70:73], v[222:225], v[214:217], v[70:73]
	v_mfma_f32_16x16x32_bf16 v[66:69], v[244:247], v[214:217], v[66:69]
	s_barrier
	ds_read_b128 v[164:167], v201 offset:16384
	ds_read_b128 v[168:171], v201 offset:17408
	ds_read_b128 v[172:175], v201 offset:18432
	ds_read_b128 v[186:189], v201 offset:19456
	ds_read_b128 v[202:205], v201 offset:20480
	ds_read_b128 v[206:209], v201 offset:21504
	ds_read_b128 v[210:213], v201 offset:22528
	ds_read_b128 v[214:217], v201 offset:23552
	s_add_i32 s56, s77, s33
	v_lshl_add_u64 v[176:177], s[58:59], 0, v[152:153]
	s_mov_b32 m0, s56
	v_lshl_add_u64 v[182:183], s[58:59], 0, v[148:149]
	global_load_lds_dwordx4 v[176:177], off
	s_add_i32 m0, s56, 0x2000
	s_nop 0
	global_load_lds_dwordx4 v[182:183], off
	s_add_u32 s56, s58, 0x20000
	s_addc_u32 s57, s59, 0
	s_add_i32 s77, s79, s33
	v_lshl_add_u64 v[234:235], s[56:57], 0, v[152:153]
	s_mov_b32 m0, s77
	s_nop 0
	global_load_lds_dwordx4 v[234:235], off
	v_lshl_add_u64 v[234:235], s[56:57], 0, v[148:149]
	s_add_i32 m0, s77, 0x2000
	s_nop 0
	global_load_lds_dwordx4 v[234:235], off
	s_waitcnt vmcnt(4)
	s_waitcnt lgkmcnt(0)
	s_barrier
; #define PG8_STAGE(bufoff, gbase, voff) do { _Pragma("unroll") for (int _i = 0; _i < 2; ++_i) \
;         __builtin_amdgcn_global_load_lds((const unsigned*)((const char*)(gbase) + (voff)[_i]), (LAS unsigned*)(lds + (bufoff) + ldsw + _i * 8192), 16, 0, 0); } while (0)
; #define PG8_LDA(dst, b, h) do { _Pragma("unroll") for (int m = 0; m < 4; ++m) _Pragma("unroll") for (int k = 0; k < 2; ++k) dst[m][k] = *(const LAS bf16x8*)(lds + PG8_SA(b, h) + aoff + m * 2048 + k * 1024); } while (0)
; #define PG8_WAIT_V(n) asm volatile("s_waitcnt vmcnt(" #n ")" ::: "memory")
; template <class Epi, class Sched>
; __device__ __forceinline__ void gemm_phase(LAS unsigned char* lds, const Gemm g, const Sched& S, const Epi& E) {
;     ...
;         for (int t = 0; t < ntu; t += 2) {
;             const bool last = (t == ntu - 2);
;             const char* a1 = cA + (size_t)(t + 1) * kstep;
;             const char* a2 = last ? nA : cA + (size_t)(t + 2) * kstep; const char* b2 = last ? nB : cB + (size_t)(t + 2) * kstep;
;             const char* a3 = a2 + kstep; const char* b3 = b2 + kstep;
;             if (last && has_next) S.a_ready(nxt);
;             PG8_LDB(B0, 0, 0); PG8_SCHED; PG8_LDA(At, 0, 0); PG8_STAGE(PG8_SA(1, 1), a1 + hstepA, voffA);
;             PG8_WAIT_L(8); PG8_BAR; PG8_WAIT_L(0); PG8_MMA(0, 0, At, B0); PG8_BAR; PG8_SCHED;
;             PG8_LDB(B1, 0, 1); PG8_STAGE(PG8_SB(0, 0), b2, voffB);
;             PG8_BAR; PG8_WAIT_L(0); PG8_MMA(0, 1, At, B1); PG8_BAR;
;             PG8_LDA(At, 0, 1); PG8_STAGE(PG8_SA(0, 0), a2, voffA);
;             PG8_BAR; PG8_WAIT_L(0); PG8_MMA(1, 0, At, B0); PG8_BAR; PG8_SCHED;
;             PG8_STAGE(PG8_SB(0, 1), b2 + hstepB, voffB);
;             PG8_WAIT_V(6); PG8_BAR; PG8_MMA(1, 1, At, B1); PG8_BAR;
;             PG8_LDB(B0, 1, 0); PG8_SCHED; PG8_LDA(At, 1, 0); PG8_STAGE(PG8_SA(0, 1), a2 + hstepA, voffA);
;             PG8_WAIT_L(8); PG8_BAR; PG8_WAIT_L(0); PG8_MMA(0, 0, At, B0); PG8_BAR; PG8_SCHED;
;             PG8_LDB(B1, 1, 1); PG8_STAGE(PG8_SB(1, 0), b3, voffB);
;             PG8_BAR; PG8_WAIT_L(0); PG8_MMA(0, 1, At, B1); PG8_BAR;
;             PG8_LDA(At, 1, 1); PG8_STAGE(PG8_SA(1, 0), a3, voffA);
;             PG8_BAR; PG8_WAIT_L(0); PG8_MMA(1, 0, At, B0); PG8_BAR; PG8_SCHED;
;             PG8_STAGE(PG8_SB(1, 1), b3 + hstepB, voffB);
;             PG8_WAIT_V(6); PG8_BAR; PG8_MMA(1, 1, At, B1); PG8_BAR;
	v_mfma_f32_16x16x32_bf16 v[62:65], v[130:133], v[164:167], v[62:65]
	v_mfma_f32_16x16x32_bf16 v[58:61], v[138:141], v[164:167], v[58:61]
	v_mfma_f32_16x16x32_bf16 v[54:57], v[130:133], v[172:175], v[54:57]
	v_mfma_f32_16x16x32_bf16 v[50:53], v[138:141], v[172:175], v[50:53]
	v_mfma_f32_16x16x32_bf16 v[46:49], v[130:133], v[202:205], v[46:49]
	v_mfma_f32_16x16x32_bf16 v[42:45], v[138:141], v[202:205], v[42:45]
	v_mfma_f32_16x16x32_bf16 v[38:41], v[130:133], v[210:213], v[38:41]
	v_mfma_f32_16x16x32_bf16 v[34:37], v[138:141], v[210:213], v[34:37]
	v_mfma_f32_16x16x32_bf16 v[62:65], v[134:137], v[168:171], v[62:65]
	v_mfma_f32_16x16x32_bf16 v[58:61], v[142:145], v[168:171], v[58:61]
	v_mfma_f32_16x16x32_bf16 v[54:57], v[134:137], v[186:189], v[54:57]
	v_mfma_f32_16x16x32_bf16 v[50:53], v[142:145], v[186:189], v[50:53]
	v_mfma_f32_16x16x32_bf16 v[46:49], v[134:137], v[206:209], v[46:49]
	v_mfma_f32_16x16x32_bf16 v[42:45], v[142:145], v[206:209], v[42:45]
	v_mfma_f32_16x16x32_bf16 v[38:41], v[134:137], v[214:217], v[38:41]
	v_mfma_f32_16x16x32_bf16 v[34:37], v[142:145], v[214:217], v[34:37]
	v_mfma_f32_16x16x32_bf16 v[30:33], v[218:221], v[164:167], v[30:33]
	v_mfma_f32_16x16x32_bf16 v[26:29], v[226:229], v[164:167], v[26:29]
	v_mfma_f32_16x16x32_bf16 v[22:25], v[218:221], v[172:175], v[22:25]
	v_mfma_f32_16x16x32_bf16 v[18:21], v[226:229], v[172:175], v[18:21]
	v_mfma_f32_16x16x32_bf16 v[14:17], v[218:221], v[202:205], v[14:17]
	v_mfma_f32_16x16x32_bf16 v[10:13], v[226:229], v[202:205], v[10:13]
	v_mfma_f32_16x16x32_bf16 v[6:9], v[218:221], v[210:213], v[6:9]
	v_mfma_f32_16x16x32_bf16 v[2:5], v[226:229], v[210:213], v[2:5]
	v_mfma_f32_16x16x32_bf16 v[30:33], v[222:225], v[168:171], v[30:33]
	v_mfma_f32_16x16x32_bf16 v[26:29], v[244:247], v[168:171], v[26:29]
	v_mfma_f32_16x16x32_bf16 v[22:25], v[222:225], v[186:189], v[22:25]
	v_mfma_f32_16x16x32_bf16 v[18:21], v[244:247], v[186:189], v[18:21]
	v_mfma_f32_16x16x32_bf16 v[14:17], v[222:225], v[206:209], v[14:17]
	v_mfma_f32_16x16x32_bf16 v[10:13], v[244:247], v[206:209], v[10:13]
	v_mfma_f32_16x16x32_bf16 v[6:9], v[222:225], v[214:217], v[6:9]
	v_mfma_f32_16x16x32_bf16 v[2:5], v[244:247], v[214:217], v[2:5]
	s_add_i32 s77, 0, 0x18000
	v_add_u32_e32 v142, s77, v197
	s_barrier
	ds_read_b128 v[130:133], v142
	ds_read_b128 v[134:137], v142 offset:1024
	ds_read_b128 v[138:141], v142 offset:2048
	ds_read_b128 v[142:145], v142 offset:3072
	ds_read_b128 v[164:167], v201 offset:32768
	ds_read_b128 v[168:171], v201 offset:33792
	ds_read_b128 v[172:175], v201 offset:34816
	ds_read_b128 v[186:189], v201 offset:35840
	ds_read_b128 v[202:205], v201 offset:36864
	ds_read_b128 v[206:209], v201 offset:37888
	ds_read_b128 v[210:213], v201 offset:38912
	ds_read_b128 v[214:217], v201 offset:39936
	s_mov_b32 m0, s38
	v_lshl_add_u64 v[184:185], s[62:63], 0, v[154:155]
	global_load_lds_dwordx4 v[184:185], off
	v_lshl_add_u64 v[190:191], s[62:63], 0, v[150:151]
	s_mov_b32 m0, s39
	s_nop 0
	global_load_lds_dwordx4 v[190:191], off
	s_add_u32 s56, s62, 0x184000
	s_addc_u32 s57, s63, 0
	s_mov_b32 m0, s46
	v_lshl_add_u64 v[236:237], s[56:57], 0, v[154:155]
	global_load_lds_dwordx4 v[236:237], off
	v_lshl_add_u64 v[236:237], s[56:57], 0, v[150:151]
	s_mov_b32 m0, s64
	s_nop 0
	global_load_lds_dwordx4 v[236:237], off
	s_add_i32 s62, 0, 0x1c000
	v_add_u32_e32 v178, s62, v197
	ds_read_b128 v[218:221], v178
	ds_read_b128 v[222:225], v178 offset:1024
	ds_read_b128 v[226:229], v178 offset:2048
	ds_read_b128 v[244:247], v178 offset:3072
	s_waitcnt lgkmcnt(0)
	s_barrier
	v_mfma_f32_16x16x32_bf16 v[126:129], v[130:133], v[164:167], v[126:129]
	v_mfma_f32_16x16x32_bf16 v[122:125], v[138:141], v[164:167], v[122:125]
	v_mfma_f32_16x16x32_bf16 v[118:121], v[130:133], v[172:175], v[118:121]
	v_mfma_f32_16x16x32_bf16 v[114:117], v[138:141], v[172:175], v[114:117]
	v_mfma_f32_16x16x32_bf16 v[110:113], v[130:133], v[202:205], v[110:113]
	v_mfma_f32_16x16x32_bf16 v[106:109], v[138:141], v[202:205], v[106:109]
	v_mfma_f32_16x16x32_bf16 v[102:105], v[130:133], v[210:213], v[102:105]
	v_mfma_f32_16x16x32_bf16 v[98:101], v[138:141], v[210:213], v[98:101]
	v_mfma_f32_16x16x32_bf16 v[126:129], v[134:137], v[168:171], v[126:129]
	v_mfma_f32_16x16x32_bf16 v[122:125], v[142:145], v[168:171], v[122:125]
	v_mfma_f32_16x16x32_bf16 v[118:121], v[134:137], v[186:189], v[118:121]
	v_mfma_f32_16x16x32_bf16 v[114:117], v[142:145], v[186:189], v[114:117]
	v_mfma_f32_16x16x32_bf16 v[110:113], v[134:137], v[206:209], v[110:113]
	v_mfma_f32_16x16x32_bf16 v[106:109], v[142:145], v[206:209], v[106:109]
	v_mfma_f32_16x16x32_bf16 v[102:105], v[134:137], v[214:217], v[102:105]
	v_mfma_f32_16x16x32_bf16 v[98:101], v[142:145], v[214:217], v[98:101]
	v_mfma_f32_16x16x32_bf16 v[94:97], v[218:221], v[164:167], v[94:97]
	v_mfma_f32_16x16x32_bf16 v[90:93], v[226:229], v[164:167], v[90:93]
	v_mfma_f32_16x16x32_bf16 v[86:89], v[218:221], v[172:175], v[86:89]
	v_mfma_f32_16x16x32_bf16 v[82:85], v[226:229], v[172:175], v[82:85]
	v_mfma_f32_16x16x32_bf16 v[78:81], v[218:221], v[202:205], v[78:81]
	v_mfma_f32_16x16x32_bf16 v[74:77], v[226:229], v[202:205], v[74:77]
	v_mfma_f32_16x16x32_bf16 v[70:73], v[218:221], v[210:213], v[70:73]
	v_mfma_f32_16x16x32_bf16 v[66:69], v[226:229], v[210:213], v[66:69]
	v_mfma_f32_16x16x32_bf16 v[94:97], v[222:225], v[168:171], v[94:97]
	v_mfma_f32_16x16x32_bf16 v[90:93], v[244:247], v[168:171], v[90:93]
	v_mfma_f32_16x16x32_bf16 v[86:89], v[222:225], v[186:189], v[86:89]
	v_mfma_f32_16x16x32_bf16 v[82:85], v[244:247], v[186:189], v[82:85]
	v_mfma_f32_16x16x32_bf16 v[78:81], v[222:225], v[206:209], v[78:81]
	v_mfma_f32_16x16x32_bf16 v[74:77], v[244:247], v[206:209], v[74:77]
	v_mfma_f32_16x16x32_bf16 v[70:73], v[222:225], v[214:217], v[70:73]
	v_mfma_f32_16x16x32_bf16 v[66:69], v[244:247], v[214:217], v[66:69]
	s_barrier
; #define PG8_WAIT_V(n) asm volatile("s_waitcnt vmcnt(" #n ")" ::: "memory")
;     __device__ __forceinline__ void operator()(f32x4 (&acc)[2][2][4][2], const Unit& u, int wr, int wc, int fr, int fq) const {
;         const int row0 = u.pm * BM + wr * 64 + fr;
; #pragma unroll
;         for (int ai = 0; ai < 2; ++ai) {
;             f32x4 s0[4], s1[4]; float rstd[4];
; #pragma unroll
;             for (int m = 0; m < 4; ++m) { const float* sp = SSQ + (size_t)(row0 + ai * HALF + m * 16) * 16 + 8; s0[m] = *(const f32x4*)sp; s1[m] = *(const f32x4*)(sp + 4); }
; #pragma unroll
; template <class Epi, class Sched>
; __device__ __forceinline__ void gemm_phase(LAS unsigned char* lds, const Gemm g, const Sched& S, const Epi& E) {
;     ...
;         for (int t = 0; t < ntu; t += 2) {
;             const bool last = (t == ntu - 2);
;             const char* a1 = cA + (size_t)(t + 1) * kstep;
;             const char* a2 = last ? nA : cA + (size_t)(t + 2) * kstep; const char* b2 = last ? nB : cB + (size_t)(t + 2) * kstep;
;             const char* a3 = a2 + kstep; const char* b3 = b2 + kstep;
;             if (last && has_next) S.a_ready(nxt);
;             PG8_LDB(B0, 0, 0); PG8_SCHED; PG8_LDA(At, 0, 0); PG8_STAGE(PG8_SA(1, 1), a1 + hstepA, voffA);
;             PG8_WAIT_L(8); PG8_BAR; PG8_WAIT_L(0); PG8_MMA(0, 0, At, B0); PG8_BAR; PG8_SCHED;
;             PG8_LDB(B1, 0, 1); PG8_STAGE(PG8_SB(0, 0), b2, voffB);
;             PG8_BAR; PG8_WAIT_L(0); PG8_MMA(0, 1, At, B1); PG8_BAR;
;             PG8_LDA(At, 0, 1); PG8_STAGE(PG8_SA(0, 0), a2, voffA);
;             PG8_BAR; PG8_WAIT_L(0); PG8_MMA(1, 0, At, B0); PG8_BAR; PG8_SCHED;
;             PG8_STAGE(PG8_SB(0, 1), b2 + hstepB, voffB);
;             PG8_WAIT_V(6); PG8_BAR; PG8_MMA(1, 1, At, B1); PG8_BAR;
;             PG8_LDB(B0, 1, 0); PG8_SCHED; PG8_LDA(At, 1, 0); PG8_STAGE(PG8_SA(0, 1), a2 + hstepA, voffA);
;             PG8_WAIT_L(8); PG8_BAR; PG8_WAIT_L(0); PG8_MMA(0, 0, At, B0); PG8_BAR; PG8_SCHED;
;             PG8_LDB(B1, 1, 1); PG8_STAGE(PG8_SB(1, 0), b3, voffB);
;             PG8_BAR; PG8_WAIT_L(0); PG8_MMA(0, 1, At, B1); PG8_BAR;
;             PG8_LDA(At, 1, 1); PG8_STAGE(PG8_SA(1, 0), a3, voffA);
;             PG8_BAR; PG8_WAIT_L(0); PG8_MMA(1, 0, At, B0); PG8_BAR; PG8_SCHED;
;             PG8_STAGE(PG8_SB(1, 1), b3 + hstepB, voffB);
;             PG8_WAIT_V(6); PG8_BAR; PG8_MMA(1, 1, At, B1); PG8_BAR;
	ds_read_b128 v[164:167], v201 offset:49152
	ds_read_b128 v[168:171], v201 offset:50176
	ds_read_b128 v[172:175], v201 offset:51200
	ds_read_b128 v[186:189], v201 offset:52224
	ds_read_b128 v[202:205], v201 offset:53248
	ds_read_b128 v[206:209], v201 offset:54272
	ds_read_b128 v[210:213], v201 offset:55296
	ds_read_b128 v[214:217], v201 offset:56320
	s_add_i32 s56, s77, s33
	v_lshl_add_u64 v[176:177], v[176:177], 0, s[92:93]
	s_mov_b32 m0, s56
	s_nop 0
	global_load_lds_dwordx4 v[176:177], off
	v_lshl_add_u64 v[176:177], v[182:183], 0, s[92:93]
	s_add_i32 m0, s56, 0x2000
	s_nop 0
	global_load_lds_dwordx4 v[176:177], off
	s_add_u32 s56, s58, 0x20080
	s_addc_u32 s57, s59, 0
	s_add_i32 s58, s62, s33
	v_lshl_add_u64 v[238:239], s[56:57], 0, v[152:153]
	s_mov_b32 m0, s58
	s_nop 0
	global_load_lds_dwordx4 v[238:239], off
	v_lshl_add_u64 v[238:239], s[56:57], 0, v[148:149]
	s_add_i32 m0, s58, 0x2000
	s_nop 0
	global_load_lds_dwordx4 v[238:239], off
	s_waitcnt vmcnt(4)
	s_waitcnt lgkmcnt(0)
	s_barrier
	v_mfma_f32_16x16x32_bf16 v[62:65], v[130:133], v[164:167], v[62:65]
	v_mfma_f32_16x16x32_bf16 v[58:61], v[138:141], v[164:167], v[58:61]
	v_mfma_f32_16x16x32_bf16 v[54:57], v[130:133], v[172:175], v[54:57]
	v_mfma_f32_16x16x32_bf16 v[50:53], v[138:141], v[172:175], v[50:53]
	v_mfma_f32_16x16x32_bf16 v[46:49], v[130:133], v[202:205], v[46:49]
	v_mfma_f32_16x16x32_bf16 v[42:45], v[138:141], v[202:205], v[42:45]
	v_mfma_f32_16x16x32_bf16 v[38:41], v[130:133], v[210:213], v[38:41]
	v_mfma_f32_16x16x32_bf16 v[34:37], v[138:141], v[210:213], v[34:37]
	v_mfma_f32_16x16x32_bf16 v[62:65], v[134:137], v[168:171], v[62:65]
	v_mfma_f32_16x16x32_bf16 v[58:61], v[142:145], v[168:171], v[58:61]
	v_mfma_f32_16x16x32_bf16 v[54:57], v[134:137], v[186:189], v[54:57]
	v_mfma_f32_16x16x32_bf16 v[50:53], v[142:145], v[186:189], v[50:53]
	v_mfma_f32_16x16x32_bf16 v[46:49], v[134:137], v[206:209], v[46:49]
	v_mfma_f32_16x16x32_bf16 v[42:45], v[142:145], v[206:209], v[42:45]
	v_mfma_f32_16x16x32_bf16 v[38:41], v[134:137], v[214:217], v[38:41]
	v_mfma_f32_16x16x32_bf16 v[34:37], v[142:145], v[214:217], v[34:37]
	v_mfma_f32_16x16x32_bf16 v[30:33], v[218:221], v[164:167], v[30:33]
	v_mfma_f32_16x16x32_bf16 v[26:29], v[226:229], v[164:167], v[26:29]
	v_mfma_f32_16x16x32_bf16 v[22:25], v[218:221], v[172:175], v[22:25]
	v_mfma_f32_16x16x32_bf16 v[18:21], v[226:229], v[172:175], v[18:21]
	v_mfma_f32_16x16x32_bf16 v[14:17], v[218:221], v[202:205], v[14:17]
	v_mfma_f32_16x16x32_bf16 v[10:13], v[226:229], v[202:205], v[10:13]
	v_mfma_f32_16x16x32_bf16 v[6:9], v[218:221], v[210:213], v[6:9]
	v_mfma_f32_16x16x32_bf16 v[2:5], v[226:229], v[210:213], v[2:5]
	v_mfma_f32_16x16x32_bf16 v[30:33], v[222:225], v[168:171], v[30:33]
	v_mfma_f32_16x16x32_bf16 v[26:29], v[244:247], v[168:171], v[26:29]
	v_mfma_f32_16x16x32_bf16 v[22:25], v[222:225], v[186:189], v[22:25]
	v_mfma_f32_16x16x32_bf16 v[18:21], v[244:247], v[186:189], v[18:21]
	v_mfma_f32_16x16x32_bf16 v[14:17], v[222:225], v[206:209], v[14:17]
	v_mfma_f32_16x16x32_bf16 v[10:13], v[244:247], v[206:209], v[10:13]
	v_mfma_f32_16x16x32_bf16 v[6:9], v[222:225], v[214:217], v[6:9]
	v_mfma_f32_16x16x32_bf16 v[2:5], v[244:247], v[214:217], v[2:5]
	s_add_i32 s76, s76, 2
	s_add_u32 s30, s30, 0x100
	s_addc_u32 s51, s51, 0
	s_cmp_gt_u32 s76, 5
	s_mov_b64 s[56:57], s[6:7]
	s_barrier
	s_cbranch_scc0 .LBB0_571
	v_lshl_add_u32 v164, s72, 8, v196
	v_ashrrev_i32_e32 v165, 31, v164
	v_lshlrev_b64 v[130:131], 6, v[164:165]
	v_readlane_b32 s76, v255, 26
	s_cmp_gt_i32 s71, 5
	v_lshl_add_u64 v[172:173], s[26:27], 0, v[130:131]
	s_mov_b64 s[6:7], -1
	v_or_b32_e32 v168, 16, v164
	v_or_b32_e32 v166, 32, v164
	v_or_b32_e32 v170, 48, v164
	v_readlane_b32 s77, v255, 27
	s_cbranch_scc0 .LBB0_582
	v_ashrrev_i32_e32 v169, 31, v168
	v_lshlrev_b64 v[130:131], 6, v[168:169]
	v_lshl_add_u64 v[130:131], s[26:27], 0, v[130:131]
	global_load_dwordx4 v[174:177], v[172:173], off offset:48
	global_load_dwordx4 v[186:189], v[172:173], off offset:32
	global_load_dwordx4 v[202:205], v[130:131], off offset:48
	global_load_dwordx4 v[206:209], v[130:131], off offset:32
	v_ashrrev_i32_e32 v167, 31, v166
	v_lshlrev_b64 v[130:131], 6, v[166:167]
	v_lshl_add_u64 v[130:131], s[26:27], 0, v[130:131]
	v_ashrrev_i32_e32 v171, 31, v170
	global_load_dwordx4 v[134:137], v[130:131], off offset:48
	global_load_dwordx4 v[138:141], v[130:131], off offset:32
	v_lshlrev_b64 v[130:131], 6, v[170:171]
	v_lshl_add_u64 v[142:143], s[26:27], 0, v[130:131]
	global_load_dwordx4 v[130:133], v[142:143], off offset:48
	s_nop 0
	global_load_dwordx4 v[142:145], v[142:143], off offset:32
	s_mov_b32 s6, 0x3727c5ac
	s_add_i32 s28, s71, -6
	s_cmp_gt_u32 s28, 3
	s_cselect_b64 s[56:57], -1, 0
	s_cmp_lt_u32 s28, 4
	v_lshl_or_b32 v178, s28, 8, v158
	s_waitcnt vmcnt(0)
; __device__ __forceinline__ unsigned cvt_pk_bf16(float lo, float hi) { const f32x2_t v = {lo, hi}; return __builtin_bit_cast(unsigned, __builtin_convertvector(v, bf16x2_t)); }
;     __device__ __forceinline__ void operator()(f32x4 (&acc)[2][2][4][2], const Unit& u, int wr, int wc, int fr, int fq) const {
;     ...
;             for (int m = 0; m < 4; ++m) { const float* sp = SSQ + (size_t)(row0 + ai * HALF + m * 16) * 16 + 8; s0[m] = *(const f32x4*)sp; s1[m] = *(const f32x4*)(sp + 4); }
; #pragma unroll
;             for (int m = 0; m < 4; ++m) rstd[m] = rsqrtf(((s0[m][0] + s0[m][1]) + (s0[m][2] + s0[m][3]) + (s1[m][0] + s1[m][1]) + (s1[m][2] + s1[m][3])) * (1.0f / 512.0f) + EPS);
;             if (u.pn < 4) {
; #pragma unroll
;                 for (int m = 0; m < 4; ++m)
; #pragma unroll
;                     for (int bj = 0; bj < 2; ++bj) { const int c0 = u.pn * BM + bj * HALF + wc * 32 + 8 * fq; const f32x4 v0 = acc[ai][bj][m][0] * rstd[m], v1 = acc[ai][bj][m][1] * rstd[m];
;                         u32x4 w; w.x = cvt_pk_bf16(v0[0], v0[1]); w.y = cvt_pk_bf16(v0[2], v0[3]); w.z = cvt_pk_bf16(v1[0], v1[1]); w.w = cvt_pk_bf16(v1[2], v1[3]);
;                         *(u32x4*)(KM + (size_t)(row0 + ai * HALF + m * 16) * 1536 + (c0 >> 7) * 192 + (c0 & 127)) = w; }
;             } else {
; #pragma unroll
;                 for (int m = 0; m < 4; ++m)
; #pragma unroll
;                     for (int bj = 0; bj < 2; ++bj) { const int c0 = u.pn * BM + bj * HALF + wc * 32 + 8 * fq; const f32x4 v0 = acc[ai][bj][m][0] * rstd[m], v1 = acc[ai][bj][m][1] * rstd[m];
;                         u32x4 w; w.x = cvt_pk_bf16(v0[0], v0[1]); w.y = cvt_pk_bf16(v0[2], v0[3]); w.z = cvt_pk_bf16(v1[0], v1[1]); w.w = cvt_pk_bf16(v1[2], v1[3]);
;                         *(u32x4*)(VM + (size_t)(row0 + ai * HALF + m * 16) * 1024 + (c0 - 1024)) = w; }
	v_mov_b32_e32 v184, v176
	v_mov_b32_e32 v182, v187
	v_mov_b32_e32 v183, v188
	v_mov_b32_e32 v187, v189
	v_mov_b32_e32 v185, v174
	v_mov_b32_e32 v174, v177
	v_mov_b32_e32 v176, v207
	v_mov_b32_e32 v177, v208
	v_mov_b32_e32 v207, v209
	v_pk_add_f32 v[182:183], v[182:183], v[186:187]
	v_pk_add_f32 v[174:175], v[184:185], v[174:175]
	v_pk_add_f32 v[176:177], v[176:177], v[206:207]
	v_mov_b32_e32 v184, v204
	v_mov_b32_e32 v185, v202
	v_mov_b32_e32 v202, v205
	v_pk_add_f32 v[184:185], v[184:185], v[202:203]
	v_mov_b32_e32 v186, v176
	v_mov_b32_e32 v187, v182
	v_mov_b32_e32 v182, v177
	v_pk_add_f32 v[176:177], v[186:187], v[182:183]
	v_mov_b32_e32 v182, v185
	v_mov_b32_e32 v183, v175
	v_pk_add_f32 v[176:177], v[176:177], v[182:183]
	v_mov_b32_e32 v185, v174
	v_pk_add_f32 v[174:175], v[184:185], v[176:177]
	v_mov_b64_e32 v[186:187], s[6:7]
	v_pk_fma_f32 v[176:177], v[174:175], s[42:43], v[186:187] op_sel_hi:[1,0,0]
	v_mov_b32_e32 v182, v139
	v_mul_f32_e32 v174, 0x4b800000, v177
	v_cmp_gt_f32_e64 s[6:7], s85, v177
	v_mov_b32_e32 v183, v140
	v_mov_b32_e32 v139, v141
	v_mov_b32_e32 v140, v136
	v_mov_b32_e32 v141, v134
	v_mov_b32_e32 v134, v137
	v_mov_b32_e32 v136, v143
	v_mov_b32_e32 v137, v144
	v_mov_b32_e32 v143, v145
	v_cndmask_b32_e64 v174, v177, v174, s[6:7]
	v_pk_add_f32 v[138:139], v[182:183], v[138:139]
	v_pk_add_f32 v[134:135], v[140:141], v[134:135]
	v_pk_add_f32 v[136:137], v[136:137], v[142:143]
	v_mov_b32_e32 v140, v132
	v_mov_b32_e32 v141, v130
	v_mov_b32_e32 v130, v133
	v_rsq_f32_e32 v174, v174
	v_pk_add_f32 v[130:131], v[140:141], v[130:131]
	v_mov_b32_e32 v132, v136
	v_mov_b32_e32 v133, v138
	v_mov_b32_e32 v138, v137
	v_pk_add_f32 v[132:133], v[132:133], v[138:139]
	v_mov_b32_e32 v136, v131
	v_mov_b32_e32 v137, v135
	v_pk_add_f32 v[132:133], v[132:133], v[136:137]
	v_mov_b32_e32 v131, v134
	v_pk_add_f32 v[130:131], v[130:131], v[132:133]
	v_mul_f32_e32 v175, 0x45800000, v174
	v_pk_fma_f32 v[130:131], v[130:131], s[42:43], v[186:187] op_sel_hi:[1,0,0]
	v_cmp_gt_f32_e32 vcc, s85, v176
	v_cndmask_b32_e64 v174, v174, v175, s[6:7]
	v_mul_f32_e32 v175, 0x4b800000, v176
	v_mul_f32_e32 v132, 0x4b800000, v131
	v_cmp_gt_f32_e64 s[6:7], s85, v131
	v_cndmask_b32_e32 v175, v176, v175, vcc
	v_rsq_f32_e32 v175, v175
	v_cndmask_b32_e64 v131, v131, v132, s[6:7]
	v_rsq_f32_e32 v131, v131
	v_mul_f32_e32 v176, 0x45800000, v175
	v_cndmask_b32_e32 v176, v175, v176, vcc
	v_mul_f32_e32 v132, 0x45800000, v131
	v_cmp_gt_f32_e32 vcc, s85, v130
	v_cndmask_b32_e64 v138, v131, v132, s[6:7]
	v_mul_f32_e32 v131, 0x4b800000, v130
	v_cndmask_b32_e32 v130, v130, v131, vcc
	v_rsq_f32_e32 v130, v130
	v_pk_mul_f32 v[132:133], v[128:129], v[174:175] op_sel_hi:[1,0]
	v_pk_mul_f32 v[134:135], v[124:125], v[174:175] op_sel_hi:[1,0]
	v_pk_mul_f32 v[136:137], v[122:123], v[174:175] op_sel_hi:[1,0]
	v_mul_f32_e32 v131, 0x45800000, v130
	v_cndmask_b32_e32 v140, v130, v131, vcc
	v_pk_mul_f32 v[130:131], v[126:127], v[174:175] op_sel_hi:[1,0]
	v_pk_mul_f32 v[142:143], v[92:93], v[174:175] op_sel_hi:[1,0]
	v_cvt_pk_bf16_f32 v130, v130, v131
	v_cvt_pk_bf16_f32 v131, v132, v133
	v_cvt_pk_bf16_f32 v132, v136, v137
	v_cvt_pk_bf16_f32 v133, v134, v135
	v_pk_mul_f32 v[136:137], v[96:97], v[174:175] op_sel_hi:[1,0]
	v_pk_mul_f32 v[134:135], v[94:95], v[174:175] op_sel_hi:[1,0]
	v_pk_mul_f32 v[144:145], v[90:91], v[174:175] op_sel_hi:[1,0]
	v_cvt_pk_bf16_f32 v134, v134, v135
	v_cvt_pk_bf16_f32 v135, v136, v137
	v_cvt_pk_bf16_f32 v136, v144, v145
	v_cvt_pk_bf16_f32 v137, v142, v143
	s_mov_b64 s[6:7], -1
	s_cbranch_scc1 .LBB0_575
; __device__ __forceinline__ unsigned cvt_pk_bf16(float lo, float hi) { const f32x2_t v = {lo, hi}; return __builtin_bit_cast(unsigned, __builtin_convertvector(v, bf16x2_t)); }
;     __device__ __forceinline__ void operator()(f32x4 (&acc)[2][2][4][2], const Unit& u, int wr, int wc, int fr, int fq) const {
;     ...
;             } else {
; #pragma unroll
;                 for (int m = 0; m < 4; ++m)
; #pragma unroll
;                     for (int bj = 0; bj < 2; ++bj) { const int c0 = u.pn * BM + bj * HALF + wc * 32 + 8 * fq; const f32x4 v0 = acc[ai][bj][m][0] * rstd[m], v1 = acc[ai][bj][m][1] * rstd[m];
;                         u32x4 w; w.x = cvt_pk_bf16(v0[0], v0[1]); w.y = cvt_pk_bf16(v0[2], v0[3]); w.z = cvt_pk_bf16(v1[0], v1[1]); w.w = cvt_pk_bf16(v1[2], v1[3]);
;                         *(u32x4*)(VM + (size_t)(row0 + ai * HALF + m * 16) * 1024 + (c0 - 1024)) = w; }
;             }
	v_lshlrev_b64 v[142:143], 11, v[164:165]
	v_lshl_add_u64 v[142:143], s[24:25], 0, v[142:143]
	v_lshlrev_b64 v[174:175], 1, v[178:179]
	v_lshl_add_u64 v[142:143], v[142:143], 0, v[174:175]
	v_lshlrev_b64 v[182:183], 11, v[168:169]
	global_store_dwordx4 v[142:143], v[130:133], off offset:-2048
	global_store_dwordx4 v[142:143], v[134:137], off offset:-1792
	v_pk_mul_f32 v[144:145], v[120:121], v[176:177] op_sel_hi:[1,0]
	v_pk_mul_f32 v[142:143], v[118:119], v[176:177] op_sel_hi:[1,0]
	v_pk_mul_f32 v[184:185], v[116:117], v[176:177] op_sel_hi:[1,0]
	v_pk_mul_f32 v[186:187], v[114:115], v[176:177] op_sel_hi:[1,0]
	v_lshl_add_u64 v[182:183], s[24:25], 0, v[182:183]
	v_cvt_pk_bf16_f32 v142, v142, v143
	v_cvt_pk_bf16_f32 v143, v144, v145
	v_cvt_pk_bf16_f32 v144, v186, v187
	v_cvt_pk_bf16_f32 v145, v184, v185
	v_lshl_add_u64 v[182:183], v[182:183], 0, v[174:175]
	global_store_dwordx4 v[182:183], v[142:145], off offset:-2048
	v_pk_mul_f32 v[184:185], v[84:85], v[176:177] op_sel_hi:[1,0]
	v_pk_mul_f32 v[186:187], v[82:83], v[176:177] op_sel_hi:[1,0]
	v_pk_mul_f32 v[144:145], v[88:89], v[176:177] op_sel_hi:[1,0]
	v_pk_mul_f32 v[142:143], v[86:87], v[176:177] op_sel_hi:[1,0]
	s_mov_b64 s[6:7], 0
	v_cvt_pk_bf16_f32 v142, v142, v143
	v_cvt_pk_bf16_f32 v143, v144, v145
	v_cvt_pk_bf16_f32 v144, v186, v187
	v_cvt_pk_bf16_f32 v145, v184, v185
	global_store_dwordx4 v[182:183], v[142:145], off offset:-1792
	v_lshlrev_b64 v[182:183], 11, v[166:167]
	v_pk_mul_f32 v[184:185], v[108:109], v[138:139] op_sel_hi:[1,0]
	v_pk_mul_f32 v[144:145], v[112:113], v[138:139] op_sel_hi:[1,0]
	v_pk_mul_f32 v[142:143], v[110:111], v[138:139] op_sel_hi:[1,0]
	v_pk_mul_f32 v[186:187], v[106:107], v[138:139] op_sel_hi:[1,0]
	v_lshl_add_u64 v[182:183], s[24:25], 0, v[182:183]
	v_cvt_pk_bf16_f32 v142, v142, v143
	v_cvt_pk_bf16_f32 v143, v144, v145
	v_cvt_pk_bf16_f32 v144, v186, v187
	v_cvt_pk_bf16_f32 v145, v184, v185
	v_lshl_add_u64 v[182:183], v[182:183], 0, v[174:175]
	global_store_dwordx4 v[182:183], v[142:145], off offset:-2048
	v_pk_mul_f32 v[184:185], v[76:77], v[138:139] op_sel_hi:[1,0]
	v_pk_mul_f32 v[186:187], v[74:75], v[138:139] op_sel_hi:[1,0]
	v_pk_mul_f32 v[144:145], v[80:81], v[138:139] op_sel_hi:[1,0]
	v_pk_mul_f32 v[142:143], v[78:79], v[138:139] op_sel_hi:[1,0]
	s_nop 0
	v_cvt_pk_bf16_f32 v142, v142, v143
	v_cvt_pk_bf16_f32 v143, v144, v145
	v_cvt_pk_bf16_f32 v144, v186, v187
	v_cvt_pk_bf16_f32 v145, v184, v185
	global_store_dwordx4 v[182:183], v[142:145], off offset:-1792
	v_lshlrev_b64 v[182:183], 11, v[170:171]
	v_pk_mul_f32 v[184:185], v[100:101], v[140:141] op_sel_hi:[1,0]
	v_pk_mul_f32 v[144:145], v[104:105], v[140:141] op_sel_hi:[1,0]
	v_pk_mul_f32 v[142:143], v[102:103], v[140:141] op_sel_hi:[1,0]
	v_pk_mul_f32 v[186:187], v[98:99], v[140:141] op_sel_hi:[1,0]
	v_lshl_add_u64 v[182:183], s[24:25], 0, v[182:183]
	v_cvt_pk_bf16_f32 v142, v142, v143
	v_cvt_pk_bf16_f32 v143, v144, v145
	v_cvt_pk_bf16_f32 v144, v186, v187
	v_cvt_pk_bf16_f32 v145, v184, v185
	v_lshl_add_u64 v[174:175], v[182:183], 0, v[174:175]
	global_store_dwordx4 v[174:175], v[142:145], off offset:-2048
	v_pk_mul_f32 v[182:183], v[68:69], v[140:141] op_sel_hi:[1,0]
	v_pk_mul_f32 v[184:185], v[66:67], v[140:141] op_sel_hi:[1,0]
	v_pk_mul_f32 v[144:145], v[72:73], v[140:141] op_sel_hi:[1,0]
	v_pk_mul_f32 v[142:143], v[70:71], v[140:141] op_sel_hi:[1,0]
	s_nop 0
	v_cvt_pk_bf16_f32 v142, v142, v143
	v_cvt_pk_bf16_f32 v143, v144, v145
	v_cvt_pk_bf16_f32 v144, v184, v185
	v_cvt_pk_bf16_f32 v145, v182, v183
	global_store_dwordx4 v[174:175], v[142:145], off offset:-1792

; #define PG8_STAGE(bufoff, gbase, voff) do { _Pragma("unroll") for (int _i = 0; _i < 2; ++_i) \
;         __builtin_amdgcn_global_load_lds((const unsigned*)((const char*)(gbase) + (voff)[_i]), (LAS unsigned*)(lds + (bufoff) + ldsw + _i * 8192), 16, 0, 0); } while (0)
; #define PG8_LDA(dst, b, h) do { _Pragma("unroll") for (int m = 0; m < 4; ++m) _Pragma("unroll") for (int k = 0; k < 2; ++k) dst[m][k] = *(const LAS bf16x8*)(lds + PG8_SA(b, h) + aoff + m * 2048 + k * 1024); } while (0)
; #define PG8_WAIT_V(n) asm volatile("s_waitcnt vmcnt(" #n ")" ::: "memory")
; template <class Epi, class Sched>
; __device__ __forceinline__ void gemm_phase(LAS unsigned char* lds, const Gemm g, const Sched& S, const Epi& E) {
;     ...
;         for (int t = 0; t < ntu; t += 2) {
;             const bool last = (t == ntu - 2);
;             const char* a1 = cA + (size_t)(t + 1) * kstep;
;             const char* a2 = last ? nA : cA + (size_t)(t + 2) * kstep; const char* b2 = last ? nB : cB + (size_t)(t + 2) * kstep;
;             const char* a3 = a2 + kstep; const char* b3 = b2 + kstep;
;             if (last && has_next) S.a_ready(nxt);
;             PG8_LDB(B0, 0, 0); PG8_SCHED; PG8_LDA(At, 0, 0); PG8_STAGE(PG8_SA(1, 1), a1 + hstepA, voffA);
;             PG8_WAIT_L(8); PG8_BAR; PG8_WAIT_L(0); PG8_MMA(0, 0, At, B0); PG8_BAR; PG8_SCHED;
;             PG8_LDB(B1, 0, 1); PG8_STAGE(PG8_SB(0, 0), b2, voffB);
;             PG8_BAR; PG8_WAIT_L(0); PG8_MMA(0, 1, At, B1); PG8_BAR;
;             PG8_LDA(At, 0, 1); PG8_STAGE(PG8_SA(0, 0), a2, voffA);
;             PG8_BAR; PG8_WAIT_L(0); PG8_MMA(1, 0, At, B0); PG8_BAR; PG8_SCHED;
;             PG8_STAGE(PG8_SB(0, 1), b2 + hstepB, voffB);
;             PG8_WAIT_V(6); PG8_BAR; PG8_MMA(1, 1, At, B1); PG8_BAR;
;             PG8_LDB(B0, 1, 0); PG8_SCHED; PG8_LDA(At, 1, 0); PG8_STAGE(PG8_SA(0, 1), a2 + hstepA, voffA);
;             PG8_WAIT_L(8); PG8_BAR; PG8_WAIT_L(0); PG8_MMA(0, 0, At, B0); PG8_BAR; PG8_SCHED;
;             PG8_LDB(B1, 1, 1); PG8_STAGE(PG8_SB(1, 0), b3, voffB);
;             PG8_BAR; PG8_WAIT_L(0); PG8_MMA(0, 1, At, B1); PG8_BAR;
;             PG8_LDA(At, 1, 1); PG8_STAGE(PG8_SA(1, 0), a3, voffA);
;             PG8_BAR; PG8_WAIT_L(0); PG8_MMA(1, 0, At, B0); PG8_BAR; PG8_SCHED;
;             PG8_STAGE(PG8_SB(1, 1), b3 + hstepB, voffB);
;             PG8_WAIT_V(6); PG8_BAR; PG8_MMA(1, 1, At, B1); PG8_BAR;
.LBB0_871:
	s_add_i32 s63, s28, 2
	s_add_u32 s6, s68, 0xfffc0080
	s_addc_u32 s7, s69, -1
	s_add_i32 s35, 0, 0x10000
	v_add_u32_e32 v1, s35, v207
	ds_read_b128 v[130:133], v1
	ds_read_b128 v[134:137], v1 offset:1024
	ds_read_b128 v[138:141], v1 offset:2048
	ds_read_b128 v[142:145], v1 offset:3072
	s_cmp_eq_u32 s23, s28
	s_cselect_b32 s28, s24, s6
	s_cselect_b32 s29, s25, s7
	s_cselect_b32 s27, s13, s59
	s_cselect_b32 s26, s21, s55
	ds_read_b128 v[146:149], v209
	ds_read_b128 v[150:153], v209 offset:1024
	ds_read_b128 v[154:157], v209 offset:2048
	ds_read_b128 v[158:161], v209 offset:3072
	ds_read_b128 v[162:165], v209 offset:4096
	ds_read_b128 v[182:185], v209 offset:5120
	ds_read_b128 v[192:195], v209 offset:6144
	ds_read_b128 v[196:199], v209 offset:7168
	s_mov_b32 s98, 0xfffc0000
	s_mov_b32 s99, -1
	v_lshl_add_u64 v[232:233], s[68:69], 0, v[188:189]
	v_lshl_add_u64 v[232:233], v[232:233], 0, s[98:99]
	s_mov_b32 m0, s76
	s_nop 0
	global_load_lds_dwordx4 v[232:233], off
	v_lshl_add_u64 v[232:233], s[68:69], 0, v[190:191]
	v_lshl_add_u64 v[232:233], v[232:233], 0, s[98:99]
	s_mov_b32 m0, s77
	s_nop 0
	global_load_lds_dwordx4 v[232:233], off
	v_lshl_add_u64 v[232:233], s[68:69], 0, v[188:189]
	s_add_i32 m0, s79, 0xc000
	s_nop 0
	global_load_lds_dwordx4 v[232:233], off
	v_lshl_add_u64 v[232:233], s[68:69], 0, v[190:191]
	s_add_i32 m0, s79, 0xe000
	s_nop 0
	global_load_lds_dwordx4 v[232:233], off
	s_add_i32 s37, 0, 0x14000
	v_add_u32_e32 v1, s37, v207
	ds_read_b128 v[200:203], v1
	ds_read_b128 v[210:213], v1 offset:1024
	ds_read_b128 v[214:217], v1 offset:2048
	ds_read_b128 v[218:221], v1 offset:3072
	s_waitcnt lgkmcnt(0)
	s_barrier
	v_mfma_f32_16x16x32_bf16 v[126:129], v[130:133], v[146:149], v[126:129]
	v_mfma_f32_16x16x32_bf16 v[122:125], v[138:141], v[146:149], v[122:125]
	v_mfma_f32_16x16x32_bf16 v[118:121], v[130:133], v[154:157], v[118:121]
	v_mfma_f32_16x16x32_bf16 v[114:117], v[138:141], v[154:157], v[114:117]
	v_mfma_f32_16x16x32_bf16 v[110:113], v[130:133], v[162:165], v[110:113]
	v_mfma_f32_16x16x32_bf16 v[106:109], v[138:141], v[162:165], v[106:109]
	v_mfma_f32_16x16x32_bf16 v[102:105], v[130:133], v[192:195], v[102:105]
	v_mfma_f32_16x16x32_bf16 v[98:101], v[138:141], v[192:195], v[98:101]
	v_mfma_f32_16x16x32_bf16 v[126:129], v[134:137], v[150:153], v[126:129]
	v_mfma_f32_16x16x32_bf16 v[122:125], v[142:145], v[150:153], v[122:125]
	v_mfma_f32_16x16x32_bf16 v[118:121], v[134:137], v[158:161], v[118:121]
	v_mfma_f32_16x16x32_bf16 v[114:117], v[142:145], v[158:161], v[114:117]
	v_mfma_f32_16x16x32_bf16 v[110:113], v[134:137], v[182:185], v[110:113]
	v_mfma_f32_16x16x32_bf16 v[106:109], v[142:145], v[182:185], v[106:109]
	v_mfma_f32_16x16x32_bf16 v[102:105], v[134:137], v[196:199], v[102:105]
	v_mfma_f32_16x16x32_bf16 v[98:101], v[142:145], v[196:199], v[98:101]
	v_mfma_f32_16x16x32_bf16 v[94:97], v[200:203], v[146:149], v[94:97]
	v_mfma_f32_16x16x32_bf16 v[90:93], v[214:217], v[146:149], v[90:93]
	v_mfma_f32_16x16x32_bf16 v[86:89], v[200:203], v[154:157], v[86:89]
	v_mfma_f32_16x16x32_bf16 v[82:85], v[214:217], v[154:157], v[82:85]
	v_mfma_f32_16x16x32_bf16 v[78:81], v[200:203], v[162:165], v[78:81]
	v_mfma_f32_16x16x32_bf16 v[74:77], v[214:217], v[162:165], v[74:77]
	v_mfma_f32_16x16x32_bf16 v[70:73], v[200:203], v[192:195], v[70:73]
	v_mfma_f32_16x16x32_bf16 v[66:69], v[214:217], v[192:195], v[66:69]
	v_mfma_f32_16x16x32_bf16 v[94:97], v[210:213], v[150:153], v[94:97]
	v_mfma_f32_16x16x32_bf16 v[90:93], v[218:221], v[150:153], v[90:93]
	v_mfma_f32_16x16x32_bf16 v[86:89], v[210:213], v[158:161], v[86:89]
	v_mfma_f32_16x16x32_bf16 v[82:85], v[218:221], v[158:161], v[82:85]
	v_mfma_f32_16x16x32_bf16 v[78:81], v[210:213], v[182:185], v[78:81]
	v_mfma_f32_16x16x32_bf16 v[74:77], v[218:221], v[182:185], v[74:77]
	v_mfma_f32_16x16x32_bf16 v[70:73], v[210:213], v[196:199], v[70:73]
	v_mfma_f32_16x16x32_bf16 v[66:69], v[218:221], v[196:199], v[66:69]
	s_barrier
	ds_read_b128 v[146:149], v209 offset:16384
	ds_read_b128 v[150:153], v209 offset:17408
	ds_read_b128 v[154:157], v209 offset:18432
	ds_read_b128 v[158:161], v209 offset:19456
	ds_read_b128 v[162:165], v209 offset:20480
	ds_read_b128 v[182:185], v209 offset:21504
	ds_read_b128 v[192:195], v209 offset:22528
	ds_read_b128 v[196:199], v209 offset:23552
	s_add_i32 s6, s35, s89
	v_lshl_add_u64 v[204:205], s[26:27], 0, v[178:179]
	s_mov_b32 m0, s6
	s_nop 0
	global_load_lds_dwordx4 v[204:205], off
	v_lshl_add_u64 v[222:223], s[26:27], 0, v[172:173]
	s_add_i32 m0, s6, 0x2000
	s_nop 0
	global_load_lds_dwordx4 v[222:223], off
	s_add_u32 s6, s26, 0x40000
	s_addc_u32 s7, s27, 0
	s_add_i32 s35, s37, s89
	v_lshl_add_u64 v[234:235], s[6:7], 0, v[178:179]
	s_mov_b32 m0, s35
	s_nop 0
	global_load_lds_dwordx4 v[234:235], off
	v_lshl_add_u64 v[234:235], s[6:7], 0, v[172:173]
	s_add_i32 m0, s35, 0x2000
	s_nop 0
	global_load_lds_dwordx4 v[234:235], off
	s_waitcnt vmcnt(4)
	s_waitcnt lgkmcnt(0)
	s_barrier
; #define PG8_STAGE(bufoff, gbase, voff) do { _Pragma("unroll") for (int _i = 0; _i < 2; ++_i) \
;         __builtin_amdgcn_global_load_lds((const unsigned*)((const char*)(gbase) + (voff)[_i]), (LAS unsigned*)(lds + (bufoff) + ldsw + _i * 8192), 16, 0, 0); } while (0)
; #define PG8_LDA(dst, b, h) do { _Pragma("unroll") for (int m = 0; m < 4; ++m) _Pragma("unroll") for (int k = 0; k < 2; ++k) dst[m][k] = *(const LAS bf16x8*)(lds + PG8_SA(b, h) + aoff + m * 2048 + k * 1024); } while (0)
; #define PG8_WAIT_V(n) asm volatile("s_waitcnt vmcnt(" #n ")" ::: "memory")
; template <class Epi, class Sched>
; __device__ __forceinline__ void gemm_phase(LAS unsigned char* lds, const Gemm g, const Sched& S, const Epi& E) {
;     ...
;         for (int t = 0; t < ntu; t += 2) {
;             const bool last = (t == ntu - 2);
;             const char* a1 = cA + (size_t)(t + 1) * kstep;
;             const char* a2 = last ? nA : cA + (size_t)(t + 2) * kstep; const char* b2 = last ? nB : cB + (size_t)(t + 2) * kstep;
;             const char* a3 = a2 + kstep; const char* b3 = b2 + kstep;
;             if (last && has_next) S.a_ready(nxt);
;             PG8_LDB(B0, 0, 0); PG8_SCHED; PG8_LDA(At, 0, 0); PG8_STAGE(PG8_SA(1, 1), a1 + hstepA, voffA);
;             PG8_WAIT_L(8); PG8_BAR; PG8_WAIT_L(0); PG8_MMA(0, 0, At, B0); PG8_BAR; PG8_SCHED;
;             PG8_LDB(B1, 0, 1); PG8_STAGE(PG8_SB(0, 0), b2, voffB);
;             PG8_BAR; PG8_WAIT_L(0); PG8_MMA(0, 1, At, B1); PG8_BAR;
;             PG8_LDA(At, 0, 1); PG8_STAGE(PG8_SA(0, 0), a2, voffA);
;             PG8_BAR; PG8_WAIT_L(0); PG8_MMA(1, 0, At, B0); PG8_BAR; PG8_SCHED;
;             PG8_STAGE(PG8_SB(0, 1), b2 + hstepB, voffB);
;             PG8_WAIT_V(6); PG8_BAR; PG8_MMA(1, 1, At, B1); PG8_BAR;
;             PG8_LDB(B0, 1, 0); PG8_SCHED; PG8_LDA(At, 1, 0); PG8_STAGE(PG8_SA(0, 1), a2 + hstepA, voffA);
;             PG8_WAIT_L(8); PG8_BAR; PG8_WAIT_L(0); PG8_MMA(0, 0, At, B0); PG8_BAR; PG8_SCHED;
;             PG8_LDB(B1, 1, 1); PG8_STAGE(PG8_SB(1, 0), b3, voffB);
;             PG8_BAR; PG8_WAIT_L(0); PG8_MMA(0, 1, At, B1); PG8_BAR;
;             PG8_LDA(At, 1, 1); PG8_STAGE(PG8_SA(1, 0), a3, voffA);
;             PG8_BAR; PG8_WAIT_L(0); PG8_MMA(1, 0, At, B0); PG8_BAR; PG8_SCHED;
;             PG8_STAGE(PG8_SB(1, 1), b3 + hstepB, voffB);
;             PG8_WAIT_V(6); PG8_BAR; PG8_MMA(1, 1, At, B1); PG8_BAR;
	v_mfma_f32_16x16x32_bf16 v[62:65], v[130:133], v[146:149], v[62:65]
	v_mfma_f32_16x16x32_bf16 v[58:61], v[138:141], v[146:149], v[58:61]
	v_mfma_f32_16x16x32_bf16 v[54:57], v[130:133], v[154:157], v[54:57]
	v_mfma_f32_16x16x32_bf16 v[50:53], v[138:141], v[154:157], v[50:53]
	v_mfma_f32_16x16x32_bf16 v[46:49], v[130:133], v[162:165], v[46:49]
	v_mfma_f32_16x16x32_bf16 v[42:45], v[138:141], v[162:165], v[42:45]
	v_mfma_f32_16x16x32_bf16 v[38:41], v[130:133], v[192:195], v[38:41]
	v_mfma_f32_16x16x32_bf16 v[34:37], v[138:141], v[192:195], v[34:37]
	v_mfma_f32_16x16x32_bf16 v[62:65], v[134:137], v[150:153], v[62:65]
	v_mfma_f32_16x16x32_bf16 v[58:61], v[142:145], v[150:153], v[58:61]
	v_mfma_f32_16x16x32_bf16 v[54:57], v[134:137], v[158:161], v[54:57]
	v_mfma_f32_16x16x32_bf16 v[50:53], v[142:145], v[158:161], v[50:53]
	v_mfma_f32_16x16x32_bf16 v[46:49], v[134:137], v[182:185], v[46:49]
	v_mfma_f32_16x16x32_bf16 v[42:45], v[142:145], v[182:185], v[42:45]
	v_mfma_f32_16x16x32_bf16 v[38:41], v[134:137], v[196:199], v[38:41]
	v_mfma_f32_16x16x32_bf16 v[34:37], v[142:145], v[196:199], v[34:37]
	v_mfma_f32_16x16x32_bf16 v[30:33], v[200:203], v[146:149], v[30:33]
	v_mfma_f32_16x16x32_bf16 v[26:29], v[214:217], v[146:149], v[26:29]
	v_mfma_f32_16x16x32_bf16 v[22:25], v[200:203], v[154:157], v[22:25]
	v_mfma_f32_16x16x32_bf16 v[18:21], v[214:217], v[154:157], v[18:21]
	v_mfma_f32_16x16x32_bf16 v[14:17], v[200:203], v[162:165], v[14:17]
	v_mfma_f32_16x16x32_bf16 v[10:13], v[214:217], v[162:165], v[10:13]
	v_mfma_f32_16x16x32_bf16 v[6:9], v[200:203], v[192:195], v[6:9]
	v_mfma_f32_16x16x32_bf16 v[2:5], v[214:217], v[192:195], v[2:5]
	v_mfma_f32_16x16x32_bf16 v[30:33], v[210:213], v[150:153], v[30:33]
	v_mfma_f32_16x16x32_bf16 v[26:29], v[218:221], v[150:153], v[26:29]
	v_mfma_f32_16x16x32_bf16 v[22:25], v[210:213], v[158:161], v[22:25]
	v_mfma_f32_16x16x32_bf16 v[18:21], v[218:221], v[158:161], v[18:21]
	v_mfma_f32_16x16x32_bf16 v[14:17], v[210:213], v[182:185], v[14:17]
	v_mfma_f32_16x16x32_bf16 v[10:13], v[218:221], v[182:185], v[10:13]
	v_mfma_f32_16x16x32_bf16 v[6:9], v[210:213], v[196:199], v[6:9]
	v_mfma_f32_16x16x32_bf16 v[2:5], v[218:221], v[196:199], v[2:5]
	s_add_i32 s35, 0, 0x18000
	v_add_u32_e32 v1, s35, v207
	s_barrier
	ds_read_b128 v[130:133], v1
	ds_read_b128 v[134:137], v1 offset:1024
	ds_read_b128 v[138:141], v1 offset:2048
	ds_read_b128 v[142:145], v1 offset:3072
	ds_read_b128 v[146:149], v209 offset:32768
	ds_read_b128 v[150:153], v209 offset:33792
	ds_read_b128 v[154:157], v209 offset:34816
	ds_read_b128 v[158:161], v209 offset:35840
	ds_read_b128 v[162:165], v209 offset:36864
	ds_read_b128 v[182:185], v209 offset:37888
	ds_read_b128 v[192:195], v209 offset:38912
	ds_read_b128 v[196:199], v209 offset:39936
	s_mov_b32 m0, s79
	v_lshl_add_u64 v[224:225], s[28:29], 0, v[168:169]
	global_load_lds_dwordx4 v[224:225], off
	v_lshl_add_u64 v[226:227], s[28:29], 0, v[170:171]
	s_mov_b32 m0, s46
	s_nop 0
	global_load_lds_dwordx4 v[226:227], off
	s_add_u32 s6, s28, 0x40000
	s_addc_u32 s7, s29, 0
	s_mov_b32 m0, s33
	v_lshl_add_u64 v[236:237], s[6:7], 0, v[168:169]
	global_load_lds_dwordx4 v[236:237], off
	v_lshl_add_u64 v[236:237], s[6:7], 0, v[170:171]
	s_mov_b32 m0, s83
	s_nop 0
	global_load_lds_dwordx4 v[236:237], off
	s_add_i32 s28, 0, 0x1c000
	v_add_u32_e32 v1, s28, v207
	ds_read_b128 v[200:203], v1
	ds_read_b128 v[210:213], v1 offset:1024
	ds_read_b128 v[214:217], v1 offset:2048
	ds_read_b128 v[218:221], v1 offset:3072
	s_waitcnt lgkmcnt(0)
	s_barrier
	v_mfma_f32_16x16x32_bf16 v[126:129], v[130:133], v[146:149], v[126:129]
	v_mfma_f32_16x16x32_bf16 v[122:125], v[138:141], v[146:149], v[122:125]
	v_mfma_f32_16x16x32_bf16 v[118:121], v[130:133], v[154:157], v[118:121]
	v_mfma_f32_16x16x32_bf16 v[114:117], v[138:141], v[154:157], v[114:117]
	v_mfma_f32_16x16x32_bf16 v[110:113], v[130:133], v[162:165], v[110:113]
	v_mfma_f32_16x16x32_bf16 v[106:109], v[138:141], v[162:165], v[106:109]
	v_mfma_f32_16x16x32_bf16 v[102:105], v[130:133], v[192:195], v[102:105]
	v_mfma_f32_16x16x32_bf16 v[98:101], v[138:141], v[192:195], v[98:101]
	v_mfma_f32_16x16x32_bf16 v[126:129], v[134:137], v[150:153], v[126:129]
	v_mfma_f32_16x16x32_bf16 v[122:125], v[142:145], v[150:153], v[122:125]
	v_mfma_f32_16x16x32_bf16 v[118:121], v[134:137], v[158:161], v[118:121]
	v_mfma_f32_16x16x32_bf16 v[114:117], v[142:145], v[158:161], v[114:117]
	v_mfma_f32_16x16x32_bf16 v[110:113], v[134:137], v[182:185], v[110:113]
	v_mfma_f32_16x16x32_bf16 v[106:109], v[142:145], v[182:185], v[106:109]
	v_mfma_f32_16x16x32_bf16 v[102:105], v[134:137], v[196:199], v[102:105]
	v_mfma_f32_16x16x32_bf16 v[98:101], v[142:145], v[196:199], v[98:101]
	v_mfma_f32_16x16x32_bf16 v[94:97], v[200:203], v[146:149], v[94:97]
	v_mfma_f32_16x16x32_bf16 v[90:93], v[214:217], v[146:149], v[90:93]
	v_mfma_f32_16x16x32_bf16 v[86:89], v[200:203], v[154:157], v[86:89]
	v_mfma_f32_16x16x32_bf16 v[82:85], v[214:217], v[154:157], v[82:85]
	v_mfma_f32_16x16x32_bf16 v[78:81], v[200:203], v[162:165], v[78:81]
	v_mfma_f32_16x16x32_bf16 v[74:77], v[214:217], v[162:165], v[74:77]
	v_mfma_f32_16x16x32_bf16 v[70:73], v[200:203], v[192:195], v[70:73]
	v_mfma_f32_16x16x32_bf16 v[66:69], v[214:217], v[192:195], v[66:69]
	v_mfma_f32_16x16x32_bf16 v[94:97], v[210:213], v[150:153], v[94:97]
	v_mfma_f32_16x16x32_bf16 v[90:93], v[218:221], v[150:153], v[90:93]
	v_mfma_f32_16x16x32_bf16 v[86:89], v[210:213], v[158:161], v[86:89]
	v_mfma_f32_16x16x32_bf16 v[82:85], v[218:221], v[158:161], v[82:85]
	v_mfma_f32_16x16x32_bf16 v[78:81], v[210:213], v[182:185], v[78:81]
	v_mfma_f32_16x16x32_bf16 v[74:77], v[218:221], v[182:185], v[74:77]
	v_mfma_f32_16x16x32_bf16 v[70:73], v[210:213], v[196:199], v[70:73]
	v_mfma_f32_16x16x32_bf16 v[66:69], v[218:221], v[196:199], v[66:69]
	s_barrier
; #define PG8_BAR __builtin_amdgcn_s_barrier()
;     __device__ __forceinline__ void operator()(f32x4 (&acc)[2][2][4][2], const Unit& u, int wr, int wc, int fr, int fq) const {
;         const int row0 = u.pm * BM + wr * 64 + fr, col0 = u.pn * BM + wc * 32 + 8 * fq;
;         const bf16_t* gl = G + ((size_t)u.pm * 24 + u.pn) * 65536 + ((size_t)(wr * 4 + wc) * 16 * 64 + fq * 16 + fr) * 8;
;         if (u.nt) {
;             const int tile = (u.pm - 64) * 8 + u.pn, w = wr * 4 + wc;
;             const auto rsrc = __builtin_amdgcn_make_buffer_rsrc((void*)PM, 0, 96 * 131072, 0x00020000);
; template <class Epi, class Sched>
; __device__ __forceinline__ void gemm_phase(LAS unsigned char* lds, const Gemm g, const Sched& S, const Epi& E) {
;     ...
;         for (int t = 0; t < ntu; t += 2) {
;             const bool last = (t == ntu - 2);
;             const char* a1 = cA + (size_t)(t + 1) * kstep;
;             const char* a2 = last ? nA : cA + (size_t)(t + 2) * kstep; const char* b2 = last ? nB : cB + (size_t)(t + 2) * kstep;
;             const char* a3 = a2 + kstep; const char* b3 = b2 + kstep;
;             if (last && has_next) S.a_ready(nxt);
;             PG8_LDB(B0, 0, 0); PG8_SCHED; PG8_LDA(At, 0, 0); PG8_STAGE(PG8_SA(1, 1), a1 + hstepA, voffA);
;             PG8_WAIT_L(8); PG8_BAR; PG8_WAIT_L(0); PG8_MMA(0, 0, At, B0); PG8_BAR; PG8_SCHED;
;             PG8_LDB(B1, 0, 1); PG8_STAGE(PG8_SB(0, 0), b2, voffB);
;             PG8_BAR; PG8_WAIT_L(0); PG8_MMA(0, 1, At, B1); PG8_BAR;
;             PG8_LDA(At, 0, 1); PG8_STAGE(PG8_SA(0, 0), a2, voffA);
;             PG8_BAR; PG8_WAIT_L(0); PG8_MMA(1, 0, At, B0); PG8_BAR; PG8_SCHED;
;             PG8_STAGE(PG8_SB(0, 1), b2 + hstepB, voffB);
;             PG8_WAIT_V(6); PG8_BAR; PG8_MMA(1, 1, At, B1); PG8_BAR;
;             PG8_LDB(B0, 1, 0); PG8_SCHED; PG8_LDA(At, 1, 0); PG8_STAGE(PG8_SA(0, 1), a2 + hstepA, voffA);
;             PG8_WAIT_L(8); PG8_BAR; PG8_WAIT_L(0); PG8_MMA(0, 0, At, B0); PG8_BAR; PG8_SCHED;
;             PG8_LDB(B1, 1, 1); PG8_STAGE(PG8_SB(1, 0), b3, voffB);
;             PG8_BAR; PG8_WAIT_L(0); PG8_MMA(0, 1, At, B1); PG8_BAR;
;             PG8_LDA(At, 1, 1); PG8_STAGE(PG8_SA(1, 0), a3, voffA);
;             PG8_BAR; PG8_WAIT_L(0); PG8_MMA(1, 0, At, B0); PG8_BAR; PG8_SCHED;
;             PG8_STAGE(PG8_SB(1, 1), b3 + hstepB, voffB);
;             PG8_WAIT_V(6); PG8_BAR; PG8_MMA(1, 1, At, B1); PG8_BAR;
	ds_read_b128 v[146:149], v209 offset:49152
	ds_read_b128 v[150:153], v209 offset:50176
	ds_read_b128 v[154:157], v209 offset:51200
	ds_read_b128 v[158:161], v209 offset:52224
	ds_read_b128 v[162:165], v209 offset:53248
	ds_read_b128 v[182:185], v209 offset:54272
	ds_read_b128 v[192:195], v209 offset:55296
	ds_read_b128 v[196:199], v209 offset:56320
	s_add_i32 s6, s35, s89
	v_lshl_add_u64 v[204:205], v[204:205], 0, s[92:93]
	s_mov_b32 m0, s6
	s_nop 0
	global_load_lds_dwordx4 v[204:205], off
	v_lshl_add_u64 v[204:205], v[222:223], 0, s[92:93]
	s_add_i32 m0, s6, 0x2000
	s_nop 0
	global_load_lds_dwordx4 v[204:205], off
	s_add_u32 s6, s26, 0x40080
	s_addc_u32 s7, s27, 0
	s_add_i32 s26, s28, s89
	v_lshl_add_u64 v[238:239], s[6:7], 0, v[178:179]
	s_mov_b32 m0, s26
	s_nop 0
	global_load_lds_dwordx4 v[238:239], off
	v_lshl_add_u64 v[238:239], s[6:7], 0, v[172:173]
	s_add_i32 m0, s26, 0x2000
	s_nop 0
	global_load_lds_dwordx4 v[238:239], off
	s_waitcnt vmcnt(4)
	s_waitcnt lgkmcnt(0)
	s_barrier
	v_mfma_f32_16x16x32_bf16 v[62:65], v[130:133], v[146:149], v[62:65]
	v_mfma_f32_16x16x32_bf16 v[58:61], v[138:141], v[146:149], v[58:61]
	v_mfma_f32_16x16x32_bf16 v[54:57], v[130:133], v[154:157], v[54:57]
	v_mfma_f32_16x16x32_bf16 v[50:53], v[138:141], v[154:157], v[50:53]
	v_mfma_f32_16x16x32_bf16 v[46:49], v[130:133], v[162:165], v[46:49]
	v_mfma_f32_16x16x32_bf16 v[42:45], v[138:141], v[162:165], v[42:45]
	v_mfma_f32_16x16x32_bf16 v[38:41], v[130:133], v[192:195], v[38:41]
	v_mfma_f32_16x16x32_bf16 v[34:37], v[138:141], v[192:195], v[34:37]
	v_mfma_f32_16x16x32_bf16 v[62:65], v[134:137], v[150:153], v[62:65]
	v_mfma_f32_16x16x32_bf16 v[58:61], v[142:145], v[150:153], v[58:61]
	v_mfma_f32_16x16x32_bf16 v[54:57], v[134:137], v[158:161], v[54:57]
	v_mfma_f32_16x16x32_bf16 v[50:53], v[142:145], v[158:161], v[50:53]
	v_mfma_f32_16x16x32_bf16 v[46:49], v[134:137], v[182:185], v[46:49]
	v_mfma_f32_16x16x32_bf16 v[42:45], v[142:145], v[182:185], v[42:45]
	v_mfma_f32_16x16x32_bf16 v[38:41], v[134:137], v[196:199], v[38:41]
	v_mfma_f32_16x16x32_bf16 v[34:37], v[142:145], v[196:199], v[34:37]
	v_mfma_f32_16x16x32_bf16 v[30:33], v[200:203], v[146:149], v[30:33]
	v_mfma_f32_16x16x32_bf16 v[26:29], v[214:217], v[146:149], v[26:29]
	v_mfma_f32_16x16x32_bf16 v[22:25], v[200:203], v[154:157], v[22:25]
	v_mfma_f32_16x16x32_bf16 v[18:21], v[214:217], v[154:157], v[18:21]
	v_mfma_f32_16x16x32_bf16 v[14:17], v[200:203], v[162:165], v[14:17]
	v_mfma_f32_16x16x32_bf16 v[10:13], v[214:217], v[162:165], v[10:13]
	v_mfma_f32_16x16x32_bf16 v[6:9], v[200:203], v[192:195], v[6:9]
	v_mfma_f32_16x16x32_bf16 v[2:5], v[214:217], v[192:195], v[2:5]
	v_mfma_f32_16x16x32_bf16 v[30:33], v[210:213], v[150:153], v[30:33]
	v_mfma_f32_16x16x32_bf16 v[26:29], v[218:221], v[150:153], v[26:29]
	v_mfma_f32_16x16x32_bf16 v[22:25], v[210:213], v[158:161], v[22:25]
	v_mfma_f32_16x16x32_bf16 v[18:21], v[218:221], v[158:161], v[18:21]
	v_mfma_f32_16x16x32_bf16 v[14:17], v[210:213], v[182:185], v[14:17]
	v_mfma_f32_16x16x32_bf16 v[10:13], v[218:221], v[182:185], v[10:13]
	v_mfma_f32_16x16x32_bf16 v[6:9], v[210:213], v[196:199], v[6:9]
	v_mfma_f32_16x16x32_bf16 v[2:5], v[218:221], v[196:199], v[2:5]
	s_add_u32 s68, s68, 0x100
	s_addc_u32 s69, s69, 0
	s_add_u32 s55, s55, 0x100
	s_addc_u32 s59, s59, 0
	s_cmp_ge_i32 s63, s1
	s_mov_b32 s28, s63
	s_barrier
	s_cbranch_scc0 .LBB0_871
	s_lshl_b64 s[6:7], s[66:67], 17
	v_lshl_add_u32 v210, s20, 8, v206
	v_lshl_or_b32 v194, s12, 8, v167
	v_lshl_add_u64 v[192:193], v[176:177], 0, s[6:7]
	s_andn2_b64 vcc, exec, vcc
	s_mov_b64 s[26:27], -1
	s_cbranch_vccnz .LBB0_880
	s_ashr_i32 s23, s22, 31
	s_lshl_b64 s[6:7], s[22:23], 20
	v_lshl_add_u64 v[158:159], v[192:193], 0, s[6:7]
	global_load_dwordx4 v[162:165], v[158:159], off
	global_load_dwordx4 v[154:157], v[158:159], off offset:1024
	global_load_dwordx4 v[150:153], v[158:159], off offset:2048
	global_load_dwordx4 v[146:149], v[158:159], off offset:3072
	v_add_co_u32_e32 v130, vcc, s48, v158
	s_movk_i32 s6, 0x2000
	s_nop 0
	v_addc_co_u32_e32 v131, vcc, 0, v159, vcc
	v_add_co_u32_e32 v160, vcc, s6, v158
	s_lshl_b32 s1, s20, 3
	s_nop 0
	v_addc_co_u32_e32 v161, vcc, 0, v159, vcc
	global_load_dwordx4 v[142:145], v[160:161], off offset:-4096
	global_load_dwordx4 v[138:141], v[130:131], off offset:1024
	global_load_dwordx4 v[134:137], v[130:131], off offset:2048
	s_nop 0
	global_load_dwordx4 v[130:133], v[130:131], off offset:3072
	s_add_i32 s1, s12, s1
	s_addk_i32 s1, 0xfe00
	s_mul_i32 s12, s1, 0x60000
	s_lshl_b32 s6, s22, 17
	s_add_i32 s12, s12, s6
	s_movk_i32 s6, 0x3000
	s_waitcnt vmcnt(0)
; __device__ __forceinline__ unsigned cvt_pk_bf16(float lo, float hi) { const f32x2_t v = {lo, hi}; return __builtin_bit_cast(unsigned, __builtin_convertvector(v, bf16x2_t)); }
;     __device__ __forceinline__ void operator()(f32x4 (&acc)[2][2][4][2], const Unit& u, int wr, int wc, int fr, int fq) const {
;     ...
;                     for (int bj = 0; bj < 2; ++bj) ra[m][bj] = *(const u32x4*)(gl + (size_t)u.seg * 8 * 65536 + ((ai * 4 + m) * 2 + bj) * 512);
; #pragma unroll
;                 for (int m = 0; m < 4; ++m)
; #pragma unroll
;                     for (int bj = 0; bj < 2; ++bj) { float f[8]; unpack8(ra[m][bj], f);
;                         const f32x4 v0 = acc[ai][bj][m][0], v1 = acc[ai][bj][m][1];
;                         u32x4 wv; wv.x = cvt_pk_bf16(v0[0] * f[0], v0[1] * f[1]); wv.y = cvt_pk_bf16(v0[2] * f[2], v0[3] * f[3]); wv.z = cvt_pk_bf16(v1[0] * f[4], v1[1] * f[5]); wv.w = cvt_pk_bf16(v1[2] * f[6], v1[3] * f[7]);
;                         __builtin_amdgcn_raw_buffer_store_b128(wv, rsrc, pbase + (unsigned)u.seg * 131072u + (unsigned)(((ai * 4 + m) * 2 + bj) * 1024), 0,   16); }
;             }
	v_lshlrev_b32_e32 v182, 16, v162
	v_and_b32_e32 v183, 0xffff0000, v162
	v_lshlrev_b32_e32 v162, 16, v163
	v_and_b32_e32 v163, 0xffff0000, v163
	v_pk_mul_f32 v[182:183], v[126:127], v[182:183]
	v_pk_mul_f32 v[162:163], v[128:129], v[162:163]
	v_cvt_pk_bf16_f32 v182, v182, v183
	v_cvt_pk_bf16_f32 v183, v162, v163
	v_lshlrev_b32_e32 v162, 16, v164
	v_and_b32_e32 v163, 0xffff0000, v164
	v_pk_mul_f32 v[162:163], v[122:123], v[162:163]
	v_lshlrev_b32_e32 v164, 16, v154
	v_cvt_pk_bf16_f32 v184, v162, v163
	v_lshlrev_b32_e32 v162, 16, v165
	v_and_b32_e32 v163, 0xffff0000, v165
	v_and_b32_e32 v165, 0xffff0000, v154
	v_pk_mul_f32 v[164:165], v[94:95], v[164:165]
	v_pk_mul_f32 v[162:163], v[124:125], v[162:163]
	v_cvt_pk_bf16_f32 v154, v164, v165
	v_lshlrev_b32_e32 v164, 16, v155
	v_and_b32_e32 v165, 0xffff0000, v155
	v_pk_mul_f32 v[164:165], v[96:97], v[164:165]
	v_cvt_pk_bf16_f32 v185, v162, v163
	v_cvt_pk_bf16_f32 v155, v164, v165
	v_lshlrev_b32_e32 v164, 16, v156
	v_and_b32_e32 v165, 0xffff0000, v156
	v_pk_mul_f32 v[164:165], v[90:91], v[164:165]
	v_add_u32_e32 v162, s12, v208
	v_cvt_pk_bf16_f32 v156, v164, v165
	v_lshlrev_b32_e32 v164, 16, v157
	v_and_b32_e32 v165, 0xffff0000, v157
	v_pk_mul_f32 v[164:165], v[92:93], v[164:165]
	v_add_u32_e32 v1, 0x1000, v162
	v_cvt_pk_bf16_f32 v157, v164, v165
	buffer_store_dwordx4 v[154:157], v162, s[16:19], 0 offen offset:1024 sc1
	buffer_store_dwordx4 v[182:185], v162, s[16:19], 0 offen sc1
	s_nop 0
	v_lshlrev_b32_e32 v154, 16, v150
	v_and_b32_e32 v155, 0xffff0000, v150
	v_pk_mul_f32 v[154:155], v[118:119], v[154:155]
	s_nop 0
	v_cvt_pk_bf16_f32 v150, v154, v155
	v_lshlrev_b32_e32 v154, 16, v151
	v_and_b32_e32 v155, 0xffff0000, v151
	v_pk_mul_f32 v[154:155], v[120:121], v[154:155]
	s_nop 0
	v_cvt_pk_bf16_f32 v151, v154, v155
	v_lshlrev_b32_e32 v154, 16, v152
	v_and_b32_e32 v155, 0xffff0000, v152
	v_pk_mul_f32 v[154:155], v[114:115], v[154:155]
	s_nop 0
	v_cvt_pk_bf16_f32 v152, v154, v155
	v_lshlrev_b32_e32 v154, 16, v153
	v_and_b32_e32 v155, 0xffff0000, v153
	v_pk_mul_f32 v[154:155], v[116:117], v[154:155]
	s_nop 0
	v_cvt_pk_bf16_f32 v153, v154, v155
	buffer_store_dwordx4 v[150:153], v162, s[16:19], 0 offen offset:2048 sc1
	s_nop 1
	v_lshlrev_b32_e32 v150, 16, v146
	v_and_b32_e32 v151, 0xffff0000, v146
	v_pk_mul_f32 v[150:151], v[86:87], v[150:151]
	s_nop 0
	v_cvt_pk_bf16_f32 v146, v150, v151
	v_lshlrev_b32_e32 v150, 16, v147
	v_and_b32_e32 v151, 0xffff0000, v147
	v_pk_mul_f32 v[150:151], v[88:89], v[150:151]
	s_nop 0
	v_cvt_pk_bf16_f32 v147, v150, v151
	v_lshlrev_b32_e32 v150, 16, v148
	v_and_b32_e32 v151, 0xffff0000, v148
	v_pk_mul_f32 v[150:151], v[82:83], v[150:151]
	s_nop 0
	v_cvt_pk_bf16_f32 v148, v150, v151
	v_lshlrev_b32_e32 v150, 16, v149
	v_and_b32_e32 v151, 0xffff0000, v149
	v_pk_mul_f32 v[150:151], v[84:85], v[150:151]
	s_nop 0
	v_cvt_pk_bf16_f32 v149, v150, v151
	buffer_store_dwordx4 v[146:149], v162, s[16:19], 0 offen offset:3072 sc1
	s_nop 1
	v_lshlrev_b32_e32 v146, 16, v142
	v_and_b32_e32 v147, 0xffff0000, v142
	v_pk_mul_f32 v[146:147], v[110:111], v[146:147]
	s_nop 0
	v_cvt_pk_bf16_f32 v142, v146, v147
	v_lshlrev_b32_e32 v146, 16, v143
	v_and_b32_e32 v147, 0xffff0000, v143
	v_pk_mul_f32 v[146:147], v[112:113], v[146:147]
	s_nop 0
	v_cvt_pk_bf16_f32 v143, v146, v147
	v_lshlrev_b32_e32 v146, 16, v144
	v_and_b32_e32 v147, 0xffff0000, v144
	v_pk_mul_f32 v[146:147], v[106:107], v[146:147]
	s_nop 0
	v_cvt_pk_bf16_f32 v144, v146, v147
	v_lshlrev_b32_e32 v146, 16, v145
	v_and_b32_e32 v147, 0xffff0000, v145
	v_pk_mul_f32 v[146:147], v[108:109], v[146:147]
	s_nop 0
	v_cvt_pk_bf16_f32 v145, v146, v147
	buffer_store_dwordx4 v[142:145], v1, s[16:19], 0 offen sc1
	s_nop 1
	v_lshlrev_b32_e32 v142, 16, v138
	v_and_b32_e32 v143, 0xffff0000, v138
	v_pk_mul_f32 v[142:143], v[78:79], v[142:143]
	s_nop 0
	v_cvt_pk_bf16_f32 v138, v142, v143
	v_lshlrev_b32_e32 v142, 16, v139
	v_and_b32_e32 v143, 0xffff0000, v139
	v_pk_mul_f32 v[142:143], v[80:81], v[142:143]
	s_nop 0
	v_cvt_pk_bf16_f32 v139, v142, v143
	v_lshlrev_b32_e32 v142, 16, v140
	v_and_b32_e32 v143, 0xffff0000, v140
	v_pk_mul_f32 v[142:143], v[74:75], v[142:143]
	s_nop 0
	v_cvt_pk_bf16_f32 v140, v142, v143
	v_lshlrev_b32_e32 v142, 16, v141
	v_and_b32_e32 v143, 0xffff0000, v141
	v_pk_mul_f32 v[142:143], v[76:77], v[142:143]
	s_nop 0
	v_cvt_pk_bf16_f32 v141, v142, v143
	buffer_store_dwordx4 v[138:141], v1, s[16:19], 0 offen offset:1024 sc1
	s_nop 1
	v_lshlrev_b32_e32 v138, 16, v134
	v_and_b32_e32 v139, 0xffff0000, v134
	v_pk_mul_f32 v[138:139], v[102:103], v[138:139]
	s_nop 0
	v_cvt_pk_bf16_f32 v134, v138, v139
	v_lshlrev_b32_e32 v138, 16, v135
	v_and_b32_e32 v139, 0xffff0000, v135
	v_pk_mul_f32 v[138:139], v[104:105], v[138:139]
	s_nop 0
	v_cvt_pk_bf16_f32 v135, v138, v139
	v_lshlrev_b32_e32 v138, 16, v136
	v_and_b32_e32 v139, 0xffff0000, v136
	v_pk_mul_f32 v[138:139], v[98:99], v[138:139]
	s_nop 0
	v_cvt_pk_bf16_f32 v136, v138, v139
	v_lshlrev_b32_e32 v138, 16, v137
	v_and_b32_e32 v139, 0xffff0000, v137
	v_pk_mul_f32 v[138:139], v[100:101], v[138:139]
	s_nop 0
	v_cvt_pk_bf16_f32 v137, v138, v139
	buffer_store_dwordx4 v[134:137], v1, s[16:19], 0 offen offset:2048 sc1
	s_nop 1
	v_lshlrev_b32_e32 v134, 16, v130
	v_and_b32_e32 v135, 0xffff0000, v130
	v_pk_mul_f32 v[134:135], v[70:71], v[134:135]
	s_nop 0
	v_cvt_pk_bf16_f32 v130, v134, v135
	v_lshlrev_b32_e32 v134, 16, v131
	v_and_b32_e32 v135, 0xffff0000, v131
	v_pk_mul_f32 v[134:135], v[72:73], v[134:135]
	s_nop 0
	v_cvt_pk_bf16_f32 v131, v134, v135
	v_lshlrev_b32_e32 v134, 16, v132
	v_and_b32_e32 v135, 0xffff0000, v132
	v_pk_mul_f32 v[134:135], v[66:67], v[134:135]
	s_nop 0
	v_cvt_pk_bf16_f32 v132, v134, v135
	v_lshlrev_b32_e32 v134, 16, v133
	v_and_b32_e32 v135, 0xffff0000, v133
	v_pk_mul_f32 v[134:135], v[68:69], v[134:135]
	s_nop 0
	v_cvt_pk_bf16_f32 v133, v134, v135
	buffer_store_dwordx4 v[130:133], v1, s[16:19], 0 offen offset:3072 sc1
	global_load_dwordx4 v[134:137], v[160:161], off
	global_load_dwordx4 v[138:141], v[160:161], off offset:1024
	global_load_dwordx4 v[142:145], v[160:161], off offset:2048
	global_load_dwordx4 v[146:149], v[160:161], off offset:3072
	v_add_co_u32_e32 v130, vcc, s6, v158
	v_add_u32_e32 v1, 0x2000, v162
	s_nop 0
	v_addc_co_u32_e32 v131, vcc, 0, v159, vcc
	global_load_dwordx4 v[150:153], v[130:131], off
	global_load_dwordx4 v[154:157], v[130:131], off offset:1024
	global_load_dwordx4 v[158:161], v[130:131], off offset:2048
	s_nop 0
	global_load_dwordx4 v[130:133], v[130:131], off offset:3072
	s_waitcnt vmcnt(0)
; __device__ __forceinline__ unsigned cvt_pk_bf16(float lo, float hi) { const f32x2_t v = {lo, hi}; return __builtin_bit_cast(unsigned, __builtin_convertvector(v, bf16x2_t)); }
;     __device__ __forceinline__ void operator()(f32x4 (&acc)[2][2][4][2], const Unit& u, int wr, int wc, int fr, int fq) const {
;     ...
;                     for (int bj = 0; bj < 2; ++bj) ra[m][bj] = *(const u32x4*)(gl + (size_t)u.seg * 8 * 65536 + ((ai * 4 + m) * 2 + bj) * 512);
; #pragma unroll
;                 for (int m = 0; m < 4; ++m)
; #pragma unroll
;                     for (int bj = 0; bj < 2; ++bj) { float f[8]; unpack8(ra[m][bj], f);
;                         const f32x4 v0 = acc[ai][bj][m][0], v1 = acc[ai][bj][m][1];
;                         u32x4 wv; wv.x = cvt_pk_bf16(v0[0] * f[0], v0[1] * f[1]); wv.y = cvt_pk_bf16(v0[2] * f[2], v0[3] * f[3]); wv.z = cvt_pk_bf16(v1[0] * f[4], v1[1] * f[5]); wv.w = cvt_pk_bf16(v1[2] * f[6], v1[3] * f[7]);
;                         __builtin_amdgcn_raw_buffer_store_b128(wv, rsrc, pbase + (unsigned)u.seg * 131072u + (unsigned)(((ai * 4 + m) * 2 + bj) * 1024), 0,   16); }
;             }
;             asm volatile("s_waitcnt vmcnt(0)" ::: "memory");
;             unsigned old = 0; if ((fq | fr) == 0) old = __hip_atomic_fetch_add(cnt + tile * 8 + w, 1u, __ATOMIC_RELAXED, __HIP_MEMORY_SCOPE_AGENT);
;             old = (unsigned)__builtin_amdgcn_readfirstlane((int)old);
;             if (old == 2) {
	v_lshlrev_b32_e32 v164, 16, v134
	v_and_b32_e32 v165, 0xffff0000, v134
	v_pk_mul_f32 v[164:165], v[62:63], v[164:165]
	s_nop 0
	v_cvt_pk_bf16_f32 v134, v164, v165
	v_lshlrev_b32_e32 v164, 16, v135
	v_and_b32_e32 v165, 0xffff0000, v135
	v_pk_mul_f32 v[164:165], v[64:65], v[164:165]
	s_nop 0
	v_cvt_pk_bf16_f32 v135, v164, v165
	v_lshlrev_b32_e32 v164, 16, v136
	v_and_b32_e32 v165, 0xffff0000, v136
	v_pk_mul_f32 v[164:165], v[58:59], v[164:165]
	s_nop 0
	v_cvt_pk_bf16_f32 v136, v164, v165
	v_lshlrev_b32_e32 v164, 16, v137
	v_and_b32_e32 v165, 0xffff0000, v137
	v_pk_mul_f32 v[164:165], v[60:61], v[164:165]
	s_nop 0
	v_cvt_pk_bf16_f32 v137, v164, v165
	buffer_store_dwordx4 v[134:137], v1, s[16:19], 0 offen sc1
	s_nop 1
	v_lshlrev_b32_e32 v134, 16, v138
	v_and_b32_e32 v135, 0xffff0000, v138
	v_lshlrev_b32_e32 v136, 16, v139
	v_and_b32_e32 v137, 0xffff0000, v139
	v_pk_mul_f32 v[134:135], v[30:31], v[134:135]
	v_pk_mul_f32 v[136:137], v[32:33], v[136:137]
	v_cvt_pk_bf16_f32 v134, v134, v135
	v_cvt_pk_bf16_f32 v135, v136, v137
	v_lshlrev_b32_e32 v136, 16, v140
	v_and_b32_e32 v137, 0xffff0000, v140
	v_lshlrev_b32_e32 v138, 16, v141
	v_and_b32_e32 v139, 0xffff0000, v141
	v_pk_mul_f32 v[136:137], v[26:27], v[136:137]
	v_pk_mul_f32 v[138:139], v[28:29], v[138:139]
	v_cvt_pk_bf16_f32 v136, v136, v137
	v_cvt_pk_bf16_f32 v137, v138, v139
	buffer_store_dwordx4 v[134:137], v1, s[16:19], 0 offen offset:1024 sc1
	v_lshlrev_b32_e32 v138, 16, v145
	v_and_b32_e32 v139, 0xffff0000, v145
	v_lshlrev_b32_e32 v134, 16, v142
	v_and_b32_e32 v135, 0xffff0000, v142
	v_lshlrev_b32_e32 v136, 16, v143
	v_and_b32_e32 v137, 0xffff0000, v143
	v_pk_mul_f32 v[134:135], v[54:55], v[134:135]
	v_pk_mul_f32 v[136:137], v[56:57], v[136:137]
	v_cvt_pk_bf16_f32 v134, v134, v135
	v_cvt_pk_bf16_f32 v135, v136, v137
	v_lshlrev_b32_e32 v136, 16, v144
	v_and_b32_e32 v137, 0xffff0000, v144
	v_pk_mul_f32 v[136:137], v[50:51], v[136:137]
	v_pk_mul_f32 v[138:139], v[52:53], v[138:139]
	v_cvt_pk_bf16_f32 v136, v136, v137
	v_cvt_pk_bf16_f32 v137, v138, v139
	buffer_store_dwordx4 v[134:137], v1, s[16:19], 0 offen offset:2048 sc1
	v_lshlrev_b32_e32 v138, 16, v149
	v_and_b32_e32 v139, 0xffff0000, v149
	v_lshlrev_b32_e32 v134, 16, v146
	v_and_b32_e32 v135, 0xffff0000, v146
	v_lshlrev_b32_e32 v136, 16, v147
	v_and_b32_e32 v137, 0xffff0000, v147
	v_pk_mul_f32 v[134:135], v[22:23], v[134:135]
	v_pk_mul_f32 v[136:137], v[24:25], v[136:137]
	v_cvt_pk_bf16_f32 v134, v134, v135
	v_cvt_pk_bf16_f32 v135, v136, v137
	v_lshlrev_b32_e32 v136, 16, v148
	v_and_b32_e32 v137, 0xffff0000, v148
	v_pk_mul_f32 v[136:137], v[18:19], v[136:137]
	v_pk_mul_f32 v[138:139], v[20:21], v[138:139]
	v_cvt_pk_bf16_f32 v136, v136, v137
	v_cvt_pk_bf16_f32 v137, v138, v139
	buffer_store_dwordx4 v[134:137], v1, s[16:19], 0 offen offset:3072 sc1
	v_lshlrev_b32_e32 v138, 16, v153
	v_and_b32_e32 v139, 0xffff0000, v153
	v_lshlrev_b32_e32 v134, 16, v150
	v_and_b32_e32 v135, 0xffff0000, v150
	v_lshlrev_b32_e32 v136, 16, v151
	v_and_b32_e32 v137, 0xffff0000, v151
	v_pk_mul_f32 v[134:135], v[46:47], v[134:135]
	v_pk_mul_f32 v[136:137], v[48:49], v[136:137]
	v_cvt_pk_bf16_f32 v134, v134, v135
	v_cvt_pk_bf16_f32 v135, v136, v137
	v_lshlrev_b32_e32 v136, 16, v152
	v_and_b32_e32 v137, 0xffff0000, v152
	v_pk_mul_f32 v[136:137], v[42:43], v[136:137]
	v_pk_mul_f32 v[138:139], v[44:45], v[138:139]
	v_cvt_pk_bf16_f32 v136, v136, v137
	v_cvt_pk_bf16_f32 v137, v138, v139
	v_add_u32_e32 v1, 0x3000, v162
	buffer_store_dwordx4 v[134:137], v1, s[16:19], 0 offen sc1
	v_lshlrev_b32_e32 v138, 16, v157
	v_and_b32_e32 v139, 0xffff0000, v157
	v_lshlrev_b32_e32 v134, 16, v154
	v_and_b32_e32 v135, 0xffff0000, v154
	v_lshlrev_b32_e32 v136, 16, v155
	v_and_b32_e32 v137, 0xffff0000, v155
	v_pk_mul_f32 v[134:135], v[14:15], v[134:135]
	v_pk_mul_f32 v[136:137], v[16:17], v[136:137]
	v_cvt_pk_bf16_f32 v134, v134, v135
	v_cvt_pk_bf16_f32 v135, v136, v137
	v_lshlrev_b32_e32 v136, 16, v156
	v_and_b32_e32 v137, 0xffff0000, v156
	v_pk_mul_f32 v[136:137], v[10:11], v[136:137]
	v_pk_mul_f32 v[138:139], v[12:13], v[138:139]
	v_cvt_pk_bf16_f32 v136, v136, v137
	v_cvt_pk_bf16_f32 v137, v138, v139
	buffer_store_dwordx4 v[134:137], v1, s[16:19], 0 offen offset:1024 sc1
	v_lshlrev_b32_e32 v138, 16, v161
	v_and_b32_e32 v139, 0xffff0000, v161
	v_lshlrev_b32_e32 v134, 16, v158
	v_and_b32_e32 v135, 0xffff0000, v158
	v_lshlrev_b32_e32 v136, 16, v159
	v_and_b32_e32 v137, 0xffff0000, v159
	v_pk_mul_f32 v[134:135], v[38:39], v[134:135]
	v_pk_mul_f32 v[136:137], v[40:41], v[136:137]
	v_cvt_pk_bf16_f32 v134, v134, v135
	v_cvt_pk_bf16_f32 v135, v136, v137
	v_lshlrev_b32_e32 v136, 16, v160
	v_and_b32_e32 v137, 0xffff0000, v160
	v_pk_mul_f32 v[136:137], v[34:35], v[136:137]
	v_pk_mul_f32 v[138:139], v[36:37], v[138:139]
	v_cvt_pk_bf16_f32 v136, v136, v137
	v_cvt_pk_bf16_f32 v137, v138, v139
	buffer_store_dwordx4 v[134:137], v1, s[16:19], 0 offen offset:2048 sc1
	s_nop 1
	v_lshlrev_b32_e32 v134, 16, v130
	v_and_b32_e32 v135, 0xffff0000, v130
	v_pk_mul_f32 v[134:135], v[6:7], v[134:135]
	s_nop 0
	v_cvt_pk_bf16_f32 v130, v134, v135
	v_lshlrev_b32_e32 v134, 16, v131
	v_and_b32_e32 v135, 0xffff0000, v131
	v_pk_mul_f32 v[134:135], v[8:9], v[134:135]
	s_nop 0
	v_cvt_pk_bf16_f32 v131, v134, v135
	v_lshlrev_b32_e32 v134, 16, v132
	v_and_b32_e32 v135, 0xffff0000, v132
	v_pk_mul_f32 v[134:135], v[2:3], v[134:135]
	s_nop 0
	v_cvt_pk_bf16_f32 v132, v134, v135
	v_lshlrev_b32_e32 v134, 16, v133
	v_and_b32_e32 v135, 0xffff0000, v133
	v_pk_mul_f32 v[134:135], v[4:5], v[134:135]
	s_nop 0
	v_cvt_pk_bf16_f32 v133, v134, v135
	buffer_store_dwordx4 v[130:133], v1, s[16:19], 0 offen offset:3072 sc1
	s_waitcnt vmcnt(0)
	s_nop 1
	v_mov_b32_e32 v130, 0
	s_and_saveexec_b64 s[12:13], s[4:5]
	s_cbranch_execz .LBB0_877
	s_mov_b64 s[26:27], exec
	v_mbcnt_lo_u32_b32 v1, s26, 0
	v_mbcnt_hi_u32_b32 v130, s27, v1
	v_cmp_eq_u32_e32 vcc, 0, v130
	s_and_saveexec_b64 s[20:21], vcc
	s_cbranch_execz .LBB0_876
	s_lshl_b32 s6, s1, 3
	s_ashr_i32 s7, s6, 31
	s_lshl_b64 s[6:7], s[6:7], 2
	v_readlane_b32 s23, v255, 36
	s_add_u32 s6, s23, s6
	v_readlane_b32 s23, v255, 37
	s_addc_u32 s7, s23, s7
	s_bcnt1_i32_b64 s23, s[26:27]
	v_mov_b32_e32 v1, s23
	global_atomic_add v131, v179, v1, s[6:7] sc0

; #define PG8_STAGE(bufoff, gbase, voff) do { _Pragma("unroll") for (int _i = 0; _i < 2; ++_i) \
;         __builtin_amdgcn_global_load_lds((const unsigned*)((const char*)(gbase) + (voff)[_i]), (LAS unsigned*)(lds + (bufoff) + ldsw + _i * 8192), 16, 0, 0); } while (0)
; #define PG8_LDA(dst, b, h) do { _Pragma("unroll") for (int m = 0; m < 4; ++m) _Pragma("unroll") for (int k = 0; k < 2; ++k) dst[m][k] = *(const LAS bf16x8*)(lds + PG8_SA(b, h) + aoff + m * 2048 + k * 1024); } while (0)
; #define PG8_WAIT_V(n) asm volatile("s_waitcnt vmcnt(" #n ")" ::: "memory")
; template <class Epi, class Sched>
; __device__ __forceinline__ void gemm_phase(LAS unsigned char* lds, const Gemm g, const Sched& S, const Epi& E) {
;     ...
;         for (int t = 0; t < ntu; t += 2) {
;             const bool last = (t == ntu - 2);
;             const char* a1 = cA + (size_t)(t + 1) * kstep;
;             const char* a2 = last ? nA : cA + (size_t)(t + 2) * kstep; const char* b2 = last ? nB : cB + (size_t)(t + 2) * kstep;
;             const char* a3 = a2 + kstep; const char* b3 = b2 + kstep;
;             if (last && has_next) S.a_ready(nxt);
;             PG8_LDB(B0, 0, 0); PG8_SCHED; PG8_LDA(At, 0, 0); PG8_STAGE(PG8_SA(1, 1), a1 + hstepA, voffA);
;             PG8_WAIT_L(8); PG8_BAR; PG8_WAIT_L(0); PG8_MMA(0, 0, At, B0); PG8_BAR; PG8_SCHED;
;             PG8_LDB(B1, 0, 1); PG8_STAGE(PG8_SB(0, 0), b2, voffB);
;             PG8_BAR; PG8_WAIT_L(0); PG8_MMA(0, 1, At, B1); PG8_BAR;
;             PG8_LDA(At, 0, 1); PG8_STAGE(PG8_SA(0, 0), a2, voffA);
;             PG8_BAR; PG8_WAIT_L(0); PG8_MMA(1, 0, At, B0); PG8_BAR; PG8_SCHED;
;             PG8_STAGE(PG8_SB(0, 1), b2 + hstepB, voffB);
;             PG8_WAIT_V(6); PG8_BAR; PG8_MMA(1, 1, At, B1); PG8_BAR;
;             PG8_LDB(B0, 1, 0); PG8_SCHED; PG8_LDA(At, 1, 0); PG8_STAGE(PG8_SA(0, 1), a2 + hstepA, voffA);
;             PG8_WAIT_L(8); PG8_BAR; PG8_WAIT_L(0); PG8_MMA(0, 0, At, B0); PG8_BAR; PG8_SCHED;
;             PG8_LDB(B1, 1, 1); PG8_STAGE(PG8_SB(1, 0), b3, voffB);
;             PG8_BAR; PG8_WAIT_L(0); PG8_MMA(0, 1, At, B1); PG8_BAR;
;             PG8_LDA(At, 1, 1); PG8_STAGE(PG8_SA(1, 0), a3, voffA);
;             PG8_BAR; PG8_WAIT_L(0); PG8_MMA(1, 0, At, B0); PG8_BAR; PG8_SCHED;
;             PG8_STAGE(PG8_SB(1, 1), b3 + hstepB, voffB);
;             PG8_WAIT_V(6); PG8_BAR; PG8_MMA(1, 1, At, B1); PG8_BAR;
.LBB0_985:
	s_add_i32 s72, s28, 2
	s_add_u32 s54, s52, 0x100
	s_addc_u32 s55, s53, 0
	s_add_i32 s35, 0, 0x10000
	v_add_u32_e32 v1, s35, v141
	ds_read_b128 v[144:147], v1
	ds_read_b128 v[148:151], v1 offset:1024
	ds_read_b128 v[152:155], v1 offset:2048
	ds_read_b128 v[156:159], v1 offset:3072
	s_cmp_eq_u32 s21, s28
	s_cselect_b32 s28, s24, s54
	s_cselect_b32 s29, s25, s55
	s_cselect_b32 s57, s27, s71
	s_cselect_b32 s56, s26, s70
	ds_read_b128 v[160:163], v143
	ds_read_b128 v[164:167], v143 offset:1024
	ds_read_b128 v[168:171], v143 offset:2048
	ds_read_b128 v[172:175], v143 offset:3072
	ds_read_b128 v[182:185], v143 offset:4096
	ds_read_b128 v[186:189], v143 offset:5120
	ds_read_b128 v[190:193], v143 offset:6144
	ds_read_b128 v[194:197], v143 offset:7168
	s_mov_b32 s98, 0xfff7c000
	s_mov_b32 s99, -1
	v_lshl_add_u64 v[232:233], s[52:53], 0, v[136:137]
	v_lshl_add_u64 v[232:233], v[232:233], 0, s[98:99]
	s_mov_b32 m0, s62
	s_nop 0
	global_load_lds_dwordx4 v[232:233], off
	v_lshl_add_u64 v[232:233], s[52:53], 0, v[138:139]
	v_lshl_add_u64 v[232:233], v[232:233], 0, s[98:99]
	s_mov_b32 m0, s63
	s_nop 0
	global_load_lds_dwordx4 v[232:233], off
	v_lshl_add_u64 v[232:233], s[52:53], 0, v[136:137]
	s_add_i32 m0, s9, 0xc000
	s_nop 0
	global_load_lds_dwordx4 v[232:233], off
	v_lshl_add_u64 v[232:233], s[52:53], 0, v[138:139]
	s_add_i32 m0, s9, 0xe000
	s_nop 0
	global_load_lds_dwordx4 v[232:233], off
	s_add_i32 s76, 0, 0x14000
	v_add_u32_e32 v1, s76, v141
	ds_read_b128 v[198:201], v1
	ds_read_b128 v[202:205], v1 offset:1024
	ds_read_b128 v[206:209], v1 offset:2048
	ds_read_b128 v[210:213], v1 offset:3072
	s_waitcnt lgkmcnt(0)
	s_barrier
	v_mfma_f32_16x16x32_bf16 v[126:129], v[144:147], v[160:163], v[126:129]
	v_mfma_f32_16x16x32_bf16 v[122:125], v[152:155], v[160:163], v[122:125]
	v_mfma_f32_16x16x32_bf16 v[110:113], v[144:147], v[168:171], v[110:113]
	v_mfma_f32_16x16x32_bf16 v[106:109], v[152:155], v[168:171], v[106:109]
	v_mfma_f32_16x16x32_bf16 v[94:97], v[144:147], v[182:185], v[94:97]
	v_mfma_f32_16x16x32_bf16 v[90:93], v[152:155], v[182:185], v[90:93]
	v_mfma_f32_16x16x32_bf16 v[78:81], v[144:147], v[190:193], v[78:81]
	v_mfma_f32_16x16x32_bf16 v[74:77], v[152:155], v[190:193], v[74:77]
	v_mfma_f32_16x16x32_bf16 v[126:129], v[148:151], v[164:167], v[126:129]
	v_mfma_f32_16x16x32_bf16 v[122:125], v[156:159], v[164:167], v[122:125]
	v_mfma_f32_16x16x32_bf16 v[110:113], v[148:151], v[172:175], v[110:113]
	v_mfma_f32_16x16x32_bf16 v[106:109], v[156:159], v[172:175], v[106:109]
	v_mfma_f32_16x16x32_bf16 v[94:97], v[148:151], v[186:189], v[94:97]
	v_mfma_f32_16x16x32_bf16 v[90:93], v[156:159], v[186:189], v[90:93]
	v_mfma_f32_16x16x32_bf16 v[78:81], v[148:151], v[194:197], v[78:81]
	v_mfma_f32_16x16x32_bf16 v[74:77], v[156:159], v[194:197], v[74:77]
	v_mfma_f32_16x16x32_bf16 v[118:121], v[198:201], v[160:163], v[118:121]
	v_mfma_f32_16x16x32_bf16 v[114:117], v[206:209], v[160:163], v[114:117]
	v_mfma_f32_16x16x32_bf16 v[102:105], v[198:201], v[168:171], v[102:105]
	v_mfma_f32_16x16x32_bf16 v[98:101], v[206:209], v[168:171], v[98:101]
	v_mfma_f32_16x16x32_bf16 v[86:89], v[198:201], v[182:185], v[86:89]
	v_mfma_f32_16x16x32_bf16 v[82:85], v[206:209], v[182:185], v[82:85]
	v_mfma_f32_16x16x32_bf16 v[70:73], v[198:201], v[190:193], v[70:73]
	v_mfma_f32_16x16x32_bf16 v[66:69], v[206:209], v[190:193], v[66:69]
	v_mfma_f32_16x16x32_bf16 v[118:121], v[202:205], v[164:167], v[118:121]
	v_mfma_f32_16x16x32_bf16 v[114:117], v[210:213], v[164:167], v[114:117]
	v_mfma_f32_16x16x32_bf16 v[102:105], v[202:205], v[172:175], v[102:105]
	v_mfma_f32_16x16x32_bf16 v[98:101], v[210:213], v[172:175], v[98:101]
	v_mfma_f32_16x16x32_bf16 v[86:89], v[202:205], v[186:189], v[86:89]
	v_mfma_f32_16x16x32_bf16 v[82:85], v[210:213], v[186:189], v[82:85]
	v_mfma_f32_16x16x32_bf16 v[70:73], v[202:205], v[194:197], v[70:73]
	v_mfma_f32_16x16x32_bf16 v[66:69], v[210:213], v[194:197], v[66:69]
	s_barrier
	ds_read_b128 v[160:163], v143 offset:16384
	ds_read_b128 v[164:167], v143 offset:17408
	ds_read_b128 v[168:171], v143 offset:18432
	ds_read_b128 v[172:175], v143 offset:19456
	ds_read_b128 v[182:185], v143 offset:20480
	ds_read_b128 v[186:189], v143 offset:21504
	ds_read_b128 v[190:193], v143 offset:22528
	ds_read_b128 v[194:197], v143 offset:23552
	s_add_i32 s35, s35, s46
	v_lshl_add_u64 v[176:177], s[56:57], 0, v[178:179]
	s_mov_b32 m0, s35
	s_nop 0
	global_load_lds_dwordx4 v[176:177], off
	v_lshl_add_u64 v[214:215], s[56:57], 0, v[134:135]
	s_add_i32 m0, s35, 0x2000
	s_nop 0
	global_load_lds_dwordx4 v[214:215], off
	s_add_u32 s52, s56, 0x80000
	s_addc_u32 s53, s57, 0
	s_add_i32 s35, s76, s46
	v_lshl_add_u64 v[234:235], s[52:53], 0, v[178:179]
	s_mov_b32 m0, s35
	s_nop 0
	global_load_lds_dwordx4 v[234:235], off
	v_lshl_add_u64 v[234:235], s[52:53], 0, v[134:135]
	s_add_i32 m0, s35, 0x2000
	s_nop 0
	global_load_lds_dwordx4 v[234:235], off
	s_waitcnt vmcnt(4)
	s_waitcnt lgkmcnt(0)
	s_barrier
; #define PG8_STAGE(bufoff, gbase, voff) do { _Pragma("unroll") for (int _i = 0; _i < 2; ++_i) \
;         __builtin_amdgcn_global_load_lds((const unsigned*)((const char*)(gbase) + (voff)[_i]), (LAS unsigned*)(lds + (bufoff) + ldsw + _i * 8192), 16, 0, 0); } while (0)
; #define PG8_LDA(dst, b, h) do { _Pragma("unroll") for (int m = 0; m < 4; ++m) _Pragma("unroll") for (int k = 0; k < 2; ++k) dst[m][k] = *(const LAS bf16x8*)(lds + PG8_SA(b, h) + aoff + m * 2048 + k * 1024); } while (0)
; #define PG8_WAIT_V(n) asm volatile("s_waitcnt vmcnt(" #n ")" ::: "memory")
; template <class Epi, class Sched>
; __device__ __forceinline__ void gemm_phase(LAS unsigned char* lds, const Gemm g, const Sched& S, const Epi& E) {
;     ...
;         for (int t = 0; t < ntu; t += 2) {
;             const bool last = (t == ntu - 2);
;             const char* a1 = cA + (size_t)(t + 1) * kstep;
;             const char* a2 = last ? nA : cA + (size_t)(t + 2) * kstep; const char* b2 = last ? nB : cB + (size_t)(t + 2) * kstep;
;             const char* a3 = a2 + kstep; const char* b3 = b2 + kstep;
;             if (last && has_next) S.a_ready(nxt);
;             PG8_LDB(B0, 0, 0); PG8_SCHED; PG8_LDA(At, 0, 0); PG8_STAGE(PG8_SA(1, 1), a1 + hstepA, voffA);
;             PG8_WAIT_L(8); PG8_BAR; PG8_WAIT_L(0); PG8_MMA(0, 0, At, B0); PG8_BAR; PG8_SCHED;
;             PG8_LDB(B1, 0, 1); PG8_STAGE(PG8_SB(0, 0), b2, voffB);
;             PG8_BAR; PG8_WAIT_L(0); PG8_MMA(0, 1, At, B1); PG8_BAR;
;             PG8_LDA(At, 0, 1); PG8_STAGE(PG8_SA(0, 0), a2, voffA);
;             PG8_BAR; PG8_WAIT_L(0); PG8_MMA(1, 0, At, B0); PG8_BAR; PG8_SCHED;
;             PG8_STAGE(PG8_SB(0, 1), b2 + hstepB, voffB);
;             PG8_WAIT_V(6); PG8_BAR; PG8_MMA(1, 1, At, B1); PG8_BAR;
;             PG8_LDB(B0, 1, 0); PG8_SCHED; PG8_LDA(At, 1, 0); PG8_STAGE(PG8_SA(0, 1), a2 + hstepA, voffA);
;             PG8_WAIT_L(8); PG8_BAR; PG8_WAIT_L(0); PG8_MMA(0, 0, At, B0); PG8_BAR; PG8_SCHED;
;             PG8_LDB(B1, 1, 1); PG8_STAGE(PG8_SB(1, 0), b3, voffB);
;             PG8_BAR; PG8_WAIT_L(0); PG8_MMA(0, 1, At, B1); PG8_BAR;
;             PG8_LDA(At, 1, 1); PG8_STAGE(PG8_SA(1, 0), a3, voffA);
;             PG8_BAR; PG8_WAIT_L(0); PG8_MMA(1, 0, At, B0); PG8_BAR; PG8_SCHED;
;             PG8_STAGE(PG8_SB(1, 1), b3 + hstepB, voffB);
;             PG8_WAIT_V(6); PG8_BAR; PG8_MMA(1, 1, At, B1); PG8_BAR;
	v_mfma_f32_16x16x32_bf16 v[62:65], v[144:147], v[160:163], v[62:65]
	v_mfma_f32_16x16x32_bf16 v[58:61], v[152:155], v[160:163], v[58:61]
	v_mfma_f32_16x16x32_bf16 v[46:49], v[144:147], v[168:171], v[46:49]
	v_mfma_f32_16x16x32_bf16 v[42:45], v[152:155], v[168:171], v[42:45]
	v_mfma_f32_16x16x32_bf16 v[30:33], v[144:147], v[182:185], v[30:33]
	v_mfma_f32_16x16x32_bf16 v[26:29], v[152:155], v[182:185], v[26:29]
	v_mfma_f32_16x16x32_bf16 v[14:17], v[144:147], v[190:193], v[14:17]
	v_mfma_f32_16x16x32_bf16 v[10:13], v[152:155], v[190:193], v[10:13]
	v_mfma_f32_16x16x32_bf16 v[62:65], v[148:151], v[164:167], v[62:65]
	v_mfma_f32_16x16x32_bf16 v[58:61], v[156:159], v[164:167], v[58:61]
	v_mfma_f32_16x16x32_bf16 v[46:49], v[148:151], v[172:175], v[46:49]
	v_mfma_f32_16x16x32_bf16 v[42:45], v[156:159], v[172:175], v[42:45]
	v_mfma_f32_16x16x32_bf16 v[30:33], v[148:151], v[186:189], v[30:33]
	v_mfma_f32_16x16x32_bf16 v[26:29], v[156:159], v[186:189], v[26:29]
	v_mfma_f32_16x16x32_bf16 v[14:17], v[148:151], v[194:197], v[14:17]
	v_mfma_f32_16x16x32_bf16 v[10:13], v[156:159], v[194:197], v[10:13]
	v_mfma_f32_16x16x32_bf16 v[54:57], v[198:201], v[160:163], v[54:57]
	v_mfma_f32_16x16x32_bf16 v[50:53], v[206:209], v[160:163], v[50:53]
	v_mfma_f32_16x16x32_bf16 v[38:41], v[198:201], v[168:171], v[38:41]
	v_mfma_f32_16x16x32_bf16 v[34:37], v[206:209], v[168:171], v[34:37]
	v_mfma_f32_16x16x32_bf16 v[22:25], v[198:201], v[182:185], v[22:25]
	v_mfma_f32_16x16x32_bf16 v[18:21], v[206:209], v[182:185], v[18:21]
	v_mfma_f32_16x16x32_bf16 v[6:9], v[198:201], v[190:193], v[6:9]
	v_mfma_f32_16x16x32_bf16 v[2:5], v[206:209], v[190:193], v[2:5]
	v_mfma_f32_16x16x32_bf16 v[54:57], v[202:205], v[164:167], v[54:57]
	v_mfma_f32_16x16x32_bf16 v[50:53], v[210:213], v[164:167], v[50:53]
	v_mfma_f32_16x16x32_bf16 v[38:41], v[202:205], v[172:175], v[38:41]
	v_mfma_f32_16x16x32_bf16 v[34:37], v[210:213], v[172:175], v[34:37]
	v_mfma_f32_16x16x32_bf16 v[22:25], v[202:205], v[186:189], v[22:25]
	v_mfma_f32_16x16x32_bf16 v[18:21], v[210:213], v[186:189], v[18:21]
	v_mfma_f32_16x16x32_bf16 v[6:9], v[202:205], v[194:197], v[6:9]
	v_mfma_f32_16x16x32_bf16 v[2:5], v[210:213], v[194:197], v[2:5]
	s_add_i32 s35, 0, 0x18000
	v_add_u32_e32 v1, s35, v141
	s_barrier
	ds_read_b128 v[144:147], v1
	ds_read_b128 v[148:151], v1 offset:1024
	ds_read_b128 v[152:155], v1 offset:2048
	ds_read_b128 v[156:159], v1 offset:3072
	ds_read_b128 v[160:163], v143 offset:32768
	ds_read_b128 v[164:167], v143 offset:33792
	ds_read_b128 v[168:171], v143 offset:34816
	ds_read_b128 v[172:175], v143 offset:35840
	ds_read_b128 v[182:185], v143 offset:36864
	ds_read_b128 v[186:189], v143 offset:37888
	ds_read_b128 v[190:193], v143 offset:38912
	ds_read_b128 v[194:197], v143 offset:39936
	s_mov_b32 m0, s9
	v_lshl_add_u64 v[216:217], s[28:29], 0, v[130:131]
	global_load_lds_dwordx4 v[216:217], off
	v_lshl_add_u64 v[218:219], s[28:29], 0, v[132:133]
	s_mov_b32 m0, s11
	s_nop 0
	global_load_lds_dwordx4 v[218:219], off
	s_add_u32 s28, s28, 0x84000
	s_addc_u32 s29, s29, 0
	s_mov_b32 m0, s58
	v_lshl_add_u64 v[236:237], s[28:29], 0, v[130:131]
	global_load_lds_dwordx4 v[236:237], off
	v_lshl_add_u64 v[236:237], s[28:29], 0, v[132:133]
	s_mov_b32 m0, s59
	s_nop 0
	global_load_lds_dwordx4 v[236:237], off
	s_add_i32 s52, 0, 0x1c000
	v_add_u32_e32 v1, s52, v141
	ds_read_b128 v[198:201], v1
	ds_read_b128 v[202:205], v1 offset:1024
	ds_read_b128 v[206:209], v1 offset:2048
	ds_read_b128 v[210:213], v1 offset:3072
	s_waitcnt lgkmcnt(0)
	s_barrier
	v_mfma_f32_16x16x32_bf16 v[126:129], v[144:147], v[160:163], v[126:129]
	v_mfma_f32_16x16x32_bf16 v[122:125], v[152:155], v[160:163], v[122:125]
	v_mfma_f32_16x16x32_bf16 v[110:113], v[144:147], v[168:171], v[110:113]
	v_mfma_f32_16x16x32_bf16 v[106:109], v[152:155], v[168:171], v[106:109]
	v_mfma_f32_16x16x32_bf16 v[94:97], v[144:147], v[182:185], v[94:97]
	v_mfma_f32_16x16x32_bf16 v[90:93], v[152:155], v[182:185], v[90:93]
	v_mfma_f32_16x16x32_bf16 v[78:81], v[144:147], v[190:193], v[78:81]
	v_mfma_f32_16x16x32_bf16 v[74:77], v[152:155], v[190:193], v[74:77]
	v_mfma_f32_16x16x32_bf16 v[126:129], v[148:151], v[164:167], v[126:129]
	v_mfma_f32_16x16x32_bf16 v[122:125], v[156:159], v[164:167], v[122:125]
	v_mfma_f32_16x16x32_bf16 v[110:113], v[148:151], v[172:175], v[110:113]
	v_mfma_f32_16x16x32_bf16 v[106:109], v[156:159], v[172:175], v[106:109]
	v_mfma_f32_16x16x32_bf16 v[94:97], v[148:151], v[186:189], v[94:97]
	v_mfma_f32_16x16x32_bf16 v[90:93], v[156:159], v[186:189], v[90:93]
	v_mfma_f32_16x16x32_bf16 v[78:81], v[148:151], v[194:197], v[78:81]
	v_mfma_f32_16x16x32_bf16 v[74:77], v[156:159], v[194:197], v[74:77]
	v_mfma_f32_16x16x32_bf16 v[118:121], v[198:201], v[160:163], v[118:121]
	v_mfma_f32_16x16x32_bf16 v[114:117], v[206:209], v[160:163], v[114:117]
	v_mfma_f32_16x16x32_bf16 v[102:105], v[198:201], v[168:171], v[102:105]
	v_mfma_f32_16x16x32_bf16 v[98:101], v[206:209], v[168:171], v[98:101]
	v_mfma_f32_16x16x32_bf16 v[86:89], v[198:201], v[182:185], v[86:89]
	v_mfma_f32_16x16x32_bf16 v[82:85], v[206:209], v[182:185], v[82:85]
	v_mfma_f32_16x16x32_bf16 v[70:73], v[198:201], v[190:193], v[70:73]
	v_mfma_f32_16x16x32_bf16 v[66:69], v[206:209], v[190:193], v[66:69]
	v_mfma_f32_16x16x32_bf16 v[118:121], v[202:205], v[164:167], v[118:121]
	v_mfma_f32_16x16x32_bf16 v[114:117], v[210:213], v[164:167], v[114:117]
	v_mfma_f32_16x16x32_bf16 v[102:105], v[202:205], v[172:175], v[102:105]
	v_mfma_f32_16x16x32_bf16 v[98:101], v[210:213], v[172:175], v[98:101]
	v_mfma_f32_16x16x32_bf16 v[86:89], v[202:205], v[186:189], v[86:89]
	v_mfma_f32_16x16x32_bf16 v[82:85], v[210:213], v[186:189], v[82:85]
	v_mfma_f32_16x16x32_bf16 v[70:73], v[202:205], v[194:197], v[70:73]
	v_mfma_f32_16x16x32_bf16 v[66:69], v[210:213], v[194:197], v[66:69]
	s_barrier
; template <class Epi, class Sched>
; __device__ __forceinline__ void gemm_phase(LAS unsigned char* lds, const Gemm g, const Sched& S, const Epi& E) {
;     ...
;         for (int t = 0; t < ntu; t += 2) {
;             const bool last = (t == ntu - 2);
;             const char* a1 = cA + (size_t)(t + 1) * kstep;
;             const char* a2 = last ? nA : cA + (size_t)(t + 2) * kstep; const char* b2 = last ? nB : cB + (size_t)(t + 2) * kstep;
;             const char* a3 = a2 + kstep; const char* b3 = b2 + kstep;
;             if (last && has_next) S.a_ready(nxt);
;             PG8_LDB(B0, 0, 0); PG8_SCHED; PG8_LDA(At, 0, 0); PG8_STAGE(PG8_SA(1, 1), a1 + hstepA, voffA);
;             PG8_WAIT_L(8); PG8_BAR; PG8_WAIT_L(0); PG8_MMA(0, 0, At, B0); PG8_BAR; PG8_SCHED;
;             PG8_LDB(B1, 0, 1); PG8_STAGE(PG8_SB(0, 0), b2, voffB);
;             PG8_BAR; PG8_WAIT_L(0); PG8_MMA(0, 1, At, B1); PG8_BAR;
;             PG8_LDA(At, 0, 1); PG8_STAGE(PG8_SA(0, 0), a2, voffA);
;             PG8_BAR; PG8_WAIT_L(0); PG8_MMA(1, 0, At, B0); PG8_BAR; PG8_SCHED;
;             PG8_STAGE(PG8_SB(0, 1), b2 + hstepB, voffB);
;             PG8_WAIT_V(6); PG8_BAR; PG8_MMA(1, 1, At, B1); PG8_BAR;
;             PG8_LDB(B0, 1, 0); PG8_SCHED; PG8_LDA(At, 1, 0); PG8_STAGE(PG8_SA(0, 1), a2 + hstepA, voffA);
;             PG8_WAIT_L(8); PG8_BAR; PG8_WAIT_L(0); PG8_MMA(0, 0, At, B0); PG8_BAR; PG8_SCHED;
;             PG8_LDB(B1, 1, 1); PG8_STAGE(PG8_SB(1, 0), b3, voffB);
;             PG8_BAR; PG8_WAIT_L(0); PG8_MMA(0, 1, At, B1); PG8_BAR;
;             PG8_LDA(At, 1, 1); PG8_STAGE(PG8_SA(1, 0), a3, voffA);
;             PG8_BAR; PG8_WAIT_L(0); PG8_MMA(1, 0, At, B0); PG8_BAR; PG8_SCHED;
;             PG8_STAGE(PG8_SB(1, 1), b3 + hstepB, voffB);
;             PG8_WAIT_V(6); PG8_BAR; PG8_MMA(1, 1, At, B1); PG8_BAR;
;     ...
;         E(acc, cur, wr, wc, fr, fq); S.done(cur);
;     ...
;         if constexpr (Epi::IDEMP && ((PROBE_EPI2 >> Epi::ID) & 1)) { asm volatile("" ::: "memory"); E(acc, cur, wr, wc, fr, fq); }
;     ...
;         if (!has_next) break;
;         if (!E.keep(cur)) {
; #pragma unroll
;             for (int a = 0; a < 2; ++a)
; #pragma unroll
;                 for (int b = 0; b < 2; ++b)
; #pragma unroll
;                     for (int m = 0; m < 4; ++m)
; #pragma unroll
;                         for (int n = 0; n < 2; ++n) acc[a][b][m][n] = (f32x4){0.f, 0.f, 0.f, 0.f};
;         }
	ds_read_b128 v[160:163], v143 offset:49152
	ds_read_b128 v[164:167], v143 offset:50176
	ds_read_b128 v[168:171], v143 offset:51200
	ds_read_b128 v[172:175], v143 offset:52224
	ds_read_b128 v[182:185], v143 offset:53248
	ds_read_b128 v[186:189], v143 offset:54272
	ds_read_b128 v[190:193], v143 offset:55296
	ds_read_b128 v[194:197], v143 offset:56320
	s_add_i32 s28, s35, s46
	v_lshl_add_u64 v[176:177], v[176:177], 0, s[92:93]
	s_mov_b32 m0, s28
	s_nop 0
	global_load_lds_dwordx4 v[176:177], off
	v_lshl_add_u64 v[176:177], v[214:215], 0, s[92:93]
	s_add_i32 m0, s28, 0x2000
	s_nop 0
	global_load_lds_dwordx4 v[176:177], off
	s_add_u32 s28, s56, 0x80080
	s_addc_u32 s29, s57, 0
	s_add_i32 s35, s52, s46
	v_lshl_add_u64 v[238:239], s[28:29], 0, v[178:179]
	s_mov_b32 m0, s35
	s_nop 0
	global_load_lds_dwordx4 v[238:239], off
	v_lshl_add_u64 v[238:239], s[28:29], 0, v[134:135]
	s_add_i32 m0, s35, 0x2000
	s_nop 0
	global_load_lds_dwordx4 v[238:239], off
	s_waitcnt vmcnt(4)
	s_waitcnt lgkmcnt(0)
	s_barrier
	v_mfma_f32_16x16x32_bf16 v[62:65], v[144:147], v[160:163], v[62:65]
	v_mfma_f32_16x16x32_bf16 v[58:61], v[152:155], v[160:163], v[58:61]
	v_mfma_f32_16x16x32_bf16 v[46:49], v[144:147], v[168:171], v[46:49]
	v_mfma_f32_16x16x32_bf16 v[42:45], v[152:155], v[168:171], v[42:45]
	v_mfma_f32_16x16x32_bf16 v[30:33], v[144:147], v[182:185], v[30:33]
	v_mfma_f32_16x16x32_bf16 v[26:29], v[152:155], v[182:185], v[26:29]
	v_mfma_f32_16x16x32_bf16 v[14:17], v[144:147], v[190:193], v[14:17]
	v_mfma_f32_16x16x32_bf16 v[10:13], v[152:155], v[190:193], v[10:13]
	v_mfma_f32_16x16x32_bf16 v[62:65], v[148:151], v[164:167], v[62:65]
	v_mfma_f32_16x16x32_bf16 v[58:61], v[156:159], v[164:167], v[58:61]
	v_mfma_f32_16x16x32_bf16 v[46:49], v[148:151], v[172:175], v[46:49]
	v_mfma_f32_16x16x32_bf16 v[42:45], v[156:159], v[172:175], v[42:45]
	v_mfma_f32_16x16x32_bf16 v[30:33], v[148:151], v[186:189], v[30:33]
	v_mfma_f32_16x16x32_bf16 v[26:29], v[156:159], v[186:189], v[26:29]
	v_mfma_f32_16x16x32_bf16 v[14:17], v[148:151], v[194:197], v[14:17]
	v_mfma_f32_16x16x32_bf16 v[10:13], v[156:159], v[194:197], v[10:13]
	v_mfma_f32_16x16x32_bf16 v[54:57], v[198:201], v[160:163], v[54:57]
	v_mfma_f32_16x16x32_bf16 v[50:53], v[206:209], v[160:163], v[50:53]
	v_mfma_f32_16x16x32_bf16 v[38:41], v[198:201], v[168:171], v[38:41]
	v_mfma_f32_16x16x32_bf16 v[34:37], v[206:209], v[168:171], v[34:37]
	v_mfma_f32_16x16x32_bf16 v[22:25], v[198:201], v[182:185], v[22:25]
	v_mfma_f32_16x16x32_bf16 v[18:21], v[206:209], v[182:185], v[18:21]
	v_mfma_f32_16x16x32_bf16 v[6:9], v[198:201], v[190:193], v[6:9]
	v_mfma_f32_16x16x32_bf16 v[2:5], v[206:209], v[190:193], v[2:5]
	v_mfma_f32_16x16x32_bf16 v[54:57], v[202:205], v[164:167], v[54:57]
	v_mfma_f32_16x16x32_bf16 v[50:53], v[210:213], v[164:167], v[50:53]
	v_mfma_f32_16x16x32_bf16 v[38:41], v[202:205], v[172:175], v[38:41]
	v_mfma_f32_16x16x32_bf16 v[34:37], v[210:213], v[172:175], v[34:37]
	v_mfma_f32_16x16x32_bf16 v[22:25], v[202:205], v[186:189], v[22:25]
	v_mfma_f32_16x16x32_bf16 v[18:21], v[210:213], v[186:189], v[18:21]
	v_mfma_f32_16x16x32_bf16 v[6:9], v[202:205], v[194:197], v[6:9]
	v_mfma_f32_16x16x32_bf16 v[2:5], v[210:213], v[194:197], v[2:5]
	s_add_u32 s70, s70, 0x100
	s_addc_u32 s71, s71, 0
	s_cmp_ge_i32 s72, s17
	s_mov_b64 s[52:53], s[54:55]
	s_mov_b32 s28, s72
	s_barrier
	s_cbranch_scc0 .LBB0_985
	v_readlane_b32 s70, v255, 24
	v_readlane_b32 s76, v255, 26
	v_readlane_b32 s71, v255, 25
	v_readlane_b32 s77, v255, 27
	s_andn2_b64 vcc, exec, s[50:51]
	s_mov_b64 s[28:29], s[12:13]
	s_cbranch_vccnz .LBB0_967
	s_branch .LBB0_966

; #define PG8_STAGE(bufoff, gbase, voff) do { _Pragma("unroll") for (int _i = 0; _i < 2; ++_i) \
;         __builtin_amdgcn_global_load_lds((const unsigned*)((const char*)(gbase) + (voff)[_i]), (LAS unsigned*)(lds + (bufoff) + ldsw + _i * 8192), 16, 0, 0); } while (0)
; #define PG8_LDA(dst, b, h) do { _Pragma("unroll") for (int m = 0; m < 4; ++m) _Pragma("unroll") for (int k = 0; k < 2; ++k) dst[m][k] = *(const LAS bf16x8*)(lds + PG8_SA(b, h) + aoff + m * 2048 + k * 1024); } while (0)
; #define PG8_WAIT_V(n) asm volatile("s_waitcnt vmcnt(" #n ")" ::: "memory")
; template <class Epi, class Sched>
; __device__ __forceinline__ void gemm_phase(LAS unsigned char* lds, const Gemm g, const Sched& S, const Epi& E) {
;     ...
;         for (int t = 0; t < ntu; t += 2) {
;             const bool last = (t == ntu - 2);
;             const char* a1 = cA + (size_t)(t + 1) * kstep;
;             const char* a2 = last ? nA : cA + (size_t)(t + 2) * kstep; const char* b2 = last ? nB : cB + (size_t)(t + 2) * kstep;
;             const char* a3 = a2 + kstep; const char* b3 = b2 + kstep;
;             if (last && has_next) S.a_ready(nxt);
;             PG8_LDB(B0, 0, 0); PG8_SCHED; PG8_LDA(At, 0, 0); PG8_STAGE(PG8_SA(1, 1), a1 + hstepA, voffA);
;             PG8_WAIT_L(8); PG8_BAR; PG8_WAIT_L(0); PG8_MMA(0, 0, At, B0); PG8_BAR; PG8_SCHED;
;             PG8_LDB(B1, 0, 1); PG8_STAGE(PG8_SB(0, 0), b2, voffB);
;             PG8_BAR; PG8_WAIT_L(0); PG8_MMA(0, 1, At, B1); PG8_BAR;
;             PG8_LDA(At, 0, 1); PG8_STAGE(PG8_SA(0, 0), a2, voffA);
;             PG8_BAR; PG8_WAIT_L(0); PG8_MMA(1, 0, At, B0); PG8_BAR; PG8_SCHED;
;             PG8_STAGE(PG8_SB(0, 1), b2 + hstepB, voffB);
;             PG8_WAIT_V(6); PG8_BAR; PG8_MMA(1, 1, At, B1); PG8_BAR;
;             PG8_LDB(B0, 1, 0); PG8_SCHED; PG8_LDA(At, 1, 0); PG8_STAGE(PG8_SA(0, 1), a2 + hstepA, voffA);
;             PG8_WAIT_L(8); PG8_BAR; PG8_WAIT_L(0); PG8_MMA(0, 0, At, B0); PG8_BAR; PG8_SCHED;
;             PG8_LDB(B1, 1, 1); PG8_STAGE(PG8_SB(1, 0), b3, voffB);
;             PG8_BAR; PG8_WAIT_L(0); PG8_MMA(0, 1, At, B1); PG8_BAR;
;             PG8_LDA(At, 1, 1); PG8_STAGE(PG8_SA(1, 0), a3, voffA);
;             PG8_BAR; PG8_WAIT_L(0); PG8_MMA(1, 0, At, B0); PG8_BAR; PG8_SCHED;
;             PG8_STAGE(PG8_SB(1, 1), b3 + hstepB, voffB);
;             PG8_WAIT_V(6); PG8_BAR; PG8_MMA(1, 1, At, B1); PG8_BAR;
.LBB0_1140:
	s_add_u32 s28, s26, 0xfff80080
	s_addc_u32 s29, s27, -1
	s_add_i32 s35, 0, 0x10000
	v_add_u32_e32 v1, s35, v143
	ds_read_b128 v[146:149], v1
	ds_read_b128 v[150:153], v1 offset:1024
	ds_read_b128 v[154:157], v1 offset:2048
	ds_read_b128 v[158:161], v1 offset:3072
	s_cmp_eq_u32 s63, 28
	s_cselect_b32 s29, s13, s29
	s_cselect_b32 s28, s57, s28
	s_cselect_b32 s51, s11, s62
	s_cselect_b32 s50, s58, s59
	ds_read_b128 v[162:165], v145
	ds_read_b128 v[166:169], v145 offset:1024
	ds_read_b128 v[170:173], v145 offset:2048
	ds_read_b128 v[174:177], v145 offset:3072
	ds_read_b128 v[182:185], v145 offset:4096
	ds_read_b128 v[186:189], v145 offset:5120
	ds_read_b128 v[190:193], v145 offset:6144
	ds_read_b128 v[194:197], v145 offset:7168
	s_mov_b32 s98, 0xfff80000
	s_mov_b32 s99, -1
	v_lshl_add_u64 v[232:233], s[26:27], 0, v[136:137]
	v_lshl_add_u64 v[232:233], v[232:233], 0, s[98:99]
	s_mov_b32 m0, s54
	s_nop 0
	global_load_lds_dwordx4 v[232:233], off
	v_lshl_add_u64 v[232:233], s[26:27], 0, v[138:139]
	v_lshl_add_u64 v[232:233], v[232:233], 0, s[98:99]
	s_mov_b32 m0, s55
	s_nop 0
	global_load_lds_dwordx4 v[232:233], off
	v_lshl_add_u64 v[232:233], s[26:27], 0, v[136:137]
	s_add_i32 m0, s23, 0xc000
	s_nop 0
	global_load_lds_dwordx4 v[232:233], off
	v_lshl_add_u64 v[232:233], s[26:27], 0, v[138:139]
	s_add_i32 m0, s23, 0xe000
	s_nop 0
	global_load_lds_dwordx4 v[232:233], off
	s_add_i32 s66, 0, 0x14000
	v_add_u32_e32 v1, s66, v143
	ds_read_b128 v[198:201], v1
	ds_read_b128 v[202:205], v1 offset:1024
	ds_read_b128 v[206:209], v1 offset:2048
	ds_read_b128 v[210:213], v1 offset:3072
	s_waitcnt lgkmcnt(0)
	s_barrier
	v_mfma_f32_16x16x32_bf16 v[126:129], v[146:149], v[162:165], v[126:129]
	v_mfma_f32_16x16x32_bf16 v[118:121], v[154:157], v[162:165], v[118:121]
	v_mfma_f32_16x16x32_bf16 v[110:113], v[146:149], v[170:173], v[110:113]
	v_mfma_f32_16x16x32_bf16 v[102:105], v[154:157], v[170:173], v[102:105]
	v_mfma_f32_16x16x32_bf16 v[94:97], v[146:149], v[182:185], v[94:97]
	v_mfma_f32_16x16x32_bf16 v[86:89], v[154:157], v[182:185], v[86:89]
	v_mfma_f32_16x16x32_bf16 v[78:81], v[146:149], v[190:193], v[78:81]
	v_mfma_f32_16x16x32_bf16 v[70:73], v[154:157], v[190:193], v[70:73]
	v_mfma_f32_16x16x32_bf16 v[126:129], v[150:153], v[166:169], v[126:129]
	v_mfma_f32_16x16x32_bf16 v[118:121], v[158:161], v[166:169], v[118:121]
	v_mfma_f32_16x16x32_bf16 v[110:113], v[150:153], v[174:177], v[110:113]
	v_mfma_f32_16x16x32_bf16 v[102:105], v[158:161], v[174:177], v[102:105]
	v_mfma_f32_16x16x32_bf16 v[94:97], v[150:153], v[186:189], v[94:97]
	v_mfma_f32_16x16x32_bf16 v[86:89], v[158:161], v[186:189], v[86:89]
	v_mfma_f32_16x16x32_bf16 v[78:81], v[150:153], v[194:197], v[78:81]
	v_mfma_f32_16x16x32_bf16 v[70:73], v[158:161], v[194:197], v[70:73]
	v_mfma_f32_16x16x32_bf16 v[122:125], v[198:201], v[162:165], v[122:125]
	v_mfma_f32_16x16x32_bf16 v[114:117], v[206:209], v[162:165], v[114:117]
	v_mfma_f32_16x16x32_bf16 v[106:109], v[198:201], v[170:173], v[106:109]
	v_mfma_f32_16x16x32_bf16 v[98:101], v[206:209], v[170:173], v[98:101]
	v_mfma_f32_16x16x32_bf16 v[90:93], v[198:201], v[182:185], v[90:93]
	v_mfma_f32_16x16x32_bf16 v[82:85], v[206:209], v[182:185], v[82:85]
	v_mfma_f32_16x16x32_bf16 v[74:77], v[198:201], v[190:193], v[74:77]
	v_mfma_f32_16x16x32_bf16 v[66:69], v[206:209], v[190:193], v[66:69]
	v_mfma_f32_16x16x32_bf16 v[122:125], v[202:205], v[166:169], v[122:125]
	v_mfma_f32_16x16x32_bf16 v[114:117], v[210:213], v[166:169], v[114:117]
	v_mfma_f32_16x16x32_bf16 v[106:109], v[202:205], v[174:177], v[106:109]
	v_mfma_f32_16x16x32_bf16 v[98:101], v[210:213], v[174:177], v[98:101]
	v_mfma_f32_16x16x32_bf16 v[90:93], v[202:205], v[186:189], v[90:93]
	v_mfma_f32_16x16x32_bf16 v[82:85], v[210:213], v[186:189], v[82:85]
	v_mfma_f32_16x16x32_bf16 v[74:77], v[202:205], v[194:197], v[74:77]
	v_mfma_f32_16x16x32_bf16 v[66:69], v[210:213], v[194:197], v[66:69]
	s_barrier
	ds_read_b128 v[162:165], v145 offset:16384
	ds_read_b128 v[166:169], v145 offset:17408
	ds_read_b128 v[170:173], v145 offset:18432
	ds_read_b128 v[174:177], v145 offset:19456
	ds_read_b128 v[182:185], v145 offset:20480
	ds_read_b128 v[186:189], v145 offset:21504
	ds_read_b128 v[190:193], v145 offset:22528
	ds_read_b128 v[194:197], v145 offset:23552
	s_add_i32 s35, s35, s46
	v_lshl_add_u64 v[140:141], s[50:51], 0, v[178:179]
	s_mov_b32 m0, s35
	s_nop 0
	global_load_lds_dwordx4 v[140:141], off
	v_lshl_add_u64 v[214:215], s[50:51], 0, v[134:135]
	s_add_i32 m0, s35, 0x2000
	s_nop 0
	global_load_lds_dwordx4 v[214:215], off
	s_add_u32 s64, s50, 0x80000
	s_addc_u32 s65, s51, 0
	s_add_i32 s35, s66, s46
	v_lshl_add_u64 v[234:235], s[64:65], 0, v[178:179]
	s_mov_b32 m0, s35
	s_nop 0
	global_load_lds_dwordx4 v[234:235], off
	v_lshl_add_u64 v[234:235], s[64:65], 0, v[134:135]
	s_add_i32 m0, s35, 0x2000
	s_nop 0
	global_load_lds_dwordx4 v[234:235], off
	s_waitcnt vmcnt(4)
	s_waitcnt lgkmcnt(0)
	s_barrier
; #define PG8_STAGE(bufoff, gbase, voff) do { _Pragma("unroll") for (int _i = 0; _i < 2; ++_i) \
;         __builtin_amdgcn_global_load_lds((const unsigned*)((const char*)(gbase) + (voff)[_i]), (LAS unsigned*)(lds + (bufoff) + ldsw + _i * 8192), 16, 0, 0); } while (0)
; #define PG8_LDA(dst, b, h) do { _Pragma("unroll") for (int m = 0; m < 4; ++m) _Pragma("unroll") for (int k = 0; k < 2; ++k) dst[m][k] = *(const LAS bf16x8*)(lds + PG8_SA(b, h) + aoff + m * 2048 + k * 1024); } while (0)
; #define PG8_WAIT_V(n) asm volatile("s_waitcnt vmcnt(" #n ")" ::: "memory")
; template <class Epi, class Sched>
; __device__ __forceinline__ void gemm_phase(LAS unsigned char* lds, const Gemm g, const Sched& S, const Epi& E) {
;     ...
;         for (int t = 0; t < ntu; t += 2) {
;             const bool last = (t == ntu - 2);
;             const char* a1 = cA + (size_t)(t + 1) * kstep;
;             const char* a2 = last ? nA : cA + (size_t)(t + 2) * kstep; const char* b2 = last ? nB : cB + (size_t)(t + 2) * kstep;
;             const char* a3 = a2 + kstep; const char* b3 = b2 + kstep;
;             if (last && has_next) S.a_ready(nxt);
;             PG8_LDB(B0, 0, 0); PG8_SCHED; PG8_LDA(At, 0, 0); PG8_STAGE(PG8_SA(1, 1), a1 + hstepA, voffA);
;             PG8_WAIT_L(8); PG8_BAR; PG8_WAIT_L(0); PG8_MMA(0, 0, At, B0); PG8_BAR; PG8_SCHED;
;             PG8_LDB(B1, 0, 1); PG8_STAGE(PG8_SB(0, 0), b2, voffB);
;             PG8_BAR; PG8_WAIT_L(0); PG8_MMA(0, 1, At, B1); PG8_BAR;
;             PG8_LDA(At, 0, 1); PG8_STAGE(PG8_SA(0, 0), a2, voffA);
;             PG8_BAR; PG8_WAIT_L(0); PG8_MMA(1, 0, At, B0); PG8_BAR; PG8_SCHED;
;             PG8_STAGE(PG8_SB(0, 1), b2 + hstepB, voffB);
;             PG8_WAIT_V(6); PG8_BAR; PG8_MMA(1, 1, At, B1); PG8_BAR;
;             PG8_LDB(B0, 1, 0); PG8_SCHED; PG8_LDA(At, 1, 0); PG8_STAGE(PG8_SA(0, 1), a2 + hstepA, voffA);
;             PG8_WAIT_L(8); PG8_BAR; PG8_WAIT_L(0); PG8_MMA(0, 0, At, B0); PG8_BAR; PG8_SCHED;
;             PG8_LDB(B1, 1, 1); PG8_STAGE(PG8_SB(1, 0), b3, voffB);
;             PG8_BAR; PG8_WAIT_L(0); PG8_MMA(0, 1, At, B1); PG8_BAR;
;             PG8_LDA(At, 1, 1); PG8_STAGE(PG8_SA(1, 0), a3, voffA);
;             PG8_BAR; PG8_WAIT_L(0); PG8_MMA(1, 0, At, B0); PG8_BAR; PG8_SCHED;
;             PG8_STAGE(PG8_SB(1, 1), b3 + hstepB, voffB);
;             PG8_WAIT_V(6); PG8_BAR; PG8_MMA(1, 1, At, B1); PG8_BAR;
	v_mfma_f32_16x16x32_bf16 v[62:65], v[146:149], v[162:165], v[62:65]
	v_mfma_f32_16x16x32_bf16 v[54:57], v[154:157], v[162:165], v[54:57]
	v_mfma_f32_16x16x32_bf16 v[46:49], v[146:149], v[170:173], v[46:49]
	v_mfma_f32_16x16x32_bf16 v[38:41], v[154:157], v[170:173], v[38:41]
	v_mfma_f32_16x16x32_bf16 v[30:33], v[146:149], v[182:185], v[30:33]
	v_mfma_f32_16x16x32_bf16 v[22:25], v[154:157], v[182:185], v[22:25]
	v_mfma_f32_16x16x32_bf16 v[14:17], v[146:149], v[190:193], v[14:17]
	v_mfma_f32_16x16x32_bf16 v[6:9], v[154:157], v[190:193], v[6:9]
	v_mfma_f32_16x16x32_bf16 v[62:65], v[150:153], v[166:169], v[62:65]
	v_mfma_f32_16x16x32_bf16 v[54:57], v[158:161], v[166:169], v[54:57]
	v_mfma_f32_16x16x32_bf16 v[46:49], v[150:153], v[174:177], v[46:49]
	v_mfma_f32_16x16x32_bf16 v[38:41], v[158:161], v[174:177], v[38:41]
	v_mfma_f32_16x16x32_bf16 v[30:33], v[150:153], v[186:189], v[30:33]
	v_mfma_f32_16x16x32_bf16 v[22:25], v[158:161], v[186:189], v[22:25]
	v_mfma_f32_16x16x32_bf16 v[14:17], v[150:153], v[194:197], v[14:17]
	v_mfma_f32_16x16x32_bf16 v[6:9], v[158:161], v[194:197], v[6:9]
	v_mfma_f32_16x16x32_bf16 v[58:61], v[198:201], v[162:165], v[58:61]
	v_mfma_f32_16x16x32_bf16 v[50:53], v[206:209], v[162:165], v[50:53]
	v_mfma_f32_16x16x32_bf16 v[42:45], v[198:201], v[170:173], v[42:45]
	v_mfma_f32_16x16x32_bf16 v[34:37], v[206:209], v[170:173], v[34:37]
	v_mfma_f32_16x16x32_bf16 v[26:29], v[198:201], v[182:185], v[26:29]
	v_mfma_f32_16x16x32_bf16 v[18:21], v[206:209], v[182:185], v[18:21]
	v_mfma_f32_16x16x32_bf16 v[10:13], v[198:201], v[190:193], v[10:13]
	v_mfma_f32_16x16x32_bf16 v[2:5], v[206:209], v[190:193], v[2:5]
	v_mfma_f32_16x16x32_bf16 v[58:61], v[202:205], v[166:169], v[58:61]
	v_mfma_f32_16x16x32_bf16 v[50:53], v[210:213], v[166:169], v[50:53]
	v_mfma_f32_16x16x32_bf16 v[42:45], v[202:205], v[174:177], v[42:45]
	v_mfma_f32_16x16x32_bf16 v[34:37], v[210:213], v[174:177], v[34:37]
	v_mfma_f32_16x16x32_bf16 v[26:29], v[202:205], v[186:189], v[26:29]
	v_mfma_f32_16x16x32_bf16 v[18:21], v[210:213], v[186:189], v[18:21]
	v_mfma_f32_16x16x32_bf16 v[10:13], v[202:205], v[194:197], v[10:13]
	v_mfma_f32_16x16x32_bf16 v[2:5], v[210:213], v[194:197], v[2:5]
	s_add_i32 s35, 0, 0x18000
	v_add_u32_e32 v1, s35, v143
	s_barrier
	ds_read_b128 v[146:149], v1
	ds_read_b128 v[150:153], v1 offset:1024
	ds_read_b128 v[154:157], v1 offset:2048
	ds_read_b128 v[158:161], v1 offset:3072
	ds_read_b128 v[162:165], v145 offset:32768
	ds_read_b128 v[166:169], v145 offset:33792
	ds_read_b128 v[170:173], v145 offset:34816
	ds_read_b128 v[174:177], v145 offset:35840
	ds_read_b128 v[182:185], v145 offset:36864
	ds_read_b128 v[186:189], v145 offset:37888
	ds_read_b128 v[190:193], v145 offset:38912
	ds_read_b128 v[194:197], v145 offset:39936
	s_mov_b32 m0, s23
	v_lshl_add_u64 v[216:217], s[28:29], 0, v[130:131]
	global_load_lds_dwordx4 v[216:217], off
	v_lshl_add_u64 v[218:219], s[28:29], 0, v[132:133]
	s_mov_b32 m0, s25
	s_nop 0
	global_load_lds_dwordx4 v[218:219], off
	s_add_u32 s28, s28, 0x80000
	s_addc_u32 s29, s29, 0
	s_mov_b32 m0, s52
	v_lshl_add_u64 v[236:237], s[28:29], 0, v[130:131]
	global_load_lds_dwordx4 v[236:237], off
	v_lshl_add_u64 v[236:237], s[28:29], 0, v[132:133]
	s_mov_b32 m0, s53
	s_nop 0
	global_load_lds_dwordx4 v[236:237], off
	s_add_i32 s64, 0, 0x1c000
	v_add_u32_e32 v1, s64, v143
	ds_read_b128 v[198:201], v1
	ds_read_b128 v[202:205], v1 offset:1024
	ds_read_b128 v[206:209], v1 offset:2048
	ds_read_b128 v[210:213], v1 offset:3072
	s_waitcnt lgkmcnt(0)
	s_barrier
	v_mfma_f32_16x16x32_bf16 v[126:129], v[146:149], v[162:165], v[126:129]
	v_mfma_f32_16x16x32_bf16 v[118:121], v[154:157], v[162:165], v[118:121]
	v_mfma_f32_16x16x32_bf16 v[110:113], v[146:149], v[170:173], v[110:113]
	v_mfma_f32_16x16x32_bf16 v[102:105], v[154:157], v[170:173], v[102:105]
	v_mfma_f32_16x16x32_bf16 v[94:97], v[146:149], v[182:185], v[94:97]
	v_mfma_f32_16x16x32_bf16 v[86:89], v[154:157], v[182:185], v[86:89]
	v_mfma_f32_16x16x32_bf16 v[78:81], v[146:149], v[190:193], v[78:81]
	v_mfma_f32_16x16x32_bf16 v[70:73], v[154:157], v[190:193], v[70:73]
	v_mfma_f32_16x16x32_bf16 v[126:129], v[150:153], v[166:169], v[126:129]
	v_mfma_f32_16x16x32_bf16 v[118:121], v[158:161], v[166:169], v[118:121]
	v_mfma_f32_16x16x32_bf16 v[110:113], v[150:153], v[174:177], v[110:113]
	v_mfma_f32_16x16x32_bf16 v[102:105], v[158:161], v[174:177], v[102:105]
	v_mfma_f32_16x16x32_bf16 v[94:97], v[150:153], v[186:189], v[94:97]
	v_mfma_f32_16x16x32_bf16 v[86:89], v[158:161], v[186:189], v[86:89]
	v_mfma_f32_16x16x32_bf16 v[78:81], v[150:153], v[194:197], v[78:81]
	v_mfma_f32_16x16x32_bf16 v[70:73], v[158:161], v[194:197], v[70:73]
	v_mfma_f32_16x16x32_bf16 v[122:125], v[198:201], v[162:165], v[122:125]
	v_mfma_f32_16x16x32_bf16 v[114:117], v[206:209], v[162:165], v[114:117]
	v_mfma_f32_16x16x32_bf16 v[106:109], v[198:201], v[170:173], v[106:109]
	v_mfma_f32_16x16x32_bf16 v[98:101], v[206:209], v[170:173], v[98:101]
	v_mfma_f32_16x16x32_bf16 v[90:93], v[198:201], v[182:185], v[90:93]
	v_mfma_f32_16x16x32_bf16 v[82:85], v[206:209], v[182:185], v[82:85]
	v_mfma_f32_16x16x32_bf16 v[74:77], v[198:201], v[190:193], v[74:77]
	v_mfma_f32_16x16x32_bf16 v[66:69], v[206:209], v[190:193], v[66:69]
	v_mfma_f32_16x16x32_bf16 v[122:125], v[202:205], v[166:169], v[122:125]
	v_mfma_f32_16x16x32_bf16 v[114:117], v[210:213], v[166:169], v[114:117]
	v_mfma_f32_16x16x32_bf16 v[106:109], v[202:205], v[174:177], v[106:109]
	v_mfma_f32_16x16x32_bf16 v[98:101], v[210:213], v[174:177], v[98:101]
	v_mfma_f32_16x16x32_bf16 v[90:93], v[202:205], v[186:189], v[90:93]
	v_mfma_f32_16x16x32_bf16 v[82:85], v[210:213], v[186:189], v[82:85]
	v_mfma_f32_16x16x32_bf16 v[74:77], v[202:205], v[194:197], v[74:77]
	v_mfma_f32_16x16x32_bf16 v[66:69], v[210:213], v[194:197], v[66:69]
	s_barrier
; #define PG8_BAR __builtin_amdgcn_s_barrier()
;     __device__ __forceinline__ void operator()(f32x4 (&acc)[2][2][4][2], const Unit& u, int wr, int wc, int fr, int fq) const {
;         const int row0 = u.pm * BM + wr * 64 + fr, col0 = u.pn * HALF + wc * 32 + 8 * fq;
; #pragma unroll
;         for (int ai = 0; ai < 2; ++ai)
; #pragma unroll
;             for (int m = 0; m < 4; ++m) { bf16_t* rowp = O + (size_t)(row0 + ai * HALF + m * 16) * FF + col0;
;                 float h[8];
; #pragma unroll
;                 for (int n = 0; n < 2; ++n)
; #pragma unroll
; template <class Epi, class Sched>
; __device__ __forceinline__ void gemm_phase(LAS unsigned char* lds, const Gemm g, const Sched& S, const Epi& E) {
;     ...
;         for (int t = 0; t < ntu; t += 2) {
;             const bool last = (t == ntu - 2);
;             const char* a1 = cA + (size_t)(t + 1) * kstep;
;             const char* a2 = last ? nA : cA + (size_t)(t + 2) * kstep; const char* b2 = last ? nB : cB + (size_t)(t + 2) * kstep;
;             const char* a3 = a2 + kstep; const char* b3 = b2 + kstep;
;             if (last && has_next) S.a_ready(nxt);
;             PG8_LDB(B0, 0, 0); PG8_SCHED; PG8_LDA(At, 0, 0); PG8_STAGE(PG8_SA(1, 1), a1 + hstepA, voffA);
;             PG8_WAIT_L(8); PG8_BAR; PG8_WAIT_L(0); PG8_MMA(0, 0, At, B0); PG8_BAR; PG8_SCHED;
;             PG8_LDB(B1, 0, 1); PG8_STAGE(PG8_SB(0, 0), b2, voffB);
;             PG8_BAR; PG8_WAIT_L(0); PG8_MMA(0, 1, At, B1); PG8_BAR;
;             PG8_LDA(At, 0, 1); PG8_STAGE(PG8_SA(0, 0), a2, voffA);
;             PG8_BAR; PG8_WAIT_L(0); PG8_MMA(1, 0, At, B0); PG8_BAR; PG8_SCHED;
;             PG8_STAGE(PG8_SB(0, 1), b2 + hstepB, voffB);
;             PG8_WAIT_V(6); PG8_BAR; PG8_MMA(1, 1, At, B1); PG8_BAR;
;             PG8_LDB(B0, 1, 0); PG8_SCHED; PG8_LDA(At, 1, 0); PG8_STAGE(PG8_SA(0, 1), a2 + hstepA, voffA);
;             PG8_WAIT_L(8); PG8_BAR; PG8_WAIT_L(0); PG8_MMA(0, 0, At, B0); PG8_BAR; PG8_SCHED;
;             PG8_LDB(B1, 1, 1); PG8_STAGE(PG8_SB(1, 0), b3, voffB);
;             PG8_BAR; PG8_WAIT_L(0); PG8_MMA(0, 1, At, B1); PG8_BAR;
;             PG8_LDA(At, 1, 1); PG8_STAGE(PG8_SA(1, 0), a3, voffA);
;             PG8_BAR; PG8_WAIT_L(0); PG8_MMA(1, 0, At, B0); PG8_BAR; PG8_SCHED;
;             PG8_STAGE(PG8_SB(1, 1), b3 + hstepB, voffB);
;             PG8_WAIT_V(6); PG8_BAR; PG8_MMA(1, 1, At, B1); PG8_BAR;
	ds_read_b128 v[162:165], v145 offset:49152
	ds_read_b128 v[166:169], v145 offset:50176
	ds_read_b128 v[170:173], v145 offset:51200
	ds_read_b128 v[174:177], v145 offset:52224
	ds_read_b128 v[182:185], v145 offset:53248
	ds_read_b128 v[186:189], v145 offset:54272
	ds_read_b128 v[190:193], v145 offset:55296
	ds_read_b128 v[194:197], v145 offset:56320
	s_add_i32 s28, s35, s46
	v_lshl_add_u64 v[140:141], v[140:141], 0, s[92:93]
	s_mov_b32 m0, s28
	s_nop 0
	global_load_lds_dwordx4 v[140:141], off
	v_lshl_add_u64 v[140:141], v[214:215], 0, s[92:93]
	s_add_i32 m0, s28, 0x2000
	s_nop 0
	global_load_lds_dwordx4 v[140:141], off
	s_add_u32 s28, s50, 0x80080
	s_addc_u32 s29, s51, 0
	s_add_i32 s35, s64, s46
	v_lshl_add_u64 v[238:239], s[28:29], 0, v[178:179]
	s_mov_b32 m0, s35
	s_nop 0
	global_load_lds_dwordx4 v[238:239], off
	v_lshl_add_u64 v[238:239], s[28:29], 0, v[134:135]
	s_add_i32 m0, s35, 0x2000
	s_nop 0
	global_load_lds_dwordx4 v[238:239], off
	s_waitcnt vmcnt(4)
	s_waitcnt lgkmcnt(0)
	s_barrier
	v_mfma_f32_16x16x32_bf16 v[62:65], v[146:149], v[162:165], v[62:65]
	v_mfma_f32_16x16x32_bf16 v[54:57], v[154:157], v[162:165], v[54:57]
	v_mfma_f32_16x16x32_bf16 v[46:49], v[146:149], v[170:173], v[46:49]
	v_mfma_f32_16x16x32_bf16 v[38:41], v[154:157], v[170:173], v[38:41]
	v_mfma_f32_16x16x32_bf16 v[30:33], v[146:149], v[182:185], v[30:33]
	v_mfma_f32_16x16x32_bf16 v[22:25], v[154:157], v[182:185], v[22:25]
	v_mfma_f32_16x16x32_bf16 v[14:17], v[146:149], v[190:193], v[14:17]
	v_mfma_f32_16x16x32_bf16 v[6:9], v[154:157], v[190:193], v[6:9]
	v_mfma_f32_16x16x32_bf16 v[62:65], v[150:153], v[166:169], v[62:65]
	v_mfma_f32_16x16x32_bf16 v[54:57], v[158:161], v[166:169], v[54:57]
	v_mfma_f32_16x16x32_bf16 v[46:49], v[150:153], v[174:177], v[46:49]
	v_mfma_f32_16x16x32_bf16 v[38:41], v[158:161], v[174:177], v[38:41]
	v_mfma_f32_16x16x32_bf16 v[30:33], v[150:153], v[186:189], v[30:33]
	v_mfma_f32_16x16x32_bf16 v[22:25], v[158:161], v[186:189], v[22:25]
	v_mfma_f32_16x16x32_bf16 v[14:17], v[150:153], v[194:197], v[14:17]
	v_mfma_f32_16x16x32_bf16 v[6:9], v[158:161], v[194:197], v[6:9]
	v_mfma_f32_16x16x32_bf16 v[58:61], v[198:201], v[162:165], v[58:61]
	v_mfma_f32_16x16x32_bf16 v[50:53], v[206:209], v[162:165], v[50:53]
	v_mfma_f32_16x16x32_bf16 v[42:45], v[198:201], v[170:173], v[42:45]
	v_mfma_f32_16x16x32_bf16 v[34:37], v[206:209], v[170:173], v[34:37]
	v_mfma_f32_16x16x32_bf16 v[26:29], v[198:201], v[182:185], v[26:29]
	v_mfma_f32_16x16x32_bf16 v[18:21], v[206:209], v[182:185], v[18:21]
	v_mfma_f32_16x16x32_bf16 v[10:13], v[198:201], v[190:193], v[10:13]
	v_mfma_f32_16x16x32_bf16 v[2:5], v[206:209], v[190:193], v[2:5]
	v_mfma_f32_16x16x32_bf16 v[58:61], v[202:205], v[166:169], v[58:61]
	v_mfma_f32_16x16x32_bf16 v[50:53], v[210:213], v[166:169], v[50:53]
	v_mfma_f32_16x16x32_bf16 v[42:45], v[202:205], v[174:177], v[42:45]
	v_mfma_f32_16x16x32_bf16 v[34:37], v[210:213], v[174:177], v[34:37]
	v_mfma_f32_16x16x32_bf16 v[26:29], v[202:205], v[186:189], v[26:29]
	v_mfma_f32_16x16x32_bf16 v[18:21], v[210:213], v[186:189], v[18:21]
	v_mfma_f32_16x16x32_bf16 v[10:13], v[202:205], v[194:197], v[10:13]
	v_mfma_f32_16x16x32_bf16 v[2:5], v[210:213], v[194:197], v[2:5]
	s_add_i32 s63, s63, 2
	s_add_u32 s26, s26, 0x100
	s_addc_u32 s27, s27, 0
	s_add_u32 s59, s59, 0x100
	s_addc_u32 s62, s62, 0
	s_cmp_gt_u32 s63, 29
	s_barrier
	s_cbranch_scc0 .LBB0_1140
	v_mul_f32_e32 v1, 0xbfb8aa3b, v126
	v_exp_f32_e32 v1, v1
	v_lshl_or_b32 v148, s22, 7, v144
	v_lshl_add_u32 v146, s24, 8, v142
	v_ashrrev_i32_e32 v149, 31, v148
	v_add_f32_e32 v1, 1.0, v1
	v_rcp_f32_e32 v152, v1
	v_mul_f32_e32 v1, 0xbfb8aa3b, v127
	v_exp_f32_e32 v1, v1
	v_mov_b64_e32 v[140:141], s[8:9]
	v_mad_i64_i32 v[150:151], s[26:27], v146, s61, v[140:141]
	v_add_f32_e32 v1, 1.0, v1
	v_rcp_f32_e32 v153, v1
	v_mul_f32_e32 v1, 0xbfb8aa3b, v128
	v_exp_f32_e32 v1, v1
	s_and_b64 vcc, exec, s[6:7]
	v_pk_mul_f32 v[126:127], v[126:127], v[152:153]
	s_mov_b32 s22, s10
	v_add_f32_e32 v1, 1.0, v1
	v_pk_mul_f32 v[122:123], v[126:127], v[122:123]
	v_rcp_f32_e32 v126, v1
	v_mul_f32_e32 v1, 0xbfb8aa3b, v129
	v_exp_f32_e32 v1, v1
	s_mov_b32 s24, s12
	s_mov_b64 s[50:51], s[20:21]
	v_add_f32_e32 v1, 1.0, v1
	v_rcp_f32_e32 v127, v1
	v_mul_f32_e32 v1, 0xbfb8aa3b, v118
	v_exp_f32_e32 v1, v1
	v_pk_mul_f32 v[126:127], v[128:129], v[126:127]
	s_nop 0
	v_pk_mul_f32 v[124:125], v[126:127], v[124:125]
	v_add_f32_e32 v1, 1.0, v1
	v_rcp_f32_e32 v126, v1
	v_mul_f32_e32 v1, 0xbfb8aa3b, v119
	v_exp_f32_e32 v1, v1
	s_nop 0
	v_add_f32_e32 v1, 1.0, v1
	v_rcp_f32_e32 v127, v1
	v_mul_f32_e32 v1, 0xbfb8aa3b, v120
	v_exp_f32_e32 v1, v1
	v_pk_mul_f32 v[118:119], v[118:119], v[126:127]
	s_nop 0
	v_pk_mul_f32 v[118:119], v[118:119], v[114:115]
	v_add_f32_e32 v1, 1.0, v1
	v_rcp_f32_e32 v114, v1
	v_mul_f32_e32 v1, 0xbfb8aa3b, v121
	v_exp_f32_e32 v1, v1
	v_cvt_pk_bf16_f32 v118, v118, v119
	v_add_f32_e32 v1, 1.0, v1
	v_rcp_f32_e32 v115, v1
	v_or_b32_e32 v1, 16, v146
	v_pk_mul_f32 v[114:115], v[120:121], v[114:115]
	s_nop 0
	v_pk_mul_f32 v[120:121], v[114:115], v[116:117]
	v_lshlrev_b64 v[114:115], 1, v[148:149]
	v_lshl_add_u64 v[126:127], v[150:151], 0, v[114:115]
	v_cvt_pk_bf16_f32 v116, v122, v123
	v_cvt_pk_bf16_f32 v117, v124, v125
	v_cvt_pk_bf16_f32 v119, v120, v121
	global_store_dwordx4 v[126:127], v[116:119], off nt
	s_nop 1
	v_mad_i64_i32 v[116:117], s[26:27], v1, s61, v[140:141]
	v_mul_f32_e32 v1, 0xbfb8aa3b, v110
	v_exp_f32_e32 v1, v1
	s_nop 0
	v_add_f32_e32 v1, 1.0, v1
	v_rcp_f32_e32 v118, v1
	v_mul_f32_e32 v1, 0xbfb8aa3b, v111
	v_exp_f32_e32 v1, v1
	s_nop 0
	v_add_f32_e32 v1, 1.0, v1
	v_rcp_f32_e32 v119, v1
	v_mul_f32_e32 v1, 0xbfb8aa3b, v112
; __device__ __forceinline__ unsigned cvt_pk_bf16(float lo, float hi) { const f32x2_t v = {lo, hi}; return __builtin_bit_cast(unsigned, __builtin_convertvector(v, bf16x2_t)); }
;     __device__ __forceinline__ void operator()(f32x4 (&acc)[2][2][4][2], const Unit& u, int wr, int wc, int fr, int fq) const {
;         const int row0 = u.pm * BM + wr * 64 + fr, col0 = u.pn * HALF + wc * 32 + 8 * fq;
; #pragma unroll
;         for (int ai = 0; ai < 2; ++ai)
; #pragma unroll
;             for (int m = 0; m < 4; ++m) { bf16_t* rowp = O + (size_t)(row0 + ai * HALF + m * 16) * FF + col0;
;                 float h[8];
; #pragma unroll
;                 for (int n = 0; n < 2; ++n)
; #pragma unroll
;                     for (int e = 0; e < 4; ++e) { const float g = acc[ai][0][m][n][e], up = acc[ai][1][m][n][e]; h[n * 4 + e] = g * __builtin_amdgcn_rcpf(1.0f + __builtin_amdgcn_exp2f(-1.4426950408889634f * g)) * up; }
;                 u32x4 w; w.x = cvt_pk_bf16(h[0], h[1]); w.y = cvt_pk_bf16(h[2], h[3]); w.z = cvt_pk_bf16(h[4], h[5]); w.w = cvt_pk_bf16(h[6], h[7]);
;                 __builtin_nontemporal_store(w, (u32x4*)rowp); }
	v_exp_f32_e32 v1, v1
	v_pk_mul_f32 v[110:111], v[110:111], v[118:119]
	s_nop 0
	v_pk_mul_f32 v[106:107], v[110:111], v[106:107]
	v_add_f32_e32 v1, 1.0, v1
	v_rcp_f32_e32 v110, v1
	v_mul_f32_e32 v1, 0xbfb8aa3b, v113
	v_exp_f32_e32 v1, v1
	s_nop 0
	v_add_f32_e32 v1, 1.0, v1
	v_rcp_f32_e32 v111, v1
	v_mul_f32_e32 v1, 0xbfb8aa3b, v102
	v_exp_f32_e32 v1, v1
	v_pk_mul_f32 v[110:111], v[112:113], v[110:111]
	s_nop 0
	v_pk_mul_f32 v[108:109], v[110:111], v[108:109]
	v_add_f32_e32 v1, 1.0, v1
	v_rcp_f32_e32 v110, v1
	v_mul_f32_e32 v1, 0xbfb8aa3b, v103
	v_exp_f32_e32 v1, v1
	s_nop 0
	v_add_f32_e32 v1, 1.0, v1
	v_rcp_f32_e32 v111, v1
	v_mul_f32_e32 v1, 0xbfb8aa3b, v104
	v_exp_f32_e32 v1, v1
	v_pk_mul_f32 v[102:103], v[102:103], v[110:111]
	s_nop 0
	v_pk_mul_f32 v[102:103], v[102:103], v[98:99]
	v_add_f32_e32 v1, 1.0, v1
	v_rcp_f32_e32 v98, v1
	v_mul_f32_e32 v1, 0xbfb8aa3b, v105
	v_exp_f32_e32 v1, v1
	v_lshl_add_u64 v[110:111], v[116:117], 0, v[114:115]
	v_add_f32_e32 v1, 1.0, v1
	v_rcp_f32_e32 v99, v1
	v_or_b32_e32 v1, 32, v146
	v_pk_mul_f32 v[98:99], v[104:105], v[98:99]
	s_nop 0
	v_pk_mul_f32 v[104:105], v[98:99], v[100:101]
	v_cvt_pk_bf16_f32 v98, v106, v107
	v_cvt_pk_bf16_f32 v99, v108, v109
	v_cvt_pk_bf16_f32 v100, v102, v103
	v_cvt_pk_bf16_f32 v101, v104, v105
	global_store_dwordx4 v[110:111], v[98:101], off nt
	s_nop 1
	v_mad_i64_i32 v[98:99], s[26:27], v1, s61, v[140:141]
	v_mul_f32_e32 v1, 0xbfb8aa3b, v94
	v_exp_f32_e32 v1, v1
	s_nop 0
	v_add_f32_e32 v1, 1.0, v1
	v_rcp_f32_e32 v100, v1
	v_mul_f32_e32 v1, 0xbfb8aa3b, v95
	v_exp_f32_e32 v1, v1
	s_nop 0
	v_add_f32_e32 v1, 1.0, v1
	v_rcp_f32_e32 v101, v1
	v_mul_f32_e32 v1, 0xbfb8aa3b, v96
	v_exp_f32_e32 v1, v1
	v_pk_mul_f32 v[94:95], v[94:95], v[100:101]
	s_nop 0
	v_pk_mul_f32 v[90:91], v[94:95], v[90:91]
	v_add_f32_e32 v1, 1.0, v1
	v_rcp_f32_e32 v94, v1
	v_mul_f32_e32 v1, 0xbfb8aa3b, v97
	v_exp_f32_e32 v1, v1
	s_nop 0
	v_add_f32_e32 v1, 1.0, v1
	v_rcp_f32_e32 v95, v1
	v_mul_f32_e32 v1, 0xbfb8aa3b, v86
	v_exp_f32_e32 v1, v1
	v_pk_mul_f32 v[94:95], v[96:97], v[94:95]
	s_nop 0
	v_pk_mul_f32 v[92:93], v[94:95], v[92:93]
	v_add_f32_e32 v1, 1.0, v1
	v_rcp_f32_e32 v94, v1
	v_mul_f32_e32 v1, 0xbfb8aa3b, v87
	v_exp_f32_e32 v1, v1
	s_nop 0
	v_add_f32_e32 v1, 1.0, v1
	v_rcp_f32_e32 v95, v1
	v_mul_f32_e32 v1, 0xbfb8aa3b, v88
	v_exp_f32_e32 v1, v1
	v_pk_mul_f32 v[86:87], v[86:87], v[94:95]
	s_nop 0
	v_pk_mul_f32 v[86:87], v[86:87], v[82:83]
	v_add_f32_e32 v1, 1.0, v1
	v_rcp_f32_e32 v82, v1
	v_mul_f32_e32 v1, 0xbfb8aa3b, v89
	v_exp_f32_e32 v1, v1
	v_lshl_add_u64 v[94:95], v[98:99], 0, v[114:115]
	v_add_f32_e32 v1, 1.0, v1
	v_rcp_f32_e32 v83, v1
	v_or_b32_e32 v1, 48, v146
	v_pk_mul_f32 v[82:83], v[88:89], v[82:83]
	s_nop 0
	v_pk_mul_f32 v[88:89], v[82:83], v[84:85]
	v_cvt_pk_bf16_f32 v82, v90, v91
	v_cvt_pk_bf16_f32 v83, v92, v93
	v_cvt_pk_bf16_f32 v84, v86, v87
	v_cvt_pk_bf16_f32 v85, v88, v89
	global_store_dwordx4 v[94:95], v[82:85], off nt
	s_nop 1
	v_mad_i64_i32 v[82:83], s[26:27], v1, s61, v[140:141]
	v_mul_f32_e32 v1, 0xbfb8aa3b, v78
	v_exp_f32_e32 v1, v1
	s_nop 0
	v_add_f32_e32 v1, 1.0, v1
	v_rcp_f32_e32 v84, v1
	v_mul_f32_e32 v1, 0xbfb8aa3b, v79
	v_exp_f32_e32 v1, v1
	s_nop 0
	v_add_f32_e32 v1, 1.0, v1
	v_rcp_f32_e32 v85, v1
	v_mul_f32_e32 v1, 0xbfb8aa3b, v80
	v_exp_f32_e32 v1, v1
	v_pk_mul_f32 v[78:79], v[78:79], v[84:85]
	s_nop 0
	v_pk_mul_f32 v[74:75], v[78:79], v[74:75]
	v_add_f32_e32 v1, 1.0, v1
	v_rcp_f32_e32 v78, v1
	v_mul_f32_e32 v1, 0xbfb8aa3b, v81
	v_exp_f32_e32 v1, v1
	s_nop 0
	v_add_f32_e32 v1, 1.0, v1
	v_rcp_f32_e32 v79, v1
	v_mul_f32_e32 v1, 0xbfb8aa3b, v70
	v_exp_f32_e32 v1, v1
	v_pk_mul_f32 v[78:79], v[80:81], v[78:79]
	s_nop 0
	v_pk_mul_f32 v[76:77], v[78:79], v[76:77]
	v_add_f32_e32 v1, 1.0, v1
	v_rcp_f32_e32 v78, v1
	v_mul_f32_e32 v1, 0xbfb8aa3b, v71
	v_exp_f32_e32 v1, v1
	s_nop 0
	v_add_f32_e32 v1, 1.0, v1
	v_rcp_f32_e32 v79, v1
	v_mul_f32_e32 v1, 0xbfb8aa3b, v72
	v_exp_f32_e32 v1, v1
	v_pk_mul_f32 v[70:71], v[70:71], v[78:79]
	s_nop 0
	v_pk_mul_f32 v[70:71], v[70:71], v[66:67]
	v_add_f32_e32 v1, 1.0, v1
	v_rcp_f32_e32 v66, v1
	v_mul_f32_e32 v1, 0xbfb8aa3b, v73
	v_exp_f32_e32 v1, v1
	v_lshl_add_u64 v[78:79], v[82:83], 0, v[114:115]
	v_add_f32_e32 v1, 1.0, v1
	v_rcp_f32_e32 v67, v1
	v_add_u32_e32 v1, 0x80, v146
	v_pk_mul_f32 v[66:67], v[72:73], v[66:67]
	s_nop 0
	v_pk_mul_f32 v[72:73], v[66:67], v[68:69]
	v_cvt_pk_bf16_f32 v66, v74, v75
	v_cvt_pk_bf16_f32 v67, v76, v77
	v_cvt_pk_bf16_f32 v68, v70, v71
	v_cvt_pk_bf16_f32 v69, v72, v73
	global_store_dwordx4 v[78:79], v[66:69], off nt
	s_nop 1
	v_mad_i64_i32 v[66:67], s[26:27], v1, s61, v[140:141]
	v_mul_f32_e32 v1, 0xbfb8aa3b, v62
	v_exp_f32_e32 v1, v1
	s_nop 0
	v_add_f32_e32 v1, 1.0, v1
	v_rcp_f32_e32 v68, v1
	v_mul_f32_e32 v1, 0xbfb8aa3b, v63
	v_exp_f32_e32 v1, v1
	s_nop 0
	v_add_f32_e32 v1, 1.0, v1
	v_rcp_f32_e32 v69, v1
	v_mul_f32_e32 v1, 0xbfb8aa3b, v64
	v_exp_f32_e32 v1, v1
	v_pk_mul_f32 v[62:63], v[62:63], v[68:69]
	s_nop 0
	v_pk_mul_f32 v[58:59], v[62:63], v[58:59]
	v_add_f32_e32 v1, 1.0, v1
	v_rcp_f32_e32 v62, v1
	v_mul_f32_e32 v1, 0xbfb8aa3b, v65
	v_exp_f32_e32 v1, v1
	s_nop 0
	v_add_f32_e32 v1, 1.0, v1
	v_rcp_f32_e32 v63, v1
	v_mul_f32_e32 v1, 0xbfb8aa3b, v54
	v_exp_f32_e32 v1, v1
	v_pk_mul_f32 v[62:63], v[64:65], v[62:63]
	s_nop 0
	v_pk_mul_f32 v[60:61], v[62:63], v[60:61]
	v_add_f32_e32 v1, 1.0, v1
	v_rcp_f32_e32 v62, v1
	v_mul_f32_e32 v1, 0xbfb8aa3b, v55
	v_exp_f32_e32 v1, v1
	s_nop 0
	v_add_f32_e32 v1, 1.0, v1
	v_rcp_f32_e32 v63, v1
	v_mul_f32_e32 v1, 0xbfb8aa3b, v56
; __device__ __forceinline__ unsigned cvt_pk_bf16(float lo, float hi) { const f32x2_t v = {lo, hi}; return __builtin_bit_cast(unsigned, __builtin_convertvector(v, bf16x2_t)); }
; #define PG8_WAIT_V(n) asm volatile("s_waitcnt vmcnt(" #n ")" ::: "memory")
; #define PG8_BAR __builtin_amdgcn_s_barrier()
;     __device__ __forceinline__ void operator()(f32x4 (&acc)[2][2][4][2], const Unit& u, int wr, int wc, int fr, int fq) const {
;         const int row0 = u.pm * BM + wr * 64 + fr, col0 = u.pn * HALF + wc * 32 + 8 * fq;
; #pragma unroll
;         for (int ai = 0; ai < 2; ++ai)
; #pragma unroll
;             for (int m = 0; m < 4; ++m) { bf16_t* rowp = O + (size_t)(row0 + ai * HALF + m * 16) * FF + col0;
;                 float h[8];
; #pragma unroll
;                 for (int n = 0; n < 2; ++n)
; #pragma unroll
;                     for (int e = 0; e < 4; ++e) { const float g = acc[ai][0][m][n][e], up = acc[ai][1][m][n][e]; h[n * 4 + e] = g * __builtin_amdgcn_rcpf(1.0f + __builtin_amdgcn_exp2f(-1.4426950408889634f * g)) * up; }
;                 u32x4 w; w.x = cvt_pk_bf16(h[0], h[1]); w.y = cvt_pk_bf16(h[2], h[3]); w.z = cvt_pk_bf16(h[4], h[5]); w.w = cvt_pk_bf16(h[6], h[7]);
;                 __builtin_nontemporal_store(w, (u32x4*)rowp); }
; template <class Epi, class Sched>
; __device__ __forceinline__ void gemm_phase(LAS unsigned char* lds, const Gemm g, const Sched& S, const Epi& E) {
;     ...
;         if (!has_next) break;
;         if (!E.keep(cur)) {
; #pragma unroll
;             for (int a = 0; a < 2; ++a)
; #pragma unroll
;                 for (int b = 0; b < 2; ++b)
; #pragma unroll
;                     for (int m = 0; m < 4; ++m)
; #pragma unroll
;                         for (int n = 0; n < 2; ++n) acc[a][b][m][n] = (f32x4){0.f, 0.f, 0.f, 0.f};
;         }
;         cur = nxt; cA = nA; cB = nB; ++ui;
;     }
;     PG8_WAIT_V(0);
;     if (wr == 0) PG8_BAR;
;     PG8_BAR;
	v_exp_f32_e32 v1, v1
	v_pk_mul_f32 v[54:55], v[54:55], v[62:63]
	s_nop 0
	v_pk_mul_f32 v[54:55], v[54:55], v[50:51]
	v_add_f32_e32 v1, 1.0, v1
	v_rcp_f32_e32 v50, v1
	v_mul_f32_e32 v1, 0xbfb8aa3b, v57
	v_exp_f32_e32 v1, v1
	v_lshl_add_u64 v[62:63], v[66:67], 0, v[114:115]
	v_add_f32_e32 v1, 1.0, v1
	v_rcp_f32_e32 v51, v1
	v_add_u32_e32 v1, 0x90, v146
	v_pk_mul_f32 v[50:51], v[56:57], v[50:51]
	s_nop 0
	v_pk_mul_f32 v[56:57], v[50:51], v[52:53]
	v_cvt_pk_bf16_f32 v50, v58, v59
	v_cvt_pk_bf16_f32 v51, v60, v61
	v_cvt_pk_bf16_f32 v52, v54, v55
	v_cvt_pk_bf16_f32 v53, v56, v57
	global_store_dwordx4 v[62:63], v[50:53], off nt
	s_nop 1
	v_mad_i64_i32 v[50:51], s[26:27], v1, s61, v[140:141]
	v_mul_f32_e32 v1, 0xbfb8aa3b, v46
	v_exp_f32_e32 v1, v1
	s_nop 0
	v_add_f32_e32 v1, 1.0, v1
	v_rcp_f32_e32 v52, v1
	v_mul_f32_e32 v1, 0xbfb8aa3b, v47
	v_exp_f32_e32 v1, v1
	s_nop 0
	v_add_f32_e32 v1, 1.0, v1
	v_rcp_f32_e32 v53, v1
	v_mul_f32_e32 v1, 0xbfb8aa3b, v48
	v_exp_f32_e32 v1, v1
	v_pk_mul_f32 v[46:47], v[46:47], v[52:53]
	s_nop 0
	v_pk_mul_f32 v[42:43], v[46:47], v[42:43]
	v_add_f32_e32 v1, 1.0, v1
	v_rcp_f32_e32 v46, v1
	v_mul_f32_e32 v1, 0xbfb8aa3b, v49
	v_exp_f32_e32 v1, v1
	s_nop 0
	v_add_f32_e32 v1, 1.0, v1
	v_rcp_f32_e32 v47, v1
	v_mul_f32_e32 v1, 0xbfb8aa3b, v38
	v_exp_f32_e32 v1, v1
	v_pk_mul_f32 v[46:47], v[48:49], v[46:47]
	s_nop 0
	v_pk_mul_f32 v[44:45], v[46:47], v[44:45]
	v_add_f32_e32 v1, 1.0, v1
	v_rcp_f32_e32 v46, v1
	v_mul_f32_e32 v1, 0xbfb8aa3b, v39
	v_exp_f32_e32 v1, v1
	s_nop 0
	v_add_f32_e32 v1, 1.0, v1
	v_rcp_f32_e32 v47, v1
	v_mul_f32_e32 v1, 0xbfb8aa3b, v40
	v_exp_f32_e32 v1, v1
	v_pk_mul_f32 v[38:39], v[38:39], v[46:47]
	s_nop 0
	v_pk_mul_f32 v[38:39], v[38:39], v[34:35]
	v_add_f32_e32 v1, 1.0, v1
	v_rcp_f32_e32 v34, v1
	v_mul_f32_e32 v1, 0xbfb8aa3b, v41
	v_exp_f32_e32 v1, v1
	v_lshl_add_u64 v[46:47], v[50:51], 0, v[114:115]
	v_add_f32_e32 v1, 1.0, v1
	v_rcp_f32_e32 v35, v1
	v_add_u32_e32 v1, 0xa0, v146
	v_pk_mul_f32 v[34:35], v[40:41], v[34:35]
	s_nop 0
	v_pk_mul_f32 v[40:41], v[34:35], v[36:37]
	v_cvt_pk_bf16_f32 v34, v42, v43
	v_cvt_pk_bf16_f32 v35, v44, v45
	v_cvt_pk_bf16_f32 v36, v38, v39
	v_cvt_pk_bf16_f32 v37, v40, v41
	global_store_dwordx4 v[46:47], v[34:37], off nt
	s_nop 1
	v_mad_i64_i32 v[34:35], s[26:27], v1, s61, v[140:141]
	v_mul_f32_e32 v1, 0xbfb8aa3b, v30
	v_exp_f32_e32 v1, v1
	s_nop 0
	v_add_f32_e32 v1, 1.0, v1
	v_rcp_f32_e32 v36, v1
	v_mul_f32_e32 v1, 0xbfb8aa3b, v31
	v_exp_f32_e32 v1, v1
	s_nop 0
	v_add_f32_e32 v1, 1.0, v1
	v_rcp_f32_e32 v37, v1
	v_mul_f32_e32 v1, 0xbfb8aa3b, v32
	v_exp_f32_e32 v1, v1
	v_pk_mul_f32 v[30:31], v[30:31], v[36:37]
	s_nop 0
	v_pk_mul_f32 v[26:27], v[30:31], v[26:27]
	v_add_f32_e32 v1, 1.0, v1
	v_rcp_f32_e32 v30, v1
	v_mul_f32_e32 v1, 0xbfb8aa3b, v33
	v_exp_f32_e32 v1, v1
	s_nop 0
	v_add_f32_e32 v1, 1.0, v1
	v_rcp_f32_e32 v31, v1
	v_mul_f32_e32 v1, 0xbfb8aa3b, v22
	v_exp_f32_e32 v1, v1
	v_pk_mul_f32 v[30:31], v[32:33], v[30:31]
	s_nop 0
	v_pk_mul_f32 v[28:29], v[30:31], v[28:29]
	v_add_f32_e32 v1, 1.0, v1
	v_rcp_f32_e32 v30, v1
	v_mul_f32_e32 v1, 0xbfb8aa3b, v23
	v_exp_f32_e32 v1, v1
	s_nop 0
	v_add_f32_e32 v1, 1.0, v1
	v_rcp_f32_e32 v31, v1
	v_mul_f32_e32 v1, 0xbfb8aa3b, v24
	v_exp_f32_e32 v1, v1
	v_pk_mul_f32 v[22:23], v[22:23], v[30:31]
	s_nop 0
	v_pk_mul_f32 v[22:23], v[22:23], v[18:19]
	v_add_f32_e32 v1, 1.0, v1
	v_rcp_f32_e32 v18, v1
	v_mul_f32_e32 v1, 0xbfb8aa3b, v25
	v_exp_f32_e32 v1, v1
	v_lshl_add_u64 v[30:31], v[34:35], 0, v[114:115]
	v_add_f32_e32 v1, 1.0, v1
	v_rcp_f32_e32 v19, v1
	v_add_u32_e32 v1, 0xb0, v146
	v_pk_mul_f32 v[18:19], v[24:25], v[18:19]
	s_nop 0
	v_pk_mul_f32 v[24:25], v[18:19], v[20:21]
	v_cvt_pk_bf16_f32 v18, v26, v27
	v_cvt_pk_bf16_f32 v19, v28, v29
	v_cvt_pk_bf16_f32 v20, v22, v23
	v_cvt_pk_bf16_f32 v21, v24, v25
	global_store_dwordx4 v[30:31], v[18:21], off nt
	s_nop 1
	v_mad_i64_i32 v[18:19], s[26:27], v1, s61, v[140:141]
	v_mul_f32_e32 v1, 0xbfb8aa3b, v14
	v_exp_f32_e32 v1, v1
	s_mov_b64 s[26:27], s[16:17]
	v_add_f32_e32 v1, 1.0, v1
	v_rcp_f32_e32 v20, v1
	v_mul_f32_e32 v1, 0xbfb8aa3b, v15
	v_exp_f32_e32 v1, v1
	s_nop 0
	v_add_f32_e32 v1, 1.0, v1
	v_rcp_f32_e32 v21, v1
	v_mul_f32_e32 v1, 0xbfb8aa3b, v16
	v_exp_f32_e32 v1, v1
	v_pk_mul_f32 v[14:15], v[14:15], v[20:21]
	s_nop 0
	v_pk_mul_f32 v[10:11], v[14:15], v[10:11]
	v_add_f32_e32 v1, 1.0, v1
	v_rcp_f32_e32 v14, v1
	v_mul_f32_e32 v1, 0xbfb8aa3b, v17
	v_exp_f32_e32 v1, v1
	s_nop 0
	v_add_f32_e32 v1, 1.0, v1
	v_rcp_f32_e32 v15, v1
	v_mul_f32_e32 v1, 0xbfb8aa3b, v6
	v_exp_f32_e32 v1, v1
	v_pk_mul_f32 v[14:15], v[16:17], v[14:15]
	s_nop 0
	v_pk_mul_f32 v[12:13], v[14:15], v[12:13]
	v_add_f32_e32 v1, 1.0, v1
	v_rcp_f32_e32 v14, v1
	v_mul_f32_e32 v1, 0xbfb8aa3b, v7
	v_exp_f32_e32 v1, v1
	s_nop 0
	v_add_f32_e32 v1, 1.0, v1
	v_rcp_f32_e32 v15, v1
	v_mul_f32_e32 v1, 0xbfb8aa3b, v8
	v_exp_f32_e32 v1, v1
	v_pk_mul_f32 v[6:7], v[6:7], v[14:15]
	s_nop 0
	v_pk_mul_f32 v[6:7], v[6:7], v[2:3]
	v_add_f32_e32 v1, 1.0, v1
	v_rcp_f32_e32 v2, v1
	v_mul_f32_e32 v1, 0xbfb8aa3b, v9
	v_exp_f32_e32 v1, v1
	v_lshl_add_u64 v[14:15], v[18:19], 0, v[114:115]
	v_add_f32_e32 v1, 1.0, v1
	v_rcp_f32_e32 v3, v1
	s_nop 0
	v_pk_mul_f32 v[2:3], v[8:9], v[2:3]
	s_nop 0
	v_pk_mul_f32 v[8:9], v[2:3], v[4:5]
	v_cvt_pk_bf16_f32 v2, v10, v11
	v_cvt_pk_bf16_f32 v3, v12, v13
	v_cvt_pk_bf16_f32 v4, v6, v7
	v_cvt_pk_bf16_f32 v5, v8, v9
	global_store_dwordx4 v[14:15], v[2:5], off nt
	s_cbranch_vccz .LBB0_1136
	s_waitcnt vmcnt(0)
	s_cmpk_gt_u32 s1, 0xff
	s_cbranch_scc1 .LBB0_1144
	s_barrier

; #define PG8_STAGE(bufoff, gbase, voff) do { _Pragma("unroll") for (int _i = 0; _i < 2; ++_i) \
;         __builtin_amdgcn_global_load_lds((const unsigned*)((const char*)(gbase) + (voff)[_i]), (LAS unsigned*)(lds + (bufoff) + ldsw + _i * 8192), 16, 0, 0); } while (0)
; #define PG8_LDA(dst, b, h) do { _Pragma("unroll") for (int m = 0; m < 4; ++m) _Pragma("unroll") for (int k = 0; k < 2; ++k) dst[m][k] = *(const LAS bf16x8*)(lds + PG8_SA(b, h) + aoff + m * 2048 + k * 1024); } while (0)
; #define PG8_WAIT_V(n) asm volatile("s_waitcnt vmcnt(" #n ")" ::: "memory")
; template <class Epi, class Sched>
; __device__ __forceinline__ void gemm_phase(LAS unsigned char* lds, const Gemm g, const Sched& S, const Epi& E) {
;     ...
;         for (int t = 0; t < ntu; t += 2) {
;             const bool last = (t == ntu - 2);
;             const char* a1 = cA + (size_t)(t + 1) * kstep;
;             const char* a2 = last ? nA : cA + (size_t)(t + 2) * kstep; const char* b2 = last ? nB : cB + (size_t)(t + 2) * kstep;
;             const char* a3 = a2 + kstep; const char* b3 = b2 + kstep;
;             if (last && has_next) S.a_ready(nxt);
;             PG8_LDB(B0, 0, 0); PG8_SCHED; PG8_LDA(At, 0, 0); PG8_STAGE(PG8_SA(1, 1), a1 + hstepA, voffA);
;             PG8_WAIT_L(8); PG8_BAR; PG8_WAIT_L(0); PG8_MMA(0, 0, At, B0); PG8_BAR; PG8_SCHED;
;             PG8_LDB(B1, 0, 1); PG8_STAGE(PG8_SB(0, 0), b2, voffB);
;             PG8_BAR; PG8_WAIT_L(0); PG8_MMA(0, 1, At, B1); PG8_BAR;
;             PG8_LDA(At, 0, 1); PG8_STAGE(PG8_SA(0, 0), a2, voffA);
;             PG8_BAR; PG8_WAIT_L(0); PG8_MMA(1, 0, At, B0); PG8_BAR; PG8_SCHED;
;             PG8_STAGE(PG8_SB(0, 1), b2 + hstepB, voffB);
;             PG8_WAIT_V(6); PG8_BAR; PG8_MMA(1, 1, At, B1); PG8_BAR;
;             PG8_LDB(B0, 1, 0); PG8_SCHED; PG8_LDA(At, 1, 0); PG8_STAGE(PG8_SA(0, 1), a2 + hstepA, voffA);
;             PG8_WAIT_L(8); PG8_BAR; PG8_WAIT_L(0); PG8_MMA(0, 0, At, B0); PG8_BAR; PG8_SCHED;
;             PG8_LDB(B1, 1, 1); PG8_STAGE(PG8_SB(1, 0), b3, voffB);
;             PG8_BAR; PG8_WAIT_L(0); PG8_MMA(0, 1, At, B1); PG8_BAR;
;             PG8_LDA(At, 1, 1); PG8_STAGE(PG8_SA(1, 0), a3, voffA);
;             PG8_BAR; PG8_WAIT_L(0); PG8_MMA(1, 0, At, B0); PG8_BAR; PG8_SCHED;
;             PG8_STAGE(PG8_SB(1, 1), b3 + hstepB, voffB);
;             PG8_WAIT_V(6); PG8_BAR; PG8_MMA(1, 1, At, B1); PG8_BAR;
.LBB0_1238:
	s_add_i32 s72, s26, 2
	s_add_u32 s24, s22, 0x100
	s_addc_u32 s25, s23, 0
	s_add_i32 s35, 0, 0x10000
	v_add_u32_e32 v1, s35, v141
	ds_read_b128 v[144:147], v1
	ds_read_b128 v[148:151], v1 offset:1024
	ds_read_b128 v[152:155], v1 offset:2048
	ds_read_b128 v[156:159], v1 offset:3072
	s_cmp_eq_u32 s69, s26
	s_cselect_b32 s26, s16, s70
	s_cselect_b32 s29, s13, s25
	s_cselect_b32 s28, s12, s24
	s_cselect_b32 s27, s17, s71
	ds_read_b128 v[160:163], v143
	ds_read_b128 v[164:167], v143 offset:1024
	ds_read_b128 v[168:171], v143 offset:2048
	ds_read_b128 v[172:175], v143 offset:3072
	ds_read_b128 v[182:185], v143 offset:4096
	ds_read_b128 v[186:189], v143 offset:5120
	ds_read_b128 v[190:193], v143 offset:6144
	ds_read_b128 v[194:197], v143 offset:7168
	s_mov_b32 s98, 0xffea0000
	s_mov_b32 s99, -1
	v_lshl_add_u64 v[232:233], s[22:23], 0, v[136:137]
	v_lshl_add_u64 v[232:233], v[232:233], 0, s[98:99]
	s_mov_b32 m0, s56
	s_nop 0
	global_load_lds_dwordx4 v[232:233], off
	v_lshl_add_u64 v[232:233], s[22:23], 0, v[138:139]
	v_lshl_add_u64 v[232:233], v[232:233], 0, s[98:99]
	s_mov_b32 m0, s57
	s_nop 0
	global_load_lds_dwordx4 v[232:233], off
	v_lshl_add_u64 v[232:233], s[22:23], 0, v[136:137]
	s_add_i32 m0, s52, 0xc000
	s_nop 0
	global_load_lds_dwordx4 v[232:233], off
	v_lshl_add_u64 v[232:233], s[22:23], 0, v[138:139]
	s_add_i32 m0, s52, 0xe000
	s_nop 0
	global_load_lds_dwordx4 v[232:233], off
	s_add_i32 s76, 0, 0x14000
	v_add_u32_e32 v1, s76, v141
	ds_read_b128 v[198:201], v1
	ds_read_b128 v[202:205], v1 offset:1024
	ds_read_b128 v[206:209], v1 offset:2048
	ds_read_b128 v[210:213], v1 offset:3072
	s_waitcnt lgkmcnt(0)
	s_barrier
	v_mfma_f32_16x16x32_bf16 v[126:129], v[144:147], v[160:163], v[126:129]
	v_mfma_f32_16x16x32_bf16 v[122:125], v[152:155], v[160:163], v[122:125]
	v_mfma_f32_16x16x32_bf16 v[110:113], v[144:147], v[168:171], v[110:113]
	v_mfma_f32_16x16x32_bf16 v[106:109], v[152:155], v[168:171], v[106:109]
	v_mfma_f32_16x16x32_bf16 v[94:97], v[144:147], v[182:185], v[94:97]
	v_mfma_f32_16x16x32_bf16 v[90:93], v[152:155], v[182:185], v[90:93]
	v_mfma_f32_16x16x32_bf16 v[78:81], v[144:147], v[190:193], v[78:81]
	v_mfma_f32_16x16x32_bf16 v[74:77], v[152:155], v[190:193], v[74:77]
	v_mfma_f32_16x16x32_bf16 v[126:129], v[148:151], v[164:167], v[126:129]
	v_mfma_f32_16x16x32_bf16 v[122:125], v[156:159], v[164:167], v[122:125]
	v_mfma_f32_16x16x32_bf16 v[110:113], v[148:151], v[172:175], v[110:113]
	v_mfma_f32_16x16x32_bf16 v[106:109], v[156:159], v[172:175], v[106:109]
	v_mfma_f32_16x16x32_bf16 v[94:97], v[148:151], v[186:189], v[94:97]
	v_mfma_f32_16x16x32_bf16 v[90:93], v[156:159], v[186:189], v[90:93]
	v_mfma_f32_16x16x32_bf16 v[78:81], v[148:151], v[194:197], v[78:81]
	v_mfma_f32_16x16x32_bf16 v[74:77], v[156:159], v[194:197], v[74:77]
	v_mfma_f32_16x16x32_bf16 v[118:121], v[198:201], v[160:163], v[118:121]
	v_mfma_f32_16x16x32_bf16 v[114:117], v[206:209], v[160:163], v[114:117]
	v_mfma_f32_16x16x32_bf16 v[102:105], v[198:201], v[168:171], v[102:105]
	v_mfma_f32_16x16x32_bf16 v[98:101], v[206:209], v[168:171], v[98:101]
	v_mfma_f32_16x16x32_bf16 v[86:89], v[198:201], v[182:185], v[86:89]
	v_mfma_f32_16x16x32_bf16 v[82:85], v[206:209], v[182:185], v[82:85]
	v_mfma_f32_16x16x32_bf16 v[70:73], v[198:201], v[190:193], v[70:73]
	v_mfma_f32_16x16x32_bf16 v[66:69], v[206:209], v[190:193], v[66:69]
	v_mfma_f32_16x16x32_bf16 v[118:121], v[202:205], v[164:167], v[118:121]
	v_mfma_f32_16x16x32_bf16 v[114:117], v[210:213], v[164:167], v[114:117]
	v_mfma_f32_16x16x32_bf16 v[102:105], v[202:205], v[172:175], v[102:105]
	v_mfma_f32_16x16x32_bf16 v[98:101], v[210:213], v[172:175], v[98:101]
	v_mfma_f32_16x16x32_bf16 v[86:89], v[202:205], v[186:189], v[86:89]
	v_mfma_f32_16x16x32_bf16 v[82:85], v[210:213], v[186:189], v[82:85]
	v_mfma_f32_16x16x32_bf16 v[70:73], v[202:205], v[194:197], v[70:73]
	v_mfma_f32_16x16x32_bf16 v[66:69], v[210:213], v[194:197], v[66:69]
	s_barrier
	ds_read_b128 v[160:163], v143 offset:16384
	ds_read_b128 v[164:167], v143 offset:17408
	ds_read_b128 v[168:171], v143 offset:18432
	ds_read_b128 v[172:175], v143 offset:19456
	ds_read_b128 v[182:185], v143 offset:20480
	ds_read_b128 v[186:189], v143 offset:21504
	ds_read_b128 v[190:193], v143 offset:22528
	ds_read_b128 v[194:197], v143 offset:23552
	s_add_i32 s22, s35, s50
	v_lshl_add_u64 v[176:177], s[26:27], 0, v[178:179]
	s_mov_b32 m0, s22
	s_nop 0
	global_load_lds_dwordx4 v[176:177], off
	v_lshl_add_u64 v[214:215], s[26:27], 0, v[134:135]
	s_add_i32 m0, s22, 0x2000
	s_nop 0
	global_load_lds_dwordx4 v[214:215], off
	s_add_u32 s22, s26, 0x160000
	s_addc_u32 s23, s27, 0
	s_add_i32 s35, s76, s50
	v_lshl_add_u64 v[234:235], s[22:23], 0, v[178:179]
	s_mov_b32 m0, s35
	s_nop 0
	global_load_lds_dwordx4 v[234:235], off
	v_lshl_add_u64 v[234:235], s[22:23], 0, v[134:135]
	s_add_i32 m0, s35, 0x2000
	s_nop 0
	global_load_lds_dwordx4 v[234:235], off
	s_waitcnt vmcnt(4)
	s_waitcnt lgkmcnt(0)
	s_barrier
; #define PG8_STAGE(bufoff, gbase, voff) do { _Pragma("unroll") for (int _i = 0; _i < 2; ++_i) \
;         __builtin_amdgcn_global_load_lds((const unsigned*)((const char*)(gbase) + (voff)[_i]), (LAS unsigned*)(lds + (bufoff) + ldsw + _i * 8192), 16, 0, 0); } while (0)
; #define PG8_LDA(dst, b, h) do { _Pragma("unroll") for (int m = 0; m < 4; ++m) _Pragma("unroll") for (int k = 0; k < 2; ++k) dst[m][k] = *(const LAS bf16x8*)(lds + PG8_SA(b, h) + aoff + m * 2048 + k * 1024); } while (0)
; #define PG8_WAIT_V(n) asm volatile("s_waitcnt vmcnt(" #n ")" ::: "memory")
; template <class Epi, class Sched>
; __device__ __forceinline__ void gemm_phase(LAS unsigned char* lds, const Gemm g, const Sched& S, const Epi& E) {
;     ...
;         for (int t = 0; t < ntu; t += 2) {
;             const bool last = (t == ntu - 2);
;             const char* a1 = cA + (size_t)(t + 1) * kstep;
;             const char* a2 = last ? nA : cA + (size_t)(t + 2) * kstep; const char* b2 = last ? nB : cB + (size_t)(t + 2) * kstep;
;             const char* a3 = a2 + kstep; const char* b3 = b2 + kstep;
;             if (last && has_next) S.a_ready(nxt);
;             PG8_LDB(B0, 0, 0); PG8_SCHED; PG8_LDA(At, 0, 0); PG8_STAGE(PG8_SA(1, 1), a1 + hstepA, voffA);
;             PG8_WAIT_L(8); PG8_BAR; PG8_WAIT_L(0); PG8_MMA(0, 0, At, B0); PG8_BAR; PG8_SCHED;
;             PG8_LDB(B1, 0, 1); PG8_STAGE(PG8_SB(0, 0), b2, voffB);
;             PG8_BAR; PG8_WAIT_L(0); PG8_MMA(0, 1, At, B1); PG8_BAR;
;             PG8_LDA(At, 0, 1); PG8_STAGE(PG8_SA(0, 0), a2, voffA);
;             PG8_BAR; PG8_WAIT_L(0); PG8_MMA(1, 0, At, B0); PG8_BAR; PG8_SCHED;
;             PG8_STAGE(PG8_SB(0, 1), b2 + hstepB, voffB);
;             PG8_WAIT_V(6); PG8_BAR; PG8_MMA(1, 1, At, B1); PG8_BAR;
;             PG8_LDB(B0, 1, 0); PG8_SCHED; PG8_LDA(At, 1, 0); PG8_STAGE(PG8_SA(0, 1), a2 + hstepA, voffA);
;             PG8_WAIT_L(8); PG8_BAR; PG8_WAIT_L(0); PG8_MMA(0, 0, At, B0); PG8_BAR; PG8_SCHED;
;             PG8_LDB(B1, 1, 1); PG8_STAGE(PG8_SB(1, 0), b3, voffB);
;             PG8_BAR; PG8_WAIT_L(0); PG8_MMA(0, 1, At, B1); PG8_BAR;
;             PG8_LDA(At, 1, 1); PG8_STAGE(PG8_SA(1, 0), a3, voffA);
;             PG8_BAR; PG8_WAIT_L(0); PG8_MMA(1, 0, At, B0); PG8_BAR; PG8_SCHED;
;             PG8_STAGE(PG8_SB(1, 1), b3 + hstepB, voffB);
;             PG8_WAIT_V(6); PG8_BAR; PG8_MMA(1, 1, At, B1); PG8_BAR;
	v_mfma_f32_16x16x32_bf16 v[62:65], v[144:147], v[160:163], v[62:65]
	v_mfma_f32_16x16x32_bf16 v[58:61], v[152:155], v[160:163], v[58:61]
	v_mfma_f32_16x16x32_bf16 v[46:49], v[144:147], v[168:171], v[46:49]
	v_mfma_f32_16x16x32_bf16 v[42:45], v[152:155], v[168:171], v[42:45]
	v_mfma_f32_16x16x32_bf16 v[30:33], v[144:147], v[182:185], v[30:33]
	v_mfma_f32_16x16x32_bf16 v[26:29], v[152:155], v[182:185], v[26:29]
	v_mfma_f32_16x16x32_bf16 v[14:17], v[144:147], v[190:193], v[14:17]
	v_mfma_f32_16x16x32_bf16 v[10:13], v[152:155], v[190:193], v[10:13]
	v_mfma_f32_16x16x32_bf16 v[62:65], v[148:151], v[164:167], v[62:65]
	v_mfma_f32_16x16x32_bf16 v[58:61], v[156:159], v[164:167], v[58:61]
	v_mfma_f32_16x16x32_bf16 v[46:49], v[148:151], v[172:175], v[46:49]
	v_mfma_f32_16x16x32_bf16 v[42:45], v[156:159], v[172:175], v[42:45]
	v_mfma_f32_16x16x32_bf16 v[30:33], v[148:151], v[186:189], v[30:33]
	v_mfma_f32_16x16x32_bf16 v[26:29], v[156:159], v[186:189], v[26:29]
	v_mfma_f32_16x16x32_bf16 v[14:17], v[148:151], v[194:197], v[14:17]
	v_mfma_f32_16x16x32_bf16 v[10:13], v[156:159], v[194:197], v[10:13]
	v_mfma_f32_16x16x32_bf16 v[54:57], v[198:201], v[160:163], v[54:57]
	v_mfma_f32_16x16x32_bf16 v[50:53], v[206:209], v[160:163], v[50:53]
	v_mfma_f32_16x16x32_bf16 v[38:41], v[198:201], v[168:171], v[38:41]
	v_mfma_f32_16x16x32_bf16 v[34:37], v[206:209], v[168:171], v[34:37]
	v_mfma_f32_16x16x32_bf16 v[22:25], v[198:201], v[182:185], v[22:25]
	v_mfma_f32_16x16x32_bf16 v[18:21], v[206:209], v[182:185], v[18:21]
	v_mfma_f32_16x16x32_bf16 v[6:9], v[198:201], v[190:193], v[6:9]
	v_mfma_f32_16x16x32_bf16 v[2:5], v[206:209], v[190:193], v[2:5]
	v_mfma_f32_16x16x32_bf16 v[54:57], v[202:205], v[164:167], v[54:57]
	v_mfma_f32_16x16x32_bf16 v[50:53], v[210:213], v[164:167], v[50:53]
	v_mfma_f32_16x16x32_bf16 v[38:41], v[202:205], v[172:175], v[38:41]
	v_mfma_f32_16x16x32_bf16 v[34:37], v[210:213], v[172:175], v[34:37]
	v_mfma_f32_16x16x32_bf16 v[22:25], v[202:205], v[186:189], v[22:25]
	v_mfma_f32_16x16x32_bf16 v[18:21], v[210:213], v[186:189], v[18:21]
	v_mfma_f32_16x16x32_bf16 v[6:9], v[202:205], v[194:197], v[6:9]
	v_mfma_f32_16x16x32_bf16 v[2:5], v[210:213], v[194:197], v[2:5]
	s_add_i32 s35, 0, 0x18000
	v_add_u32_e32 v1, s35, v141
	s_barrier
	ds_read_b128 v[144:147], v1
	ds_read_b128 v[148:151], v1 offset:1024
	ds_read_b128 v[152:155], v1 offset:2048
	ds_read_b128 v[156:159], v1 offset:3072
	ds_read_b128 v[160:163], v143 offset:32768
	ds_read_b128 v[164:167], v143 offset:33792
	ds_read_b128 v[168:171], v143 offset:34816
	ds_read_b128 v[172:175], v143 offset:35840
	ds_read_b128 v[182:185], v143 offset:36864
	ds_read_b128 v[186:189], v143 offset:37888
	ds_read_b128 v[190:193], v143 offset:38912
	ds_read_b128 v[194:197], v143 offset:39936
	s_mov_b32 m0, s52
	v_lshl_add_u64 v[216:217], s[28:29], 0, v[130:131]
	global_load_lds_dwordx4 v[216:217], off
	v_lshl_add_u64 v[218:219], s[28:29], 0, v[132:133]
	s_mov_b32 m0, s53
	s_nop 0
	global_load_lds_dwordx4 v[218:219], off
	s_add_u32 s22, s28, 0x160000
	s_addc_u32 s23, s29, 0
	s_mov_b32 m0, s54
	v_lshl_add_u64 v[236:237], s[22:23], 0, v[130:131]
	global_load_lds_dwordx4 v[236:237], off
	v_lshl_add_u64 v[236:237], s[22:23], 0, v[132:133]
	s_mov_b32 m0, s55
	s_nop 0
	global_load_lds_dwordx4 v[236:237], off
	s_add_i32 s28, 0, 0x1c000
	v_add_u32_e32 v1, s28, v141
	ds_read_b128 v[198:201], v1
	ds_read_b128 v[202:205], v1 offset:1024
	ds_read_b128 v[206:209], v1 offset:2048
	ds_read_b128 v[210:213], v1 offset:3072
	s_waitcnt lgkmcnt(0)
	s_barrier
; #define PG8_STAGE(bufoff, gbase, voff) do { _Pragma("unroll") for (int _i = 0; _i < 2; ++_i) \
;         __builtin_amdgcn_global_load_lds((const unsigned*)((const char*)(gbase) + (voff)[_i]), (LAS unsigned*)(lds + (bufoff) + ldsw + _i * 8192), 16, 0, 0); } while (0)
; #define PG8_LDA(dst, b, h) do { _Pragma("unroll") for (int m = 0; m < 4; ++m) _Pragma("unroll") for (int k = 0; k < 2; ++k) dst[m][k] = *(const LAS bf16x8*)(lds + PG8_SA(b, h) + aoff + m * 2048 + k * 1024); } while (0)
; #define PG8_LDB(dst, b, h) do { _Pragma("unroll") for (int n = 0; n < 2; ++n) _Pragma("unroll") for (int k = 0; k < 2; ++k) dst[n][k] = *(const LAS bf16x8*)(lds + PG8_SB(b, h) + boff + n * 2048 + k * 1024); } while (0)
; #define PG8_MMA(ai, bj, At, Bt) do { __builtin_amdgcn_s_setprio(1); _Pragma("unroll") for (int m = 0; m < 4; ++m) _Pragma("unroll") for (int n = 0; n < 2; ++n) _Pragma("unroll") for (int k = 0; k < 2; ++k) \
;         acc[ai][bj][m][n] = __builtin_amdgcn_mfma_f32_16x16x32_bf16(Bt[n][k], At[m][k], acc[ai][bj][m][n], 0, 0, 0); __builtin_amdgcn_s_setprio(0); } while (0)
; #define PG8_WAIT_V(n) asm volatile("s_waitcnt vmcnt(" #n ")" ::: "memory")
; #define PG8_WAIT_L(n) asm volatile("s_waitcnt lgkmcnt(" #n ")" ::: "memory")
; #define PG8_BAR __builtin_amdgcn_s_barrier()
; #define PG8_SCHED __builtin_amdgcn_sched_barrier(0)
; template <class Epi, class Sched>
; __device__ __forceinline__ void gemm_phase(LAS unsigned char* lds, const Gemm g, const Sched& S, const Epi& E) {
;     ...
;             PG8_LDB(B0, 1, 0); PG8_SCHED; PG8_LDA(At, 1, 0); PG8_STAGE(PG8_SA(0, 1), a2 + hstepA, voffA);
;             PG8_WAIT_L(8); PG8_BAR; PG8_WAIT_L(0); PG8_MMA(0, 0, At, B0); PG8_BAR; PG8_SCHED;
;             PG8_LDB(B1, 1, 1); PG8_STAGE(PG8_SB(1, 0), b3, voffB);
;             PG8_BAR; PG8_WAIT_L(0); PG8_MMA(0, 1, At, B1); PG8_BAR;
;             PG8_LDA(At, 1, 1); PG8_STAGE(PG8_SA(1, 0), a3, voffA);
;             PG8_BAR; PG8_WAIT_L(0); PG8_MMA(1, 0, At, B0); PG8_BAR; PG8_SCHED;
;             PG8_STAGE(PG8_SB(1, 1), b3 + hstepB, voffB);
;             PG8_WAIT_V(6); PG8_BAR; PG8_MMA(1, 1, At, B1); PG8_BAR;
;         }
	v_mfma_f32_16x16x32_bf16 v[126:129], v[144:147], v[160:163], v[126:129]
	v_mfma_f32_16x16x32_bf16 v[122:125], v[152:155], v[160:163], v[122:125]
	v_mfma_f32_16x16x32_bf16 v[110:113], v[144:147], v[168:171], v[110:113]
	v_mfma_f32_16x16x32_bf16 v[106:109], v[152:155], v[168:171], v[106:109]
	v_mfma_f32_16x16x32_bf16 v[94:97], v[144:147], v[182:185], v[94:97]
	v_mfma_f32_16x16x32_bf16 v[90:93], v[152:155], v[182:185], v[90:93]
	v_mfma_f32_16x16x32_bf16 v[78:81], v[144:147], v[190:193], v[78:81]
	v_mfma_f32_16x16x32_bf16 v[74:77], v[152:155], v[190:193], v[74:77]
	v_mfma_f32_16x16x32_bf16 v[126:129], v[148:151], v[164:167], v[126:129]
	v_mfma_f32_16x16x32_bf16 v[122:125], v[156:159], v[164:167], v[122:125]
	v_mfma_f32_16x16x32_bf16 v[110:113], v[148:151], v[172:175], v[110:113]
	v_mfma_f32_16x16x32_bf16 v[106:109], v[156:159], v[172:175], v[106:109]
	v_mfma_f32_16x16x32_bf16 v[94:97], v[148:151], v[186:189], v[94:97]
	v_mfma_f32_16x16x32_bf16 v[90:93], v[156:159], v[186:189], v[90:93]
	v_mfma_f32_16x16x32_bf16 v[78:81], v[148:151], v[194:197], v[78:81]
	v_mfma_f32_16x16x32_bf16 v[74:77], v[156:159], v[194:197], v[74:77]
	v_mfma_f32_16x16x32_bf16 v[118:121], v[198:201], v[160:163], v[118:121]
	v_mfma_f32_16x16x32_bf16 v[114:117], v[206:209], v[160:163], v[114:117]
	v_mfma_f32_16x16x32_bf16 v[102:105], v[198:201], v[168:171], v[102:105]
	v_mfma_f32_16x16x32_bf16 v[98:101], v[206:209], v[168:171], v[98:101]
	v_mfma_f32_16x16x32_bf16 v[86:89], v[198:201], v[182:185], v[86:89]
	v_mfma_f32_16x16x32_bf16 v[82:85], v[206:209], v[182:185], v[82:85]
	v_mfma_f32_16x16x32_bf16 v[70:73], v[198:201], v[190:193], v[70:73]
	v_mfma_f32_16x16x32_bf16 v[66:69], v[206:209], v[190:193], v[66:69]
	v_mfma_f32_16x16x32_bf16 v[118:121], v[202:205], v[164:167], v[118:121]
	v_mfma_f32_16x16x32_bf16 v[114:117], v[210:213], v[164:167], v[114:117]
	v_mfma_f32_16x16x32_bf16 v[102:105], v[202:205], v[172:175], v[102:105]
	v_mfma_f32_16x16x32_bf16 v[98:101], v[210:213], v[172:175], v[98:101]
	v_mfma_f32_16x16x32_bf16 v[86:89], v[202:205], v[186:189], v[86:89]
	v_mfma_f32_16x16x32_bf16 v[82:85], v[210:213], v[186:189], v[82:85]
	v_mfma_f32_16x16x32_bf16 v[70:73], v[202:205], v[194:197], v[70:73]
	v_mfma_f32_16x16x32_bf16 v[66:69], v[210:213], v[194:197], v[66:69]
	s_barrier
	ds_read_b128 v[160:163], v143 offset:49152
	ds_read_b128 v[164:167], v143 offset:50176
	ds_read_b128 v[168:171], v143 offset:51200
	ds_read_b128 v[172:175], v143 offset:52224
	ds_read_b128 v[182:185], v143 offset:53248
	ds_read_b128 v[186:189], v143 offset:54272
	ds_read_b128 v[190:193], v143 offset:55296
	ds_read_b128 v[194:197], v143 offset:56320
	s_add_i32 s22, s35, s50
	v_lshl_add_u64 v[176:177], v[176:177], 0, s[92:93]
	s_mov_b32 m0, s22
	s_nop 0
	global_load_lds_dwordx4 v[176:177], off
	v_lshl_add_u64 v[176:177], v[214:215], 0, s[92:93]
	s_add_i32 m0, s22, 0x2000
	s_nop 0
	global_load_lds_dwordx4 v[176:177], off
	s_add_u32 s22, s26, 0x160080
	s_addc_u32 s23, s27, 0
	s_add_i32 s26, s28, s50
	v_lshl_add_u64 v[238:239], s[22:23], 0, v[178:179]
	s_mov_b32 m0, s26
	s_nop 0
	global_load_lds_dwordx4 v[238:239], off
	v_lshl_add_u64 v[238:239], s[22:23], 0, v[134:135]
	s_add_i32 m0, s26, 0x2000
	s_nop 0
	global_load_lds_dwordx4 v[238:239], off
	s_waitcnt vmcnt(4)
	s_waitcnt lgkmcnt(0)
	s_barrier
	v_mfma_f32_16x16x32_bf16 v[62:65], v[144:147], v[160:163], v[62:65]
	v_mfma_f32_16x16x32_bf16 v[58:61], v[152:155], v[160:163], v[58:61]
	v_mfma_f32_16x16x32_bf16 v[46:49], v[144:147], v[168:171], v[46:49]
	v_mfma_f32_16x16x32_bf16 v[42:45], v[152:155], v[168:171], v[42:45]
	v_mfma_f32_16x16x32_bf16 v[30:33], v[144:147], v[182:185], v[30:33]
	v_mfma_f32_16x16x32_bf16 v[26:29], v[152:155], v[182:185], v[26:29]
	v_mfma_f32_16x16x32_bf16 v[14:17], v[144:147], v[190:193], v[14:17]
	v_mfma_f32_16x16x32_bf16 v[10:13], v[152:155], v[190:193], v[10:13]
	v_mfma_f32_16x16x32_bf16 v[62:65], v[148:151], v[164:167], v[62:65]
	v_mfma_f32_16x16x32_bf16 v[58:61], v[156:159], v[164:167], v[58:61]
	v_mfma_f32_16x16x32_bf16 v[46:49], v[148:151], v[172:175], v[46:49]
	v_mfma_f32_16x16x32_bf16 v[42:45], v[156:159], v[172:175], v[42:45]
	v_mfma_f32_16x16x32_bf16 v[30:33], v[148:151], v[186:189], v[30:33]
	v_mfma_f32_16x16x32_bf16 v[26:29], v[156:159], v[186:189], v[26:29]
	v_mfma_f32_16x16x32_bf16 v[14:17], v[148:151], v[194:197], v[14:17]
	v_mfma_f32_16x16x32_bf16 v[10:13], v[156:159], v[194:197], v[10:13]
	v_mfma_f32_16x16x32_bf16 v[54:57], v[198:201], v[160:163], v[54:57]
	v_mfma_f32_16x16x32_bf16 v[50:53], v[206:209], v[160:163], v[50:53]
	v_mfma_f32_16x16x32_bf16 v[38:41], v[198:201], v[168:171], v[38:41]
	v_mfma_f32_16x16x32_bf16 v[34:37], v[206:209], v[168:171], v[34:37]
	v_mfma_f32_16x16x32_bf16 v[22:25], v[198:201], v[182:185], v[22:25]
	v_mfma_f32_16x16x32_bf16 v[18:21], v[206:209], v[182:185], v[18:21]
	v_mfma_f32_16x16x32_bf16 v[6:9], v[198:201], v[190:193], v[6:9]
	v_mfma_f32_16x16x32_bf16 v[2:5], v[206:209], v[190:193], v[2:5]
	v_mfma_f32_16x16x32_bf16 v[54:57], v[202:205], v[164:167], v[54:57]
	v_mfma_f32_16x16x32_bf16 v[50:53], v[210:213], v[164:167], v[50:53]
	v_mfma_f32_16x16x32_bf16 v[38:41], v[202:205], v[172:175], v[38:41]
	v_mfma_f32_16x16x32_bf16 v[34:37], v[210:213], v[172:175], v[34:37]
	v_mfma_f32_16x16x32_bf16 v[22:25], v[202:205], v[186:189], v[22:25]
	v_mfma_f32_16x16x32_bf16 v[18:21], v[210:213], v[186:189], v[18:21]
	v_mfma_f32_16x16x32_bf16 v[6:9], v[202:205], v[194:197], v[6:9]
	v_mfma_f32_16x16x32_bf16 v[2:5], v[210:213], v[194:197], v[2:5]
	s_add_u32 s70, s70, 0x100
	s_addc_u32 s71, s71, 0
	s_cmp_ge_i32 s72, s68
	s_mov_b64 s[22:23], s[24:25]
	s_mov_b32 s26, s72
	s_barrier
	s_cbranch_scc0 .LBB0_1238
	v_readlane_b32 s76, v255, 26
	v_readlane_b32 s77, v255, 27
	s_branch .LBB0_1241
